# GEMM: LDS-DMA staging issued by all waves interleaved with first k-step MFMA groups (saddr form); GDN scan chunk loads hoisted; MLA attention LDS reads ring-buffered + unstaggered staging
# speedup vs baseline: 1.0377x; 1.0377x over previous
; template <int MODE, class Epi>
; DEVI void gemm256_phase(int sw, const bf16_t* __restrict__ W, int ldw, const bf16_t* __restrict__ X, int ldx, int K, int nN, char* shm, const Epi& epi) {
;     ...
;   auto stage = [&](int buf, int n0, int m0, int kt) {
;     const char* wk = (const char*)(W + (size_t)n0 * ldw) + kt * 128;
;     const char* xk = (const char*)(X + (size_t)m0 * ldx) + kt * 128;
; #pragma unroll
;     for (int i = 0; i < 4; ++i) {
;       unsigned ow = offW[i], ox = offX[i];
;       asm volatile("" : "+v"(ow), "+v"(ox));
;       __builtin_amdgcn_global_load_lds((const unsigned*)(wk + ow), (unsigned*)(shm + buf * STAGE_B + wid * 1024 + i * 8192), 16, 0, 0);
;       __builtin_amdgcn_global_load_lds((const unsigned*)(xk + ox), (unsigned*)(shm + buf * STAGE_B + TILE_B + wid * 1024 + i * 8192), 16, 0, 0);
;     }
;   };
;     ...
;     for (int t = 0; t < ntk; ++t) {
;       const int cur = (b0 + t) & 1;
;       const bool st_own = t + 1 < ntk, st_next = !st_own && has_next;
;       if (wid < 4) {
;         if (st_own) stage(cur ^ 1, n0, m0, kt0 + t + 1);
;         else if (st_next) stage(cur ^ 1, n1, m1, kt1);
;       }
.LBB0_168:
	s_add_i32 s0, s45, s68
	s_and_b32 s69, s0, 1
	s_add_i32 s68, s68, 1
	s_cmp_lt_i32 s68, s46
	s_cselect_b64 s[0:1], -1, 0
	s_cmp_ge_i32 s68, s46
	s_cselect_b64 s[8:9], -1, 0
	v_cndmask_b32_e64 v128, 0, 1, s[0:1]
	s_and_b64 s[8:9], s[2:3], s[8:9]
	s_andn2_b64 vcc, exec, s[36:37]
	v_cmp_ne_u32_e64 s[0:1], 1, v128
	s_branch .LBB0_177
	s_and_b64 vcc, exec, s[0:1]
	s_cbranch_vccnz .LBB0_171
	s_ashr_i32 s12, s67, 31
	s_add_u32 s14, s62, s67
	s_addc_u32 s15, s63, s12
	s_add_u32 s10, s14, 0x80
	s_addc_u32 s11, s15, 0
	s_add_u32 s42, s64, s67
	s_addc_u32 s43, s65, s12
	s_add_u32 s12, s42, 0x80
	s_addc_u32 s13, s43, 0
	s_lshl_b32 s70, s69, 16
	s_xor_b32 s70, s70, 0x10000
	v_mov_b32_e32 v188, v190
	v_mov_b32_e32 v128, v190
	s_add_i32 s70, s44, s70
	v_lshl_add_u64 v[130:131], s[14:15], 0, v[188:189]
	v_mov_b32_e32 v129, v189
	v_lshl_add_u64 v[130:131], v[130:131], 0, s[38:39]
	s_mov_b32 m0, s70
	v_lshl_add_u64 v[128:129], s[42:43], 0, v[128:129]
	global_load_lds_dwordx4 v[130:131], off
	v_lshl_add_u64 v[128:129], v[128:129], 0, s[38:39]
	s_add_i32 m0, s70, 0x8000
	v_mov_b32_e32 v188, v191
	global_load_lds_dwordx4 v[128:129], off
	v_mov_b32_e32 v128, v191
	v_mov_b32_e32 v129, v189
	v_lshl_add_u64 v[130:131], s[14:15], 0, v[188:189]
	v_lshl_add_u64 v[130:131], v[130:131], 0, s[38:39]
	s_add_i32 m0, s70, 0x2000
	v_lshl_add_u64 v[128:129], s[42:43], 0, v[128:129]
	global_load_lds_dwordx4 v[130:131], off
	v_lshl_add_u64 v[128:129], v[128:129], 0, s[38:39]
	s_add_i32 m0, s70, 0xa000
	v_mov_b32_e32 v188, v192
	global_load_lds_dwordx4 v[128:129], off
	v_mov_b32_e32 v128, v192
	v_mov_b32_e32 v129, v189
	v_lshl_add_u64 v[130:131], s[14:15], 0, v[188:189]
	v_lshl_add_u64 v[130:131], v[130:131], 0, s[38:39]
	s_add_i32 m0, s70, 0x4000
	v_lshl_add_u64 v[128:129], s[42:43], 0, v[128:129]
	global_load_lds_dwordx4 v[130:131], off
	v_lshl_add_u64 v[128:129], v[128:129], 0, s[38:39]
	s_add_i32 m0, s70, 0xc000
	s_nop 0
	global_load_lds_dwordx4 v[128:129], off
	v_mov_b32_e32 v128, v193
	v_mov_b32_e32 v129, v193
	s_mov_b64 s[14:15], -1
	s_cbranch_execz .LBB0_172
	s_branch .LBB0_175

; DEVI f32x4 mfma16(bf16x8 a, bf16x8 b, f32x4 c) { return __builtin_amdgcn_mfma_f32_16x16x32_bf16(a, b, c, 0, 0, 0); }
; template <int MODE, class Epi>
; DEVI void gemm256_phase(int sw, const bf16_t* __restrict__ W, int ldw, const bf16_t* __restrict__ X, int ldx, int K, int nN, char* shm, const Epi& epi) {
;     ...
;       const char* SAp = shm + cur * STAGE_B + wr * (16 * 1024) + lds_lo;
;       const char* SBp = shm + cur * STAGE_B + TILE_B + wc * (8 * 1024) + lds_lo;
; #pragma unroll
;       for (int ks = 0; ks < 2; ++ks) {
;         const int kx = (wid >> 2) ? (1 - 2 * ks) * 1024 : 0;
;         bf16x8 At[8], Bf[4];
; #pragma unroll
;         for (int m = 0; m < 8; ++m) At[m] = *(const bf16x8*)(SAp + (2 * m + ks) * 1024 + kx);
; #pragma unroll
;         for (int n = 0; n < 4; ++n) Bf[n] = *(const bf16x8*)(SBp + (2 * n + ks) * 1024 + kx);
; #pragma unroll
;         for (int m = 0; m < 8; ++m)
; #pragma unroll
;           for (int n = 0; n < 4; ++n) acc[m][n] = mfma16(At[m], Bf[n], acc[m][n]);
;         __builtin_amdgcn_sched_barrier(0);
;         if (ks == 0 && wid >= 4) {
;           if (st_own) stage(cur ^ 1, n0, m0, kt0 + t + 1);
;           else if (st_next) stage(cur ^ 1, n1, m1, kt1);
;         }
.LBB0_177:
	s_lshl_b32 s10, s69, 16
	s_add_i32 s11, s10, s47
	v_add_u32_e32 v129, s11, v194
	v_add_u32_e32 v150, s53, v129
	ds_read_b128 v[220:223], v150
	s_or_b32 s11, s10, s52
	v_add_u32_e32 v128, s11, v194
	v_add_u32_e32 v146, s53, v128
	ds_read_b128 v[134:137], v146 offset:32768
	ds_read_b128 v[138:141], v146 offset:34816
	ds_read_b128 v[142:145], v146 offset:36864
	ds_read_b128 v[146:149], v146 offset:38912
	ds_read_b128 v[224:227], v150 offset:2048
	ds_read_b128 v[228:231], v150 offset:4096
	ds_read_b128 v[232:235], v150 offset:6144
	s_add_u32 s98, s62, s67
	s_addc_u32 s99, s63, 0
	s_add_u32 s98, s98, 0x80
	s_addc_u32 s99, s99, 0
	s_add_u32 s100, s64, s67
	s_addc_u32 s101, s65, 0
	s_add_u32 s100, s100, 0x80
	s_addc_u32 s101, s101, 0
	s_xor_b32 m0, s10, 0x10000
	s_add_i32 m0, m0, s44
	s_waitcnt lgkmcnt(3)
	v_mfma_f32_16x16x32_bf16 v[124:127], v[220:223], v[134:137], v[124:127]
	v_mfma_f32_16x16x32_bf16 v[120:123], v[220:223], v[138:141], v[120:123]
	v_mfma_f32_16x16x32_bf16 v[116:119], v[220:223], v[142:145], v[116:119]
	v_mfma_f32_16x16x32_bf16 v[112:115], v[220:223], v[146:149], v[112:115]
	global_load_lds_dwordx4 v190, s[98:99]
	ds_read_b128 v[236:239], v150 offset:8192
	s_add_i32 m0, m0, 0x8000
	s_waitcnt lgkmcnt(3)
	v_mfma_f32_16x16x32_bf16 v[108:111], v[224:227], v[134:137], v[108:111]
	v_mfma_f32_16x16x32_bf16 v[104:107], v[224:227], v[138:141], v[104:107]
	v_mfma_f32_16x16x32_bf16 v[100:103], v[224:227], v[142:145], v[100:103]
	v_mfma_f32_16x16x32_bf16 v[96:99], v[224:227], v[146:149], v[96:99]
	global_load_lds_dwordx4 v190, s[100:101]
	ds_read_b128 v[240:243], v150 offset:10240
	s_add_i32 m0, m0, 0xffffa000
	s_waitcnt lgkmcnt(3)
	v_mfma_f32_16x16x32_bf16 v[92:95], v[228:231], v[134:137], v[92:95]
	v_mfma_f32_16x16x32_bf16 v[88:91], v[228:231], v[138:141], v[88:91]
	v_mfma_f32_16x16x32_bf16 v[84:87], v[228:231], v[142:145], v[84:87]
	v_mfma_f32_16x16x32_bf16 v[80:83], v[228:231], v[146:149], v[80:83]
	global_load_lds_dwordx4 v191, s[98:99]
	ds_read_b128 v[244:247], v150 offset:12288
	s_add_i32 m0, m0, 0x8000
	s_waitcnt lgkmcnt(3)
	v_mfma_f32_16x16x32_bf16 v[76:79], v[232:235], v[134:137], v[76:79]
	v_mfma_f32_16x16x32_bf16 v[72:75], v[232:235], v[138:141], v[72:75]
	v_mfma_f32_16x16x32_bf16 v[68:71], v[232:235], v[142:145], v[68:71]
	v_mfma_f32_16x16x32_bf16 v[64:67], v[232:235], v[146:149], v[64:67]
	global_load_lds_dwordx4 v191, s[100:101]
	ds_read_b128 v[248:251], v150 offset:14336
	s_add_i32 m0, m0, 0xffffa000
	s_waitcnt lgkmcnt(3)
	v_mfma_f32_16x16x32_bf16 v[60:63], v[236:239], v[134:137], v[60:63]
	v_mfma_f32_16x16x32_bf16 v[56:59], v[236:239], v[138:141], v[56:59]
	v_mfma_f32_16x16x32_bf16 v[52:55], v[236:239], v[142:145], v[52:55]
	v_mfma_f32_16x16x32_bf16 v[48:51], v[236:239], v[146:149], v[48:51]
	global_load_lds_dwordx4 v192, s[98:99]
	s_add_i32 m0, m0, 0x8000
	s_waitcnt lgkmcnt(2)
	v_mfma_f32_16x16x32_bf16 v[44:47], v[240:243], v[134:137], v[44:47]
	v_mfma_f32_16x16x32_bf16 v[40:43], v[240:243], v[138:141], v[40:43]
	v_mfma_f32_16x16x32_bf16 v[36:39], v[240:243], v[142:145], v[36:39]
	v_mfma_f32_16x16x32_bf16 v[32:35], v[240:243], v[146:149], v[32:35]
	global_load_lds_dwordx4 v192, s[100:101]
	s_add_i32 m0, m0, 0xffffa000
	s_waitcnt lgkmcnt(1)
	v_mfma_f32_16x16x32_bf16 v[28:31], v[244:247], v[134:137], v[28:31]
	v_mfma_f32_16x16x32_bf16 v[24:27], v[244:247], v[138:141], v[24:27]
	v_mfma_f32_16x16x32_bf16 v[20:23], v[244:247], v[142:145], v[20:23]
	v_mfma_f32_16x16x32_bf16 v[16:19], v[244:247], v[146:149], v[16:19]
	global_load_lds_dwordx4 v193, s[98:99]
	s_add_i32 m0, m0, 0x8000
	s_waitcnt lgkmcnt(0)
	v_mfma_f32_16x16x32_bf16 v[12:15], v[248:251], v[134:137], v[12:15]
	v_mfma_f32_16x16x32_bf16 v[8:11], v[248:251], v[138:141], v[8:11]
	v_mfma_f32_16x16x32_bf16 v[4:7], v[248:251], v[142:145], v[4:7]
	v_mfma_f32_16x16x32_bf16 v[0:3], v[248:251], v[146:149], v[0:3]
	global_load_lds_dwordx4 v193, s[100:101]
	s_andn2_b64 vcc, exec, s[30:31]
	s_branch .LBB0_167
	s_and_b64 vcc, exec, s[0:1]
	s_xor_b32 s42, s10, 0x10000
	s_cbranch_vccnz .LBB0_180
	s_ashr_i32 s10, s67, 31
	s_add_u32 s12, s62, s67
	s_addc_u32 s13, s63, s10
	s_add_u32 s0, s12, 0x80
	s_addc_u32 s1, s13, 0
	s_add_u32 s14, s64, s67
	s_addc_u32 s15, s65, s10
	s_add_u32 s10, s14, 0x80
	v_mov_b32_e32 v130, v190
	v_mov_b32_e32 v188, v190
	s_addc_u32 s11, s15, 0
	s_add_i32 s43, s44, s42
	v_lshl_add_u64 v[132:133], s[12:13], 0, v[188:189]
	v_mov_b32_e32 v131, v189
	v_lshl_add_u64 v[132:133], v[132:133], 0, s[38:39]
	s_mov_b32 m0, s43
	v_lshl_add_u64 v[130:131], s[14:15], 0, v[130:131]
	global_load_lds_dwordx4 v[132:133], off
	v_lshl_add_u64 v[130:131], v[130:131], 0, s[38:39]
	s_add_i32 m0, s43, 0x8000
	v_mov_b32_e32 v188, v191
	global_load_lds_dwordx4 v[130:131], off
	v_mov_b32_e32 v130, v191
	v_mov_b32_e32 v131, v189
	v_lshl_add_u64 v[132:133], s[12:13], 0, v[188:189]
	v_lshl_add_u64 v[132:133], v[132:133], 0, s[38:39]
	s_add_i32 m0, s43, 0x2000
	v_lshl_add_u64 v[130:131], s[14:15], 0, v[130:131]
	global_load_lds_dwordx4 v[132:133], off
	v_lshl_add_u64 v[130:131], v[130:131], 0, s[38:39]
	s_add_i32 m0, s43, 0xa000
	v_mov_b32_e32 v188, v192
	global_load_lds_dwordx4 v[130:131], off
	v_mov_b32_e32 v130, v192
	v_mov_b32_e32 v131, v189
	v_lshl_add_u64 v[132:133], s[12:13], 0, v[188:189]
	v_lshl_add_u64 v[132:133], v[132:133], 0, s[38:39]
	s_add_i32 m0, s43, 0x4000
	v_lshl_add_u64 v[130:131], s[14:15], 0, v[130:131]
	global_load_lds_dwordx4 v[132:133], off
	v_lshl_add_u64 v[130:131], v[130:131], 0, s[38:39]
	s_add_i32 m0, s43, 0xc000
	s_nop 0
	global_load_lds_dwordx4 v[130:131], off
	v_mov_b32_e32 v130, v193
	v_mov_b32_e32 v131, v193
	s_mov_b64 s[12:13], -1
	s_cbranch_execz .LBB0_181
	s_branch .LBB0_184

; DEVI f32x4 mfma16(bf16x8 a, bf16x8 b, f32x4 c) { return __builtin_amdgcn_mfma_f32_16x16x32_bf16(a, b, c, 0, 0, 0); }
; DEVI bf16x8 pack8(f32x4 a, f32x4 b) { u32x4 u = {pk2(a[0], a[1]), pk2(a[2], a[3]), pk2(b[0], b[1]), pk2(b[2], b[3])}; return __builtin_bit_cast(bf16x8, u); }
; template <int DQK>
; DEVI void attn256_item(int sw, const bf16_t* __restrict__ Q, int ldq, const bf16_t* __restrict__ Kp, int ldk, const bf16_t* __restrict__ Vt,
;                        bf16_t* __restrict__ O, int ldo, int nkeys, float negB, char* shm) {
;     ...
; #pragma unroll
;     for (int half = 0; half < 2; ++half) {
;       f32x4 s[2][2];
; #pragma unroll
;       for (int i = 0; i < 2; ++i) { s[i][0] = (f32x4){negB, negB, negB, negB}; s[i][1] = (f32x4){negB, negB, negB, negB}; }
; #pragma unroll
;       for (int ks = 0; ks < KS; ++ks)
; #pragma unroll
;         for (int kt = 0; kt < 2; ++kt) {
;           const int krow = half * 32 + 8 * (fr >> 2) + 4 * kt + (fr & 3);
;           const int ksw = (krow >> 1) & 7;
;           bf16x8 kf = *(const bf16x8*)(Ks + krow * DQK + ((((ks * 4 + fq) & ~7) | (((ks * 4 + fq) & 7) ^ ksw)) * 8));
;           s[kt][0] = mfma16(kf, qf[0][ks], s[kt][0]);
;           s[kt][1] = mfma16(kf, qf[1][ks], s[kt][1]);
;         }
;       bf16x8 pf[2];
; #pragma unroll
;       for (int nt = 0; nt < 2; ++nt) {
;         float rs = 0.f;
; #pragma unroll
;         for (int kt = 0; kt < 2; ++kt)
; #pragma unroll
;           for (int j = 0; j < 4; ++j) { float pv = __builtin_amdgcn_exp2f(s[kt][nt][j]); s[kt][nt][j] = pv; rs += pv; }
;         l_[nt] += rs;
;         pf[nt] = pack8(s[0][nt], s[1][nt]);
;       }
; #pragma unroll
;       for (int dt = 0; dt < 8; ++dt) {
;         bf16x8 vf = *(const bf16x8*)(Vs + (dt * 16 + fr) * 128 + (((half * 4 + fq) ^ rsw) * 16));
;         o[dt][0] = mfma16(vf, pf[0], o[dt][0]);
;         o[dt][1] = mfma16(vf, pf[1], o[dt][1]);
;       }
;       if (half == 0 && wid >= 4 && t + 1 < ntile) stage(cur ^ 1, (t + 1) * 64);
;     }
;     asm volatile("s_waitcnt vmcnt(0)" ::: "memory");
;     __syncthreads();
.LBB0_560:
	s_add_i32 s47, s47, 1
	s_add_u32 s2, s2, 0x80
	s_addc_u32 s3, s3, 0
	s_add_u32 s45, s45, 0x32000
	s_addc_u32 s56, s56, 0
	s_cmp_eq_u32 s44, s47
	v_add3_u32 v255, s57, v152, v151
	ds_read_b128 v[220:223], v172 offset:12288
	ds_read_b128 v[224:227], v173 offset:13824
	ds_read_b128 v[228:231], v174 offset:12288
	ds_read_b128 v[232:235], v175 offset:13824
	ds_read_b128 v[236:239], v176 offset:12288
	ds_read_b128 v[240:243], v177 offset:13824
	v_pk_add_f32 v[122:123], v[122:123], 0 op_sel_hi:[1,0]
	v_pk_add_f32 v[122:123], v[130:131], v[122:123]
	v_pk_add_f32 v[120:121], v[120:121], v[122:123]
	v_pk_add_f32 v[120:121], v[128:129], v[120:121]
	v_pk_add_f32 v[118:119], v[118:119], v[120:121]
	v_pk_add_f32 v[118:119], v[126:127], v[118:119]
	v_pk_add_f32 v[116:117], v[116:117], v[118:119]
	v_pk_add_f32 v[116:117], v[124:125], v[116:117]
	v_pk_add_f32 v[140:141], v[140:141], v[116:117]
	s_waitcnt lgkmcnt(5)
	v_mfma_f32_16x16x32_bf16 v[120:123], v[220:223], v[44:47], v[24:27]
	v_mfma_f32_16x16x32_bf16 v[116:119], v[220:223], v[48:51], v[24:27]
	ds_read_b128 v[244:247], v178 offset:12288
	s_waitcnt lgkmcnt(5)
	v_mfma_f32_16x16x32_bf16 v[128:131], v[224:227], v[44:47], v[24:27]
	v_mfma_f32_16x16x32_bf16 v[124:127], v[224:227], v[48:51], v[24:27]
	ds_read_b128 v[248:251], v180 offset:13824
	s_waitcnt lgkmcnt(5)
	v_mfma_f32_16x16x32_bf16 v[120:123], v[228:231], v[36:39], v[120:123]
	v_mfma_f32_16x16x32_bf16 v[116:119], v[228:231], v[40:43], v[116:119]
	ds_read_b128 v[220:223], v182 offset:12288
	s_waitcnt lgkmcnt(5)
	v_mfma_f32_16x16x32_bf16 v[128:131], v[232:235], v[36:39], v[128:131]
	v_mfma_f32_16x16x32_bf16 v[124:127], v[232:235], v[40:43], v[124:127]
	ds_read_b128 v[224:227], v183 offset:13824
	s_waitcnt lgkmcnt(5)
	v_mfma_f32_16x16x32_bf16 v[120:123], v[236:239], v[32:35], v[120:123]
	v_mfma_f32_16x16x32_bf16 v[116:119], v[236:239], v[28:31], v[116:119]
	ds_read_b128 v[228:231], v181 offset:12288
	s_waitcnt lgkmcnt(5)
	v_mfma_f32_16x16x32_bf16 v[128:131], v[240:243], v[32:35], v[128:131]
	v_mfma_f32_16x16x32_bf16 v[124:127], v[240:243], v[28:31], v[124:127]
	ds_read_b128 v[232:235], v179 offset:13824
	s_waitcnt lgkmcnt(5)
	v_mfma_f32_16x16x32_bf16 v[120:123], v[244:247], v[16:19], v[120:123]
	v_mfma_f32_16x16x32_bf16 v[116:119], v[244:247], v[20:23], v[116:119]
	s_waitcnt lgkmcnt(4)
	v_mfma_f32_16x16x32_bf16 v[128:131], v[248:251], v[16:19], v[128:131]
	v_mfma_f32_16x16x32_bf16 v[124:127], v[248:251], v[20:23], v[124:127]
	s_waitcnt lgkmcnt(3)
	v_mfma_f32_16x16x32_bf16 v[120:123], v[220:223], v[12:15], v[120:123]
	v_mfma_f32_16x16x32_bf16 v[116:119], v[220:223], v[8:11], v[116:119]
	s_waitcnt lgkmcnt(2)
	v_mfma_f32_16x16x32_bf16 v[128:131], v[224:227], v[12:15], v[128:131]
	v_mfma_f32_16x16x32_bf16 v[124:127], v[224:227], v[8:11], v[124:127]
	s_waitcnt lgkmcnt(1)
	v_mfma_f32_16x16x32_bf16 v[120:123], v[228:231], v[4:7], v[120:123]
	v_mfma_f32_16x16x32_bf16 v[116:119], v[228:231], v[0:3], v[116:119]
	s_waitcnt lgkmcnt(0)
	v_mfma_f32_16x16x32_bf16 v[128:131], v[232:235], v[4:7], v[128:131]
	v_mfma_f32_16x16x32_bf16 v[124:127], v[232:235], v[0:3], v[124:127]
	ds_read_b128 v[220:223], v255 offset:24576
	ds_read_b128 v[224:227], v255 offset:26624
	ds_read_b128 v[228:231], v255 offset:28672
	ds_read_b128 v[232:235], v255 offset:30720
	ds_read_b128 v[236:239], v255 offset:32768
	ds_read_b128 v[240:243], v255 offset:34816
	ds_read_b128 v[244:247], v255 offset:36864
	ds_read_b128 v[248:251], v255 offset:38912
	v_exp_f32_e32 v121, v121
	v_exp_f32_e32 v123, v123
	v_exp_f32_e32 v177, v128
	v_exp_f32_e32 v173, v120
	v_exp_f32_e32 v172, v116
	v_exp_f32_e32 v120, v117
	v_exp_f32_e32 v175, v122
	v_exp_f32_e32 v174, v118
	v_exp_f32_e32 v122, v119
	v_exp_f32_e32 v176, v124
	v_pk_add_f32 v[116:117], v[172:173], 0 op_sel_hi:[1,0]
	v_exp_f32_e32 v129, v129
	v_exp_f32_e32 v128, v125
	v_pk_add_f32 v[116:117], v[120:121], v[116:117]
	v_exp_f32_e32 v179, v130
	v_exp_f32_e32 v178, v126
	v_pk_add_f32 v[116:117], v[174:175], v[116:117]
	v_exp_f32_e32 v131, v131
	v_exp_f32_e32 v130, v127
	v_pk_add_f32 v[116:117], v[122:123], v[116:117]
	v_cvt_pk_bf16_f32 v118, v177, v129
	v_pk_add_f32 v[116:117], v[176:177], v[116:117]
	v_cvt_pk_bf16_f32 v119, v179, v131
	v_pk_add_f32 v[116:117], v[128:129], v[116:117]
	v_cvt_pk_bf16_f32 v120, v172, v120
	v_pk_add_f32 v[116:117], v[178:179], v[116:117]
	s_nop 0
	v_pk_add_f32 v[124:125], v[130:131], v[116:117]
	v_cvt_pk_bf16_f32 v116, v173, v121
	v_cvt_pk_bf16_f32 v121, v174, v122
	v_cvt_pk_bf16_f32 v122, v176, v128
	v_pk_add_f32 v[140:141], v[140:141], v[124:125]
	v_cvt_pk_bf16_f32 v117, v175, v123
	v_cvt_pk_bf16_f32 v123, v178, v130
	s_nop 1
	s_waitcnt lgkmcnt(7)
	v_mfma_f32_16x16x32_bf16 v[108:111], v[220:223], v[116:119], v[108:111]
	v_mfma_f32_16x16x32_bf16 v[112:115], v[220:223], v[120:123], v[112:115]
	s_waitcnt lgkmcnt(6)
	v_mfma_f32_16x16x32_bf16 v[100:103], v[224:227], v[116:119], v[100:103]
	v_mfma_f32_16x16x32_bf16 v[104:107], v[224:227], v[120:123], v[104:107]
	s_waitcnt lgkmcnt(5)
	v_mfma_f32_16x16x32_bf16 v[96:99], v[228:231], v[116:119], v[96:99]
	v_mfma_f32_16x16x32_bf16 v[60:63], v[228:231], v[120:123], v[60:63]
	s_waitcnt lgkmcnt(4)
	v_mfma_f32_16x16x32_bf16 v[92:95], v[232:235], v[116:119], v[92:95]
	v_mfma_f32_16x16x32_bf16 v[52:55], v[232:235], v[120:123], v[52:55]
	s_waitcnt lgkmcnt(3)
	v_mfma_f32_16x16x32_bf16 v[88:91], v[236:239], v[116:119], v[88:91]
	v_mfma_f32_16x16x32_bf16 v[56:59], v[236:239], v[120:123], v[56:59]
	s_waitcnt lgkmcnt(2)
	v_mfma_f32_16x16x32_bf16 v[76:79], v[240:243], v[116:119], v[76:79]
	v_mfma_f32_16x16x32_bf16 v[64:67], v[240:243], v[120:123], v[64:67]
	s_waitcnt lgkmcnt(1)
	v_mfma_f32_16x16x32_bf16 v[84:87], v[244:247], v[116:119], v[84:87]
	v_mfma_f32_16x16x32_bf16 v[68:71], v[244:247], v[120:123], v[68:71]
	s_waitcnt lgkmcnt(0)
	v_mfma_f32_16x16x32_bf16 v[80:83], v[248:251], v[116:119], v[80:83]
	v_mfma_f32_16x16x32_bf16 v[72:75], v[248:251], v[120:123], v[72:75]
	s_waitcnt vmcnt(0)
	s_barrier
	s_cbranch_scc1 .LBB0_565
; template <int DQK>
; DEVI void attn256_item(int sw, const bf16_t* __restrict__ Q, int ldq, const bf16_t* __restrict__ Kp, int ldk, const bf16_t* __restrict__ Vt,
;                        bf16_t* __restrict__ O, int ldo, int nkeys, float negB, char* shm) {
;     ...
;   auto stage = [&](int buf, int k0) {
;     const char* kb = (const char*)(Kp + (size_t)k0 * ldk);
;     const char* vb = (const char*)(Vt + k0);
; #pragma unroll
;     for (int i = 0; i < NKI; ++i) {
;       unsigned o = offK[i]; asm volatile("" : "+v"(o));
;       __builtin_amdgcn_global_load_lds((const unsigned*)(kb + o), (unsigned*)(shm + buf * STG + (wid * NKI + i) * 1024), 16, 0, 0);
;     }
; #pragma unroll
;     for (int i = 0; i < 2; ++i) {
;     ...
;   for (int t = 0; t < ntile; ++t) {
;     const int cur = t & 1;
;     if (wid < 4 && t + 1 < ntile) stage(cur ^ 1, (t + 1) * 64);
;     const bf16_t* Ks = (const bf16_t*)(shm + cur * STG);
;     const char* Vs = shm + cur * STG + KBYTES;
; #pragma unroll
;     for (int half = 0; half < 2; ++half) {
;       f32x4 s[2][2];
; #pragma unroll
;       for (int i = 0; i < 2; ++i) { s[i][0] = (f32x4){negB, negB, negB, negB}; s[i][1] = (f32x4){negB, negB, negB, negB}; }
; #pragma unroll
;       for (int ks = 0; ks < KS; ++ks)
; #pragma unroll
;         for (int kt = 0; kt < 2; ++kt) {
;           const int krow = half * 32 + 8 * (fr >> 2) + 4 * kt + (fr & 3);
;           const int ksw = (krow >> 1) & 7;
;           bf16x8 kf = *(const bf16x8*)(Ks + krow * DQK + ((((ks * 4 + fq) & ~7) | (((ks * 4 + fq) & 7) ^ ksw)) * 8));
;           s[kt][0] = mfma16(kf, qf[0][ks], s[kt][0]);
;           s[kt][1] = mfma16(kf, qf[1][ks], s[kt][1]);
;         }
;       bf16x8 pf[2];
; #pragma unroll
;       for (int nt = 0; nt < 2; ++nt) {
;         float rs = 0.f;
; #pragma unroll
;         for (int kt = 0; kt < 2; ++kt)
; #pragma unroll
;           for (int j = 0; j < 4; ++j) { float pv = __builtin_amdgcn_exp2f(s[kt][nt][j]); s[kt][nt][j] = pv; rs += pv; }
;         l_[nt] += rs;
;         pf[nt] = pack8(s[0][nt], s[1][nt]);
;       }
; #pragma unroll
;       for (int dt = 0; dt < 8; ++dt) {
;         bf16x8 vf = *(const bf16x8*)(Vs + (dt * 16 + fr) * 128 + (((half * 4 + fq) ^ rsw) * 16));
;         o[dt][0] = mfma16(vf, pf[0], o[dt][0]);
;         o[dt][1] = mfma16(vf, pf[1], o[dt][1]);
;       }
;       if (half == 0 && wid >= 4 && t + 1 < ntile) stage(cur ^ 1, (t + 1) * 64);
.LBB0_561:
	s_andn2_b64 vcc, exec, s[8:9]
	s_and_b32 s58, s47, 1
	s_xor_b32 s54, s58, 1
	s_mul_i32 s57, s54, 0xa000
	s_add_i32 s59, s57, s93
	v_mov_b32_e32 v116, v154
	s_add_u32 s54, s22, s45
	s_addc_u32 s55, s23, s56
	s_mov_b32 m0, s59
	s_add_i32 s57, s57, s94
	global_load_lds_dwordx4 v116, s[54:55]
	v_mov_b32_e32 v116, v155
	s_add_i32 m0, s59, 0x400
	s_nop 0
	global_load_lds_dwordx4 v116, s[54:55]
	v_mov_b32_e32 v116, v156
	s_add_i32 m0, s59, 0x800
	s_nop 0
	global_load_lds_dwordx4 v116, s[54:55]
	s_add_i32 m0, s57, 0x6000
	v_mov_b32_e32 v116, v157
	s_add_u32 s54, s22, s2
	s_addc_u32 s55, s23, s3
	global_load_lds_dwordx4 v116, s[54:55]
	v_mov_b32_e32 v116, v158
	s_add_i32 m0, s57, 0x6400
	s_nop 0
	global_load_lds_dwordx4 v116, s[54:55]
.LBB0_563:
	s_mul_i32 s57, s58, 0xa000
	s_andn2_b64 vcc, exec, s[10:11]
	v_lshl_add_u32 v192, v169, 1, s57
	v_lshl_add_u32 v172, v171, 1, v192
	v_lshl_add_u32 v174, v168, 1, v192
	v_lshl_add_u32 v173, v170, 1, v192
	v_lshl_add_u32 v175, v166, 1, v192
	v_lshl_add_u32 v176, v167, 1, v192
	v_lshl_add_u32 v177, v165, 1, v192
	v_lshl_add_u32 v178, v164, 1, v192
	v_lshl_add_u32 v179, v159, 1, v192
	v_lshl_add_u32 v180, v163, 1, v192
	v_lshl_add_u32 v181, v160, 1, v192
	v_lshl_add_u32 v182, v162, 1, v192
	v_lshl_add_u32 v183, v161, 1, v192
	v_add3_u32 v255, s57, v153, v151
	ds_read_b128 v[220:223], v172
	ds_read_b128 v[224:227], v173 offset:1536
	ds_read_b128 v[228:231], v174
	ds_read_b128 v[232:235], v175 offset:1536
	ds_read_b128 v[236:239], v176
	ds_read_b128 v[240:243], v177 offset:1536
	s_waitcnt lgkmcnt(5)
	v_mfma_f32_16x16x32_bf16 v[120:123], v[220:223], v[44:47], v[24:27]
	v_mfma_f32_16x16x32_bf16 v[116:119], v[220:223], v[48:51], v[24:27]
	ds_read_b128 v[244:247], v178
	s_waitcnt lgkmcnt(5)
	v_mfma_f32_16x16x32_bf16 v[128:131], v[224:227], v[44:47], v[24:27]
	v_mfma_f32_16x16x32_bf16 v[124:127], v[224:227], v[48:51], v[24:27]
	ds_read_b128 v[248:251], v180 offset:1536
	s_waitcnt lgkmcnt(5)
	v_mfma_f32_16x16x32_bf16 v[120:123], v[228:231], v[36:39], v[120:123]
	v_mfma_f32_16x16x32_bf16 v[116:119], v[228:231], v[40:43], v[116:119]
	ds_read_b128 v[220:223], v182
	s_waitcnt lgkmcnt(5)
	v_mfma_f32_16x16x32_bf16 v[128:131], v[232:235], v[36:39], v[128:131]
	v_mfma_f32_16x16x32_bf16 v[124:127], v[232:235], v[40:43], v[124:127]
	ds_read_b128 v[224:227], v183 offset:1536
	s_waitcnt lgkmcnt(5)
	v_mfma_f32_16x16x32_bf16 v[120:123], v[236:239], v[32:35], v[120:123]
	v_mfma_f32_16x16x32_bf16 v[116:119], v[236:239], v[28:31], v[116:119]
	ds_read_b128 v[228:231], v181
	s_waitcnt lgkmcnt(5)
	v_mfma_f32_16x16x32_bf16 v[128:131], v[240:243], v[32:35], v[128:131]
	v_mfma_f32_16x16x32_bf16 v[124:127], v[240:243], v[28:31], v[124:127]
	ds_read_b128 v[232:235], v179 offset:1536
	s_waitcnt lgkmcnt(5)
	v_mfma_f32_16x16x32_bf16 v[120:123], v[244:247], v[16:19], v[120:123]
	v_mfma_f32_16x16x32_bf16 v[116:119], v[244:247], v[20:23], v[116:119]
	s_waitcnt lgkmcnt(4)
	v_mfma_f32_16x16x32_bf16 v[128:131], v[248:251], v[16:19], v[128:131]
	v_mfma_f32_16x16x32_bf16 v[124:127], v[248:251], v[20:23], v[124:127]
	s_waitcnt lgkmcnt(3)
	v_mfma_f32_16x16x32_bf16 v[120:123], v[220:223], v[12:15], v[120:123]
	v_mfma_f32_16x16x32_bf16 v[116:119], v[220:223], v[8:11], v[116:119]
	s_waitcnt lgkmcnt(2)
	v_mfma_f32_16x16x32_bf16 v[128:131], v[224:227], v[12:15], v[128:131]
	v_mfma_f32_16x16x32_bf16 v[124:127], v[224:227], v[8:11], v[124:127]
	s_waitcnt lgkmcnt(1)
	v_mfma_f32_16x16x32_bf16 v[188:191], v[228:231], v[4:7], v[120:123]
	v_mfma_f32_16x16x32_bf16 v[184:187], v[228:231], v[0:3], v[116:119]
	s_waitcnt lgkmcnt(0)
	v_mfma_f32_16x16x32_bf16 v[192:195], v[232:235], v[4:7], v[128:131]
	v_mfma_f32_16x16x32_bf16 v[196:199], v[232:235], v[0:3], v[124:127]
	ds_read_b128 v[220:223], v255 offset:24576
	ds_read_b128 v[224:227], v255 offset:26624
	ds_read_b128 v[228:231], v255 offset:28672
	ds_read_b128 v[232:235], v255 offset:30720
	ds_read_b128 v[236:239], v255 offset:32768
	ds_read_b128 v[240:243], v255 offset:34816
	ds_read_b128 v[244:247], v255 offset:36864
	ds_read_b128 v[248:251], v255 offset:38912
	v_exp_f32_e32 v123, v188
	v_exp_f32_e32 v121, v190
	v_exp_f32_e32 v122, v184
	v_exp_f32_e32 v120, v186
	v_exp_f32_e32 v126, v197
	v_exp_f32_e32 v118, v196
	v_exp_f32_e32 v116, v198
	v_exp_f32_e32 v131, v189
	v_exp_f32_e32 v129, v191
	v_exp_f32_e32 v119, v192
	v_exp_f32_e32 v127, v193
	v_exp_f32_e32 v117, v194
	v_exp_f32_e32 v125, v195
	v_exp_f32_e32 v130, v185
	v_exp_f32_e32 v128, v187
	v_exp_f32_e32 v124, v199
	v_cvt_pk_bf16_f32 v184, v123, v131
	v_cvt_pk_bf16_f32 v185, v121, v129
	v_cvt_pk_bf16_f32 v186, v119, v127
	v_cvt_pk_bf16_f32 v187, v117, v125
	v_cvt_pk_bf16_f32 v188, v122, v130
	v_cvt_pk_bf16_f32 v189, v120, v128
	v_cvt_pk_bf16_f32 v190, v118, v126
	v_cvt_pk_bf16_f32 v191, v116, v124
	s_nop 1
	s_waitcnt lgkmcnt(7)
	v_mfma_f32_16x16x32_bf16 v[108:111], v[220:223], v[184:187], v[108:111]
	v_mfma_f32_16x16x32_bf16 v[112:115], v[220:223], v[188:191], v[112:115]
	s_waitcnt lgkmcnt(6)
	v_mfma_f32_16x16x32_bf16 v[100:103], v[224:227], v[184:187], v[100:103]
	v_mfma_f32_16x16x32_bf16 v[104:107], v[224:227], v[188:191], v[104:107]
	s_waitcnt lgkmcnt(5)
	v_mfma_f32_16x16x32_bf16 v[96:99], v[228:231], v[184:187], v[96:99]
	v_mfma_f32_16x16x32_bf16 v[60:63], v[228:231], v[188:191], v[60:63]
	s_waitcnt lgkmcnt(4)
	v_mfma_f32_16x16x32_bf16 v[92:95], v[232:235], v[184:187], v[92:95]
	v_mfma_f32_16x16x32_bf16 v[52:55], v[232:235], v[188:191], v[52:55]
	s_waitcnt lgkmcnt(3)
	v_mfma_f32_16x16x32_bf16 v[88:91], v[236:239], v[184:187], v[88:91]
	v_mfma_f32_16x16x32_bf16 v[56:59], v[236:239], v[188:191], v[56:59]
	s_waitcnt lgkmcnt(2)
	v_mfma_f32_16x16x32_bf16 v[76:79], v[240:243], v[184:187], v[76:79]
	v_mfma_f32_16x16x32_bf16 v[64:67], v[240:243], v[188:191], v[64:67]
	s_waitcnt lgkmcnt(1)
	v_mfma_f32_16x16x32_bf16 v[84:87], v[244:247], v[184:187], v[84:87]
	v_mfma_f32_16x16x32_bf16 v[68:71], v[244:247], v[188:191], v[68:71]
	s_waitcnt lgkmcnt(0)
	v_mfma_f32_16x16x32_bf16 v[80:83], v[248:251], v[184:187], v[80:83]
	v_mfma_f32_16x16x32_bf16 v[72:75], v[248:251], v[188:191], v[72:75]
	s_branch .LBB0_560
	s_xor_b32 s54, s58, 1
	s_mul_i32 s54, s54, 0xa000
	s_add_i32 s55, s54, s94
	s_add_i32 s64, s54, s93
	s_add_i32 s58, s55, 0x6400
	s_add_i32 s59, s55, 0x6000
	s_add_i32 s65, s64, 0x800
	s_add_i32 s72, s64, 0x400
	v_mov_b32_e32 v184, v154
	s_add_u32 s54, s22, s45
	s_addc_u32 s55, s23, s56
	s_mov_b32 m0, s64
	s_nop 0
	global_load_lds_dwordx4 v184, s[54:55]
	v_mov_b32_e32 v184, v155
	s_mov_b32 m0, s72
	s_nop 0
	global_load_lds_dwordx4 v184, s[54:55]
	v_mov_b32_e32 v184, v156
	s_mov_b32 m0, s65
	s_nop 0
	global_load_lds_dwordx4 v184, s[54:55]
	v_mov_b32_e32 v184, v157
	s_add_u32 s54, s22, s2
	s_addc_u32 s55, s23, s3
	s_mov_b32 m0, s59
	s_nop 0
	global_load_lds_dwordx4 v184, s[54:55]
	v_mov_b32_e32 v184, v158
	s_mov_b32 m0, s58
	s_nop 0
	global_load_lds_dwordx4 v184, s[54:55]
	s_branch .LBB0_560

; DEVI unsigned pk2(float lo, float hi) { f32x2 v = {lo, hi}; bfv2 b = __builtin_convertvector(v, bfv2); return __builtin_bit_cast(unsigned, b); }
; DEVI float bflo(unsigned u) { return __uint_as_float(u << 16); }
; DEVI float bfhi(unsigned u) { return __uint_as_float(u & 0xffff0000u); }
; template <bool GDN>
; DEVI void scan_chain(int sw, const P& p, int item, char* smraw) {
;     ...
; #pragma unroll
;       for (int i = 0; i < 4; ++i) {
;         int c = tid + 256 * i, row = c >> 4, kc = c & 15;
;         u32x4 uq = *(const u32x4*)(gq + row * 128 + kc * 8), uk = *(const u32x4*)(gk + row * 128 + kc * 8);
;         float fe = f_e[row], fk = f_b[row] * fe;
;         u32x4 oq, ok;
; #pragma unroll
;         for (int j = 0; j < 4; ++j) { oq[j] = pk2(bflo(uq[j]) * fe, bfhi(uq[j]) * fe); ok[j] = pk2(bflo(uk[j]) * fk, bfhi(uk[j]) * fk); }
;         *(u32x4*)(qd + row * 136 + kc * 8) = oq;
;         *(u32x4*)(kbg + row * 136 + kc * 8) = ok;
;       }
; #pragma unroll
;       for (int i = 0; i < 4; ++i) {
;         int c = tid + 256 * i, row = c >> 3, cc = c & 7;
;         u32x4 u = *(const u32x4*)(gkt + (size_t)row * TPS + cc * 8), o;
; #pragma unroll
;         for (int j = 0; j < 4; ++j) o[j] = pk2(bflo(u[j]) * f_k[cc * 8 + 2 * j], bfhi(u[j]) * f_k[cc * 8 + 2 * j + 1]);
;         *(u32x4*)(kend + row * 72 + cc * 8) = o;
;       }
.LBB0_568:
	s_or_b64 exec, exec, s[56:57]
	s_add_i32 s56, s58, s81
	s_add_u32 s54, s83, s46
	s_addc_u32 s55, s82, s47
	s_lshl_b64 s[54:55], s[54:55], 8
	v_lshl_add_u64 v[34:35], v[58:59], 0, s[54:55]
	v_lshl_add_u64 v[36:37], v[34:35], 0, v[94:95]
	s_waitcnt lgkmcnt(0)
	s_barrier
	v_lshl_add_u64 v[32:33], v[60:61], 0, s[54:55]
	v_lshl_add_u64 v[40:41], v[32:33], 0, v[94:95]
	ds_read_b32 v44, v113
	ds_read_b32 v45, v114
	s_lshl_b64 s[58:59], s[46:47], 1
	s_ashr_i32 s57, s56, 31
	s_lshl_b64 s[54:55], s[56:57], 13
	v_add_u32_e32 v127, 0x2000, v85
	s_waitcnt lgkmcnt(0)
	v_mul_f32_e32 v46, v44, v45
	v_add_u32_e32 v149, 0x3000, v85
	s_add_i32 s72, s72, 1
	s_add_i32 s4, s4, -1
	s_cmpk_eq_i32 s4, 0xffbc
	s_waitcnt vmcnt(19)
	v_mov_b32_e32 v36, v170
	v_mov_b32_e32 v37, v171
	v_mov_b32_e32 v38, v172
	v_mov_b32_e32 v39, v173
	v_lshlrev_b32_e32 v48, 16, v36
	v_and_b32_e32 v49, 0xffff0000, v36
	v_pk_mul_f32 v[48:49], v[44:45], v[48:49] op_sel_hi:[0,1]
	v_cvt_pk_bf16_f32 v36, v48, v49
	s_waitcnt vmcnt(18)
	v_mov_b32_e32 v40, v174
	v_mov_b32_e32 v41, v175
	v_mov_b32_e32 v42, v176
	v_mov_b32_e32 v43, v177
	v_lshlrev_b32_e32 v48, 16, v40
	v_and_b32_e32 v49, 0xffff0000, v40
	v_pk_mul_f32 v[48:49], v[46:47], v[48:49] op_sel_hi:[0,1]
	v_cvt_pk_bf16_f32 v40, v48, v49
	v_lshlrev_b32_e32 v48, 16, v37
	v_and_b32_e32 v49, 0xffff0000, v37
	v_pk_mul_f32 v[48:49], v[44:45], v[48:49] op_sel_hi:[0,1]
	v_cvt_pk_bf16_f32 v37, v48, v49
	v_lshlrev_b32_e32 v48, 16, v41
	v_and_b32_e32 v49, 0xffff0000, v41
	v_pk_mul_f32 v[48:49], v[46:47], v[48:49] op_sel_hi:[0,1]
	v_cvt_pk_bf16_f32 v41, v48, v49
	v_lshlrev_b32_e32 v48, 16, v38
	v_and_b32_e32 v49, 0xffff0000, v38
	v_pk_mul_f32 v[48:49], v[44:45], v[48:49] op_sel_hi:[0,1]
	v_cvt_pk_bf16_f32 v38, v48, v49
	v_lshlrev_b32_e32 v48, 16, v42
	v_and_b32_e32 v49, 0xffff0000, v42
	v_pk_mul_f32 v[48:49], v[46:47], v[48:49] op_sel_hi:[0,1]
	v_cvt_pk_bf16_f32 v42, v48, v49
	v_lshlrev_b32_e32 v48, 16, v39
	v_and_b32_e32 v49, 0xffff0000, v39
	v_pk_mul_f32 v[44:45], v[44:45], v[48:49] op_sel_hi:[0,1]
	v_cvt_pk_bf16_f32 v39, v44, v45
	v_lshlrev_b32_e32 v44, 16, v43
	v_and_b32_e32 v45, 0xffff0000, v43
	v_pk_mul_f32 v[44:45], v[46:47], v[44:45] op_sel_hi:[0,1]
	v_cvt_pk_bf16_f32 v43, v44, v45
	ds_write_b128 v74, v[36:39] offset:17408
	ds_write_b128 v74, v[40:43]
	v_lshl_add_u64 v[36:37], v[34:35], 0, v[96:97]
	v_lshl_add_u64 v[40:41], v[32:33], 0, v[96:97]
	ds_read_b32 v44, v75
	ds_read_b32 v45, v115
	s_waitcnt lgkmcnt(0)
	v_mul_f32_e32 v46, v44, v45
	s_waitcnt vmcnt(17)
	v_mov_b32_e32 v36, v178
	v_mov_b32_e32 v37, v179
	v_mov_b32_e32 v38, v180
	v_mov_b32_e32 v39, v181
	v_lshlrev_b32_e32 v48, 16, v36
	v_and_b32_e32 v49, 0xffff0000, v36
	v_pk_mul_f32 v[48:49], v[44:45], v[48:49] op_sel_hi:[0,1]
	v_cvt_pk_bf16_f32 v36, v48, v49
	s_waitcnt vmcnt(16)
	v_mov_b32_e32 v40, v182
	v_mov_b32_e32 v41, v183
	v_mov_b32_e32 v42, v184
	v_mov_b32_e32 v43, v185
	v_lshlrev_b32_e32 v48, 16, v40
	v_and_b32_e32 v49, 0xffff0000, v40
	v_pk_mul_f32 v[48:49], v[46:47], v[48:49] op_sel_hi:[0,1]
	v_cvt_pk_bf16_f32 v40, v48, v49
	v_lshlrev_b32_e32 v48, 16, v37
	v_and_b32_e32 v49, 0xffff0000, v37
	v_pk_mul_f32 v[48:49], v[44:45], v[48:49] op_sel_hi:[0,1]
	v_cvt_pk_bf16_f32 v37, v48, v49
	v_lshlrev_b32_e32 v48, 16, v41
	v_and_b32_e32 v49, 0xffff0000, v41
	v_pk_mul_f32 v[48:49], v[46:47], v[48:49] op_sel_hi:[0,1]
	v_cvt_pk_bf16_f32 v41, v48, v49
	v_lshlrev_b32_e32 v48, 16, v38
	v_and_b32_e32 v49, 0xffff0000, v38
	v_pk_mul_f32 v[48:49], v[44:45], v[48:49] op_sel_hi:[0,1]
	v_cvt_pk_bf16_f32 v38, v48, v49
	v_lshlrev_b32_e32 v48, 16, v42
	v_and_b32_e32 v49, 0xffff0000, v42
	v_pk_mul_f32 v[48:49], v[46:47], v[48:49] op_sel_hi:[0,1]
	v_cvt_pk_bf16_f32 v42, v48, v49
	v_lshlrev_b32_e32 v48, 16, v39
	v_and_b32_e32 v49, 0xffff0000, v39
	v_pk_mul_f32 v[44:45], v[44:45], v[48:49] op_sel_hi:[0,1]
	v_cvt_pk_bf16_f32 v39, v44, v45
	v_lshlrev_b32_e32 v44, 16, v43
	v_and_b32_e32 v45, 0xffff0000, v43
	v_pk_mul_f32 v[44:45], v[46:47], v[44:45] op_sel_hi:[0,1]
	v_cvt_pk_bf16_f32 v43, v44, v45
	ds_write_b128 v76, v[36:39] offset:17408
	ds_write_b128 v76, v[40:43]
	v_lshl_add_u64 v[36:37], v[34:35], 0, v[98:99]
	v_lshl_add_u64 v[40:41], v[32:33], 0, v[98:99]
	ds_read_b32 v44, v77
	ds_read_b32 v45, v116
	v_lshl_add_u64 v[34:35], v[34:35], 0, v[100:101]
	v_lshl_add_u64 v[32:33], v[32:33], 0, v[100:101]
	s_waitcnt lgkmcnt(0)
	v_mul_f32_e32 v46, v44, v45
	s_waitcnt vmcnt(15)
	v_mov_b32_e32 v36, v186
	v_mov_b32_e32 v37, v187
	v_mov_b32_e32 v38, v188
	v_mov_b32_e32 v39, v189
	v_lshlrev_b32_e32 v48, 16, v36
	v_and_b32_e32 v49, 0xffff0000, v36
	v_pk_mul_f32 v[48:49], v[44:45], v[48:49] op_sel_hi:[0,1]
	v_cvt_pk_bf16_f32 v36, v48, v49
	s_waitcnt vmcnt(14)
	v_mov_b32_e32 v40, v190
	v_mov_b32_e32 v41, v191
	v_mov_b32_e32 v42, v192
	v_mov_b32_e32 v43, v193
	v_lshlrev_b32_e32 v48, 16, v40
	v_and_b32_e32 v49, 0xffff0000, v40
	v_pk_mul_f32 v[48:49], v[46:47], v[48:49] op_sel_hi:[0,1]
	v_cvt_pk_bf16_f32 v40, v48, v49
	v_lshlrev_b32_e32 v48, 16, v37
	v_and_b32_e32 v49, 0xffff0000, v37
	v_pk_mul_f32 v[48:49], v[44:45], v[48:49] op_sel_hi:[0,1]
	v_cvt_pk_bf16_f32 v37, v48, v49
	v_lshlrev_b32_e32 v48, 16, v41
	v_and_b32_e32 v49, 0xffff0000, v41
	v_pk_mul_f32 v[48:49], v[46:47], v[48:49] op_sel_hi:[0,1]
	v_cvt_pk_bf16_f32 v41, v48, v49
	v_lshlrev_b32_e32 v48, 16, v38
	v_and_b32_e32 v49, 0xffff0000, v38
	v_pk_mul_f32 v[48:49], v[44:45], v[48:49] op_sel_hi:[0,1]
	v_cvt_pk_bf16_f32 v38, v48, v49
	v_lshlrev_b32_e32 v48, 16, v42
	v_and_b32_e32 v49, 0xffff0000, v42
	v_pk_mul_f32 v[48:49], v[46:47], v[48:49] op_sel_hi:[0,1]
	v_cvt_pk_bf16_f32 v42, v48, v49
	v_lshlrev_b32_e32 v48, 16, v39
	v_and_b32_e32 v49, 0xffff0000, v39
	v_pk_mul_f32 v[44:45], v[44:45], v[48:49] op_sel_hi:[0,1]
	v_cvt_pk_bf16_f32 v39, v44, v45
	v_lshlrev_b32_e32 v44, 16, v43
	v_and_b32_e32 v45, 0xffff0000, v43
	v_pk_mul_f32 v[44:45], v[46:47], v[44:45] op_sel_hi:[0,1]
	v_cvt_pk_bf16_f32 v43, v44, v45
	ds_write_b128 v78, v[36:39] offset:17408
	ds_write_b128 v78, v[40:43]
	v_lshl_add_u64 v[48:49], v[68:69], 0, s[58:59]
	ds_read_b32 v42, v79
	ds_read_b32 v32, v117
	s_waitcnt lgkmcnt(0)
; DEVI unsigned pk2(float lo, float hi) { f32x2 v = {lo, hi}; bfv2 b = __builtin_convertvector(v, bfv2); return __builtin_bit_cast(unsigned, b); }
; DEVI float bflo(unsigned u) { return __uint_as_float(u << 16); }
; DEVI float bfhi(unsigned u) { return __uint_as_float(u & 0xffff0000u); }
; template <bool GDN>
; DEVI void scan_chain(int sw, const P& p, int item, char* smraw) {
;     ...
; #pragma unroll
;       for (int i = 0; i < 4; ++i) {
;         int c = tid + 256 * i, row = c >> 4, kc = c & 15;
;         u32x4 uq = *(const u32x4*)(gq + row * 128 + kc * 8), uk = *(const u32x4*)(gk + row * 128 + kc * 8);
;         float fe = f_e[row], fk = f_b[row] * fe;
;         u32x4 oq, ok;
; #pragma unroll
;         for (int j = 0; j < 4; ++j) { oq[j] = pk2(bflo(uq[j]) * fe, bfhi(uq[j]) * fe); ok[j] = pk2(bflo(uk[j]) * fk, bfhi(uk[j]) * fk); }
;         *(u32x4*)(qd + row * 136 + kc * 8) = oq;
;         *(u32x4*)(kbg + row * 136 + kc * 8) = ok;
;       }
; #pragma unroll
;       for (int i = 0; i < 4; ++i) {
;         int c = tid + 256 * i, row = c >> 3, cc = c & 7;
;         u32x4 u = *(const u32x4*)(gkt + (size_t)row * TPS + cc * 8), o;
; #pragma unroll
;         for (int j = 0; j < 4; ++j) o[j] = pk2(bflo(u[j]) * f_k[cc * 8 + 2 * j], bfhi(u[j]) * f_k[cc * 8 + 2 * j + 1]);
;         *(u32x4*)(kend + row * 72 + cc * 8) = o;
;       }
; #pragma unroll
;       for (int i = 0; i < 2; ++i) {
;         int c = tid + 256 * i, row = c >> 3, cc = c & 7;
;         *(u32x4*)(Tm + row * 72 + cc * 8) = *(const u32x4*)(tm + row * 64 + cc * 8);
;         *(u32x4*)(QK + row * 72 + cc * 8) = *(const u32x4*)(qkm + row * 64 + cc * 8);
;       }
	v_mul_f32_e32 v44, v42, v32
	s_waitcnt vmcnt(13)
	v_mov_b32_e32 v34, v194
	v_mov_b32_e32 v35, v195
	v_mov_b32_e32 v36, v196
	v_mov_b32_e32 v37, v197
	v_lshlrev_b32_e32 v32, 16, v34
	v_and_b32_e32 v33, 0xffff0000, v34
	v_lshlrev_b32_e32 v34, 16, v35
	v_and_b32_e32 v35, 0xffff0000, v35
	v_pk_mul_f32 v[32:33], v[42:43], v[32:33] op_sel_hi:[0,1]
	v_pk_mul_f32 v[34:35], v[42:43], v[34:35] op_sel_hi:[0,1]
	v_cvt_pk_bf16_f32 v32, v32, v33
	v_cvt_pk_bf16_f32 v33, v34, v35
	s_waitcnt vmcnt(12)
	v_mov_b32_e32 v38, v198
	v_mov_b32_e32 v39, v199
	v_mov_b32_e32 v40, v200
	v_mov_b32_e32 v41, v201
	v_lshlrev_b32_e32 v34, 16, v39
	v_and_b32_e32 v35, 0xffff0000, v39
	v_pk_mul_f32 v[34:35], v[44:45], v[34:35] op_sel_hi:[0,1]
	v_lshlrev_b32_e32 v46, 16, v38
	v_and_b32_e32 v47, 0xffff0000, v38
	v_cvt_pk_bf16_f32 v39, v34, v35
	v_lshlrev_b32_e32 v34, 16, v36
	v_and_b32_e32 v35, 0xffff0000, v36
	v_lshlrev_b32_e32 v36, 16, v37
	v_and_b32_e32 v37, 0xffff0000, v37
	v_pk_mul_f32 v[46:47], v[44:45], v[46:47] op_sel_hi:[0,1]
	v_pk_mul_f32 v[34:35], v[42:43], v[34:35] op_sel_hi:[0,1]
	v_pk_mul_f32 v[36:37], v[42:43], v[36:37] op_sel_hi:[0,1]
	v_cvt_pk_bf16_f32 v38, v46, v47
	v_cvt_pk_bf16_f32 v34, v34, v35
	v_lshlrev_b32_e32 v46, 16, v40
	v_and_b32_e32 v47, 0xffff0000, v40
	v_cvt_pk_bf16_f32 v35, v36, v37
	v_lshlrev_b32_e32 v36, 16, v41
	v_and_b32_e32 v37, 0xffff0000, v41
	v_pk_mul_f32 v[46:47], v[44:45], v[46:47] op_sel_hi:[0,1]
	v_pk_mul_f32 v[36:37], v[44:45], v[36:37] op_sel_hi:[0,1]
	v_cvt_pk_bf16_f32 v40, v46, v47
	v_cvt_pk_bf16_f32 v41, v36, v37
	ds_write_b128 v80, v[32:35] offset:17408
	ds_write_b128 v80, v[38:41]
	v_lshl_add_u64 v[32:33], v[62:63], 0, s[58:59]
	v_lshl_add_u64 v[34:35], v[32:33], 0, v[82:83]
	ds_read_b128 v[38:41], v81
	ds_read_b128 v[42:45], v81 offset:16
	s_waitcnt vmcnt(11)
	v_mov_b32_e32 v34, v202
	v_mov_b32_e32 v35, v203
	v_mov_b32_e32 v36, v204
	v_mov_b32_e32 v37, v205
	v_lshlrev_b32_e32 v46, 16, v34
	v_and_b32_e32 v47, 0xffff0000, v34
	s_waitcnt lgkmcnt(1)
	v_pk_mul_f32 v[38:39], v[38:39], v[46:47]
	s_nop 0
	v_cvt_pk_bf16_f32 v34, v38, v39
	v_lshlrev_b32_e32 v38, 16, v35
	v_and_b32_e32 v39, 0xffff0000, v35
	v_pk_mul_f32 v[38:39], v[40:41], v[38:39]
	s_nop 0
	v_cvt_pk_bf16_f32 v35, v38, v39
	v_lshlrev_b32_e32 v38, 16, v36
	v_and_b32_e32 v39, 0xffff0000, v36
	s_waitcnt lgkmcnt(0)
	v_pk_mul_f32 v[38:39], v[42:43], v[38:39]
	s_nop 0
	v_cvt_pk_bf16_f32 v36, v38, v39
	v_lshlrev_b32_e32 v38, 16, v37
	v_and_b32_e32 v39, 0xffff0000, v37
	v_pk_mul_f32 v[38:39], v[44:45], v[38:39]
	s_nop 0
	v_cvt_pk_bf16_f32 v37, v38, v39
	ds_write_b128 v84, v[34:37] offset:34816
	v_lshl_add_u64 v[34:35], v[32:33], 0, v[86:87]
	ds_read_b128 v[38:41], v81
	ds_read_b128 v[42:45], v81 offset:16
	s_waitcnt vmcnt(10)
	v_mov_b32_e32 v34, v206
	v_mov_b32_e32 v35, v207
	v_mov_b32_e32 v36, v208
	v_mov_b32_e32 v37, v209
	v_lshlrev_b32_e32 v46, 16, v34
	v_and_b32_e32 v47, 0xffff0000, v34
	s_waitcnt lgkmcnt(1)
	v_pk_mul_f32 v[38:39], v[38:39], v[46:47]
	s_nop 0
	v_cvt_pk_bf16_f32 v34, v38, v39
	v_lshlrev_b32_e32 v38, 16, v35
	v_and_b32_e32 v39, 0xffff0000, v35
	v_pk_mul_f32 v[38:39], v[40:41], v[38:39]
	s_nop 0
	v_cvt_pk_bf16_f32 v35, v38, v39
	v_lshlrev_b32_e32 v38, 16, v36
	v_and_b32_e32 v39, 0xffff0000, v36
	s_waitcnt lgkmcnt(0)
	v_pk_mul_f32 v[38:39], v[42:43], v[38:39]
	s_nop 0
	v_cvt_pk_bf16_f32 v36, v38, v39
	v_lshlrev_b32_e32 v38, 16, v37
	v_and_b32_e32 v39, 0xffff0000, v37
	v_pk_mul_f32 v[38:39], v[44:45], v[38:39]
	s_nop 0
	v_cvt_pk_bf16_f32 v37, v38, v39
	ds_write_b128 v88, v[34:37] offset:34816
	v_lshl_add_u64 v[34:35], v[32:33], 0, v[90:91]
	ds_read_b128 v[38:41], v81
	ds_read_b128 v[42:45], v81 offset:16
	v_lshl_add_u64 v[32:33], v[32:33], 0, v[92:93]
	s_waitcnt vmcnt(9)
	v_mov_b32_e32 v34, v210
	v_mov_b32_e32 v35, v211
	v_mov_b32_e32 v36, v212
	v_mov_b32_e32 v37, v213
	v_lshlrev_b32_e32 v46, 16, v34
	v_and_b32_e32 v47, 0xffff0000, v34
	s_waitcnt lgkmcnt(1)
	v_pk_mul_f32 v[38:39], v[38:39], v[46:47]
	v_cvt_pk_bf16_f32 v46, v12, v13
	v_cvt_pk_bf16_f32 v34, v38, v39
	v_lshlrev_b32_e32 v38, 16, v35
	v_and_b32_e32 v39, 0xffff0000, v35
	v_pk_mul_f32 v[38:39], v[40:41], v[38:39]
	v_cvt_pk_bf16_f32 v47, v14, v15
	v_cvt_pk_bf16_f32 v35, v38, v39
	v_lshlrev_b32_e32 v38, 16, v36
	v_and_b32_e32 v39, 0xffff0000, v36
	s_waitcnt lgkmcnt(0)
	v_pk_mul_f32 v[38:39], v[42:43], v[38:39]
	s_nop 0
	v_cvt_pk_bf16_f32 v36, v38, v39
	v_lshlrev_b32_e32 v38, 16, v37
	v_and_b32_e32 v39, 0xffff0000, v37
	v_pk_mul_f32 v[38:39], v[44:45], v[38:39]
	s_nop 0
	v_cvt_pk_bf16_f32 v37, v38, v39
	ds_write_b128 v122, v[34:37] offset:34816
	ds_read_b128 v[36:39], v81
	ds_read_b128 v[40:43], v81 offset:16
	s_waitcnt vmcnt(8)
	v_mov_b32_e32 v32, v214
	v_mov_b32_e32 v33, v215
	v_mov_b32_e32 v34, v216
	v_mov_b32_e32 v35, v217
	v_lshlrev_b32_e32 v44, 16, v32
	v_and_b32_e32 v45, 0xffff0000, v32
	s_waitcnt lgkmcnt(1)
	v_pk_mul_f32 v[36:37], v[36:37], v[44:45]
	v_cvt_pk_bf16_f32 v44, v8, v9
	v_cvt_pk_bf16_f32 v32, v36, v37
	v_lshlrev_b32_e32 v36, 16, v33
	v_and_b32_e32 v37, 0xffff0000, v33
	v_pk_mul_f32 v[36:37], v[38:39], v[36:37]
	v_lshl_add_u64 v[38:39], v[66:67], 0, s[54:55]
	v_cvt_pk_bf16_f32 v33, v36, v37
	v_lshlrev_b32_e32 v36, 16, v34
	v_and_b32_e32 v37, 0xffff0000, v34
	s_waitcnt lgkmcnt(0)
	v_pk_mul_f32 v[36:37], v[40:41], v[36:37]
	v_cvt_pk_bf16_f32 v40, v4, v5
	v_cvt_pk_bf16_f32 v34, v36, v37
	v_lshlrev_b32_e32 v36, 16, v35
	v_and_b32_e32 v37, 0xffff0000, v35
	v_pk_mul_f32 v[36:37], v[42:43], v[36:37]
	v_cvt_pk_bf16_f32 v41, v6, v7
	v_cvt_pk_bf16_f32 v35, v36, v37
	v_lshl_add_u64 v[36:37], v[64:65], 0, s[54:55]
	ds_write_b128 v123, v[32:35] offset:34816
	v_lshl_add_u64 v[32:33], v[36:37], 0, v[102:103]
	v_cvt_pk_bf16_f32 v42, v0, v1
	v_cvt_pk_bf16_f32 v43, v2, v3
	v_cvt_pk_bf16_f32 v45, v10, v11
	s_waitcnt vmcnt(7)
	v_mov_b32_e32 v32, v220
	v_mov_b32_e32 v33, v221
	v_mov_b32_e32 v34, v222
	v_mov_b32_e32 v35, v223
	ds_write_b128 v84, v[32:35] offset:53248
	v_lshl_add_u64 v[32:33], v[38:39], 0, v[102:103]
	s_waitcnt vmcnt(6)
	v_mov_b32_e32 v32, v224
	v_mov_b32_e32 v33, v225
	v_mov_b32_e32 v34, v226
	v_mov_b32_e32 v35, v227
	ds_write_b128 v84, v[32:35] offset:62464
	v_lshl_add_u64 v[32:33], v[36:37], 0, v[104:105]
	v_cvt_pk_bf16_f32 v36, v16, v17
	v_cvt_pk_bf16_f32 v37, v18, v19
	s_waitcnt vmcnt(5)
	v_mov_b32_e32 v32, v228
	v_mov_b32_e32 v33, v229
	v_mov_b32_e32 v34, v230
	v_mov_b32_e32 v35, v231
	ds_write_b128 v88, v[32:35] offset:53248
	v_lshl_add_u64 v[32:33], v[38:39], 0, v[104:105]
	v_cvt_pk_bf16_f32 v38, v20, v21
	v_cvt_pk_bf16_f32 v39, v22, v23
	s_waitcnt vmcnt(4)
	v_mov_b32_e32 v32, v232
	v_mov_b32_e32 v33, v233
	v_mov_b32_e32 v34, v234
	v_mov_b32_e32 v35, v235
	ds_write_b128 v88, v[32:35] offset:62464
	s_waitcnt lgkmcnt(0)
	s_barrier
; DEVI float bflo(unsigned u) { return __uint_as_float(u << 16); }
; DEVI float bfhi(unsigned u) { return __uint_as_float(u & 0xffff0000u); }
; DEVI f32x4 mfma16(bf16x8 a, bf16x8 b, f32x4 c) { return __builtin_amdgcn_mfma_f32_16x16x32_bf16(a, b, c, 0, 0, 0); }
; DEVI bf16x8 pack8(f32x4 a, f32x4 b) { u32x4 u = {pk2(a[0], a[1]), pk2(a[2], a[3]), pk2(b[0], b[1]), pk2(b[2], b[3])}; return __builtin_bit_cast(bf16x8, u); }
; template <bool GDN>
; DEVI void scan_chain(int sw, const P& p, int item, char* smraw) {
;     ...
;     bf16x8 vop[2];
;     if (GDN) {
;       const bf16_t* gvt = (const bf16_t*)(R2 + R_GVT) + ((size_t)bh * 128 + e0 + fr) * TPS + p0;
;       f32x4 X[4];
; #pragma unroll
;       for (int ct = 0; ct < 4; ++ct) {
;         u32x2 u = *(const u32x2*)(gvt + ct * 16 + fq * 4);
;         const float* fb = f_b + ct * 16 + fq * 4;
;         f32x4 vb = {bflo(u[0]) * fb[0], bfhi(u[0]) * fb[1], bflo(u[1]) * fb[2], bfhi(u[1]) * fb[3]};
;         f32x4 acc = {0.f, 0.f, 0.f, 0.f};
; #pragma unroll
;         for (int ks = 0; ks < 4; ++ks) acc = mfma16(ldsperm(kbg, ct * 16 + fr, 136, ks, fq), Sop[ks], acc);
;         X[ct] = vb - acc;
;       }
;       bf16x8 Xop[2] = {pack8(X[0], X[1]), pack8(X[2], X[3])};
;       f32x4 vn[4];
; #pragma unroll
;       for (int ct = 0; ct < 4; ++ct) {
;         f32x4 acc = {0.f, 0.f, 0.f, 0.f};
; #pragma unroll
;         for (int kk = 0; kk < 2; ++kk) acc = mfma16(ldsperm(Tm, ct * 16 + fr, 72, kk, fq), Xop[kk], acc);
;         vn[ct] = acc;
;       }
;       vop[0] = pack8(vn[0], vn[1]); vop[1] = pack8(vn[2], vn[3]);
	ds_read_b128 v[50:53], v108
	ds_read2_b64 v[128:131], v85 offset0:8 offset1:12
	v_cvt_pk_bf16_f32 v32, v28, v29
	v_cvt_pk_bf16_f32 v33, v30, v31
	v_cvt_pk_bf16_f32 v34, v24, v25
	v_cvt_pk_bf16_f32 v35, v26, v27
	s_waitcnt vmcnt(3)
	v_mov_b32_e32 v54, v236
	v_mov_b32_e32 v55, v237
	v_lshlrev_b32_e32 v106, 16, v54
	v_and_b32_e32 v107, 0xffff0000, v54
	s_waitcnt lgkmcnt(1)
	v_pk_mul_f32 v[106:107], v[50:51], v[106:107]
	v_lshlrev_b32_e32 v50, 16, v55
	v_and_b32_e32 v51, 0xffff0000, v55
	v_pk_mul_f32 v[54:55], v[52:53], v[50:51]
	ds_read2_b64 v[50:53], v85 offset1:4
	s_waitcnt lgkmcnt(0)
	v_mfma_f32_16x16x32_bf16 v[50:53], v[50:53], v[40:43], 0
	v_mfma_f32_16x16x32_bf16 v[50:53], v[128:131], v[44:47], v[50:53]
	ds_read2_b64 v[128:131], v85 offset0:16 offset1:20
	s_waitcnt lgkmcnt(0)
	v_mfma_f32_16x16x32_bf16 v[50:53], v[128:131], v[36:39], v[50:53]
	ds_read2_b64 v[128:131], v85 offset0:24 offset1:28
	s_waitcnt lgkmcnt(0)
	v_mfma_f32_16x16x32_bf16 v[128:131], v[128:131], v[32:35], v[50:53]
	s_nop 7
	v_sub_f32_e32 v50, v55, v131
	v_sub_f32_e32 v51, v54, v130
	v_sub_f32_e32 v52, v107, v129
	v_sub_f32_e32 v53, v106, v128
	ds_read_b128 v[128:131], v108 offset:64
	s_waitcnt vmcnt(2)
	v_mov_b32_e32 v54, v238
	v_mov_b32_e32 v55, v239
	v_lshlrev_b32_e32 v106, 16, v54
	v_and_b32_e32 v107, 0xffff0000, v54
	v_lshlrev_b32_e32 v54, 16, v55
	v_and_b32_e32 v55, 0xffff0000, v55
	s_waitcnt lgkmcnt(0)
	v_pk_mul_f32 v[140:141], v[128:129], v[106:107]
	v_pk_mul_f32 v[106:107], v[130:131], v[54:55]
	v_add_u32_e32 v54, 0x1000, v85
	ds_read2_b64 v[128:131], v54 offset0:32 offset1:36
	ds_read2_b64 v[150:153], v54 offset0:40 offset1:44
	s_waitcnt lgkmcnt(1)
	v_mfma_f32_16x16x32_bf16 v[128:131], v[128:131], v[40:43], 0
	s_waitcnt lgkmcnt(0)
	v_mfma_f32_16x16x32_bf16 v[128:131], v[150:153], v[44:47], v[128:131]
	ds_read2_b64 v[150:153], v54 offset0:48 offset1:52
	s_waitcnt lgkmcnt(0)
	v_mfma_f32_16x16x32_bf16 v[128:131], v[150:153], v[36:39], v[128:131]
	ds_read2_b64 v[150:153], v54 offset0:56 offset1:60
	s_waitcnt lgkmcnt(0)
	v_mfma_f32_16x16x32_bf16 v[128:131], v[150:153], v[32:35], v[128:131]
	s_nop 7
	v_sub_f32_e32 v54, v107, v131
	v_sub_f32_e32 v55, v106, v130
	v_sub_f32_e32 v106, v141, v129
	v_sub_f32_e32 v107, v140, v128
	ds_read_b128 v[128:131], v108 offset:128
	s_waitcnt vmcnt(1)
	v_mov_b32_e32 v140, v240
	v_mov_b32_e32 v141, v241
	v_lshlrev_b32_e32 v150, 16, v140
	v_and_b32_e32 v151, 0xffff0000, v140
	s_waitcnt lgkmcnt(0)
	v_pk_mul_f32 v[154:155], v[128:129], v[150:151]
	v_lshlrev_b32_e32 v128, 16, v141
	v_and_b32_e32 v129, 0xffff0000, v141
	v_pk_mul_f32 v[140:141], v[130:131], v[128:129]
	ds_read2_b64 v[128:131], v127 offset0:64 offset1:68
	ds_read2_b64 v[150:153], v127 offset0:72 offset1:76
	s_waitcnt lgkmcnt(1)
	v_mfma_f32_16x16x32_bf16 v[128:131], v[128:131], v[40:43], 0
	s_waitcnt lgkmcnt(0)
	v_mfma_f32_16x16x32_bf16 v[128:131], v[150:153], v[44:47], v[128:131]
	ds_read2_b64 v[150:153], v127 offset0:80 offset1:84
	s_waitcnt lgkmcnt(0)
	v_mfma_f32_16x16x32_bf16 v[128:131], v[150:153], v[36:39], v[128:131]
	ds_read2_b64 v[150:153], v127 offset0:88 offset1:92
	s_waitcnt lgkmcnt(0)
	v_mfma_f32_16x16x32_bf16 v[128:131], v[150:153], v[32:35], v[128:131]
	ds_read2_b64 v[150:153], v149 offset0:104 offset1:108
	s_nop 6
	v_sub_f32_e32 v127, v141, v131
	v_sub_f32_e32 v132, v140, v130
	v_sub_f32_e32 v135, v155, v129
	v_sub_f32_e32 v138, v154, v128
	ds_read_b128 v[128:131], v108 offset:192
	s_waitcnt vmcnt(0)
	v_mov_b32_e32 v48, v242
	v_mov_b32_e32 v49, v243
	v_lshlrev_b32_e32 v140, 16, v48
	v_and_b32_e32 v141, 0xffff0000, v48
	v_lshlrev_b32_e32 v48, 16, v49
	v_and_b32_e32 v49, 0xffff0000, v49
	s_waitcnt lgkmcnt(0)
	v_pk_mul_f32 v[140:141], v[128:129], v[140:141]
	v_pk_mul_f32 v[48:49], v[130:131], v[48:49]
	ds_read2_b64 v[128:131], v149 offset0:96 offset1:100
	s_waitcnt lgkmcnt(0)
	v_mfma_f32_16x16x32_bf16 v[128:131], v[128:131], v[40:43], 0
	v_mfma_f32_16x16x32_bf16 v[128:131], v[150:153], v[44:47], v[128:131]
	ds_read2_b64 v[150:153], v149 offset0:112 offset1:116
	s_waitcnt lgkmcnt(0)
	v_mfma_f32_16x16x32_bf16 v[128:131], v[150:153], v[36:39], v[128:131]
	ds_read2_b64 v[150:153], v149 offset0:120 offset1:124
	s_waitcnt lgkmcnt(0)
	v_mfma_f32_16x16x32_bf16 v[128:131], v[150:153], v[32:35], v[128:131]
	s_nop 7
	v_sub_f32_e32 v131, v49, v131
	v_sub_f32_e32 v130, v48, v130
	v_sub_f32_e32 v129, v141, v129
	v_sub_f32_e32 v128, v140, v128
	v_cvt_pk_bf16_f32 v49, v51, v50
	v_cvt_pk_bf16_f32 v50, v107, v106
	v_add_u32_e32 v106, 0xd000, v126
	v_cvt_pk_bf16_f32 v51, v55, v54
	v_cvt_pk_bf16_f32 v54, v128, v129
	v_cvt_pk_bf16_f32 v55, v130, v131
	ds_read2_b64 v[128:131], v106 offset1:4
	ds_read2_b64 v[150:153], v106 offset0:8 offset1:12
	v_cvt_pk_bf16_f32 v48, v53, v52
	v_add_u32_e32 v106, v85, v118
	v_cvt_pk_bf16_f32 v52, v138, v135
	s_waitcnt lgkmcnt(1)
	v_mfma_f32_16x16x32_bf16 v[128:131], v[128:131], v[48:51], 0
	v_cvt_pk_bf16_f32 v53, v132, v127
	v_add_u32_e32 v106, 0xe000, v106
	ds_read2_b64 v[154:157], v106 offset0:40 offset1:44
	s_waitcnt lgkmcnt(1)
	v_mfma_f32_16x16x32_bf16 v[128:131], v[150:153], v[52:55], v[128:131]
	ds_read2_b64 v[150:153], v106 offset0:32 offset1:36
	v_add_u32_e32 v106, v85, v119
	v_add_u32_e32 v106, 0xf000, v106
	s_waitcnt lgkmcnt(0)
	v_mfma_f32_16x16x32_bf16 v[150:153], v[150:153], v[48:51], 0
	ds_read2_b64 v[158:161], v106 offset0:72 offset1:76
	v_add_u32_e32 v107, 0x4000, v85
	v_mfma_f32_16x16x32_bf16 v[150:153], v[154:157], v[52:55], v[150:153]
	ds_read2_b64 v[154:157], v106 offset0:64 offset1:68
	v_add_u32_e32 v106, v89, v120
	v_add_u32_e32 v106, 0xf000, v106
	s_waitcnt lgkmcnt(0)
; DEVI f32x4 mfma16(bf16x8 a, bf16x8 b, f32x4 c) { return __builtin_amdgcn_mfma_f32_16x16x32_bf16(a, b, c, 0, 0, 0); }
; DEVI u32x2 pack4(f32x4 a) { u32x2 u = {pk2(a[0], a[1]), pk2(a[2], a[3])}; return u; }
; template <bool GDN>
; DEVI void scan_chain(int sw, const P& p, int item, char* smraw) {
;     ...
; #pragma unroll
;     for (int ct = 0; ct < 4; ++ct) {
;       f32x4 acc = {0.f, 0.f, 0.f, 0.f};
; #pragma unroll
;       for (int ks = 0; ks < 4; ++ks) acc = mfma16(Sop[ks], ldsperm(qd, ct * 16 + fr, 136, ks, fq), acc);
; #pragma unroll
;       for (int kk = 0; kk < 2; ++kk) acc = mfma16(vop[kk], ldsperm(QK, ct * 16 + fr, 72, kk, fq), acc);
;       *(u32x2*)(rec + (size_t)(b * TPB + p0 + ct * 16 + fr) * 1024 + h * DV + e0 + fq * 4) = pack4(acc);
;     }
	v_mfma_f32_16x16x32_bf16 v[154:157], v[154:157], v[48:51], 0
	v_mfma_f32_16x16x32_bf16 v[154:157], v[158:161], v[52:55], v[154:157]
	ds_read2_b64 v[158:161], v106 offset0:64 offset1:68
	s_waitcnt lgkmcnt(0)
	v_mfma_f32_16x16x32_bf16 v[48:51], v[158:161], v[48:51], 0
	ds_read2_b64 v[158:161], v106 offset0:72 offset1:76
	v_add_u32_e32 v106, s46, v109
	s_waitcnt lgkmcnt(0)
	v_mfma_f32_16x16x32_bf16 v[158:161], v[158:161], v[52:55], v[48:51]
	v_cvt_pk_bf16_f32 v52, v128, v129
	v_cvt_pk_bf16_f32 v53, v130, v131
	ds_read2_b64 v[128:131], v107 offset0:128 offset1:132
	v_cvt_pk_bf16_f32 v54, v150, v151
	v_cvt_pk_bf16_f32 v55, v152, v153
	ds_read2_b64 v[150:153], v107 offset0:136 offset1:140
	s_waitcnt lgkmcnt(1)
	v_mfma_f32_16x16x32_bf16 v[128:131], v[40:43], v[128:131], 0
	v_cvt_pk_bf16_f32 v48, v154, v155
	v_cvt_pk_bf16_f32 v49, v156, v157
	v_cvt_pk_bf16_f32 v50, v158, v159
	s_waitcnt lgkmcnt(0)
	v_mfma_f32_16x16x32_bf16 v[128:131], v[44:47], v[150:153], v[128:131]
	ds_read2_b64 v[150:153], v107 offset0:144 offset1:148
	v_cvt_pk_bf16_f32 v51, v160, v161
	s_waitcnt lgkmcnt(0)
	v_mfma_f32_16x16x32_bf16 v[128:131], v[36:39], v[150:153], v[128:131]
	ds_read2_b64 v[150:153], v107 offset0:152 offset1:156
	v_add_u32_e32 v107, 0xf000, v126
	s_waitcnt lgkmcnt(0)
	v_mfma_f32_16x16x32_bf16 v[128:131], v[32:35], v[150:153], v[128:131]
	ds_read2_b64 v[150:153], v107 offset0:128 offset1:132
	s_waitcnt lgkmcnt(0)
	v_mfma_f32_16x16x32_bf16 v[128:131], v[52:55], v[150:153], v[128:131]
	ds_read2_b64 v[150:153], v107 offset0:136 offset1:140
	v_ashrrev_i32_e32 v107, 31, v106
	s_waitcnt lgkmcnt(0)
	v_mfma_f32_16x16x32_bf16 v[128:131], v[48:51], v[150:153], v[128:131]
	s_nop 7
	v_cvt_pk_bf16_f32 v128, v128, v129
	v_cvt_pk_bf16_f32 v129, v130, v131
	v_lshlrev_b64 v[130:131], 11, v[106:107]
	v_lshl_add_u64 v[130:131], v[70:71], 0, v[130:131]
	v_add_u32_e32 v107, 0x5000, v85
	global_store_dwordx2 v[130:131], v[128:129], off
	ds_read2_b64 v[128:131], v107 offset0:160 offset1:164
	ds_read2_b64 v[150:153], v107 offset0:168 offset1:172
	s_waitcnt lgkmcnt(1)
	v_mfma_f32_16x16x32_bf16 v[128:131], v[40:43], v[128:131], 0
	s_waitcnt lgkmcnt(0)
	v_mfma_f32_16x16x32_bf16 v[128:131], v[44:47], v[150:153], v[128:131]
	ds_read2_b64 v[150:153], v107 offset0:176 offset1:180
	s_waitcnt lgkmcnt(0)
	v_mfma_f32_16x16x32_bf16 v[128:131], v[36:39], v[150:153], v[128:131]
	ds_read2_b64 v[150:153], v107 offset0:184 offset1:188
	v_add_u32_e32 v107, v89, v118
	v_add_u32_e32 v107, 0xf000, v107
	s_waitcnt lgkmcnt(0)
	v_mfma_f32_16x16x32_bf16 v[128:131], v[32:35], v[150:153], v[128:131]
	ds_read2_b64 v[150:153], v107 offset0:128 offset1:132
	s_waitcnt lgkmcnt(0)
	v_mfma_f32_16x16x32_bf16 v[128:131], v[52:55], v[150:153], v[128:131]
	ds_read2_b64 v[150:153], v107 offset0:136 offset1:140
	v_add_u32_e32 v107, 0x6000, v85
	s_waitcnt lgkmcnt(0)
	v_mfma_f32_16x16x32_bf16 v[128:131], v[48:51], v[150:153], v[128:131]
	ds_read2_b64 v[150:153], v107 offset0:200 offset1:204
	s_nop 6
	v_cvt_pk_bf16_f32 v128, v128, v129
	v_cvt_pk_bf16_f32 v129, v130, v131
	v_or_b32_e32 v130, 16, v106
	v_ashrrev_i32_e32 v131, 31, v130
	v_lshlrev_b64 v[130:131], 11, v[130:131]
	v_lshl_add_u64 v[130:131], v[70:71], 0, v[130:131]
	global_store_dwordx2 v[130:131], v[128:129], off
	ds_read2_b64 v[128:131], v107 offset0:192 offset1:196
	s_waitcnt lgkmcnt(0)
	v_mfma_f32_16x16x32_bf16 v[128:131], v[40:43], v[128:131], 0
	v_mfma_f32_16x16x32_bf16 v[128:131], v[44:47], v[150:153], v[128:131]
	ds_read2_b64 v[150:153], v107 offset0:208 offset1:212
	s_waitcnt lgkmcnt(0)
	v_mfma_f32_16x16x32_bf16 v[128:131], v[36:39], v[150:153], v[128:131]
	ds_read2_b64 v[150:153], v107 offset0:216 offset1:220
	v_add_u32_e32 v107, 0xf000, v124
	s_waitcnt lgkmcnt(0)
	v_mfma_f32_16x16x32_bf16 v[128:131], v[32:35], v[150:153], v[128:131]
	ds_read2_b64 v[150:153], v107 offset0:128 offset1:132
	s_waitcnt lgkmcnt(0)
	v_mfma_f32_16x16x32_bf16 v[128:131], v[52:55], v[150:153], v[128:131]
	ds_read2_b64 v[150:153], v107 offset0:136 offset1:140
	v_add_u32_e32 v107, 0x7000, v85
	s_waitcnt lgkmcnt(0)
	v_mfma_f32_16x16x32_bf16 v[128:131], v[48:51], v[150:153], v[128:131]
	s_nop 7
	v_cvt_pk_bf16_f32 v128, v128, v129
	v_cvt_pk_bf16_f32 v129, v130, v131
	v_or_b32_e32 v130, 32, v106
	v_ashrrev_i32_e32 v131, 31, v130
	v_lshlrev_b64 v[130:131], 11, v[130:131]
	v_lshl_add_u64 v[130:131], v[70:71], 0, v[130:131]
	global_store_dwordx2 v[130:131], v[128:129], off
	ds_read2_b64 v[128:131], v107 offset0:224 offset1:228
	s_waitcnt lgkmcnt(0)
	v_mfma_f32_16x16x32_bf16 v[40:43], v[40:43], v[128:131], 0
	ds_read2_b64 v[128:131], v107 offset0:232 offset1:236
	s_waitcnt lgkmcnt(0)
	v_mfma_f32_16x16x32_bf16 v[40:43], v[44:47], v[128:131], v[40:43]
	ds_read2_b64 v[44:47], v107 offset0:240 offset1:244
	s_waitcnt lgkmcnt(0)
	v_mfma_f32_16x16x32_bf16 v[36:39], v[36:39], v[44:47], v[40:43]
	s_nop 4
	ds_read2_b64 v[40:43], v107 offset0:248 offset1:252
	s_waitcnt lgkmcnt(0)
	v_mfma_f32_16x16x32_bf16 v[32:35], v[32:35], v[40:43], v[36:39]
	v_add_u32_e32 v40, 0xf000, v125
	s_nop 1
	ds_read2_b64 v[36:39], v40 offset0:128 offset1:132
	s_waitcnt lgkmcnt(0)
	v_mfma_f32_16x16x32_bf16 v[32:35], v[52:55], v[36:39], v[32:35]
	ds_read2_b64 v[36:39], v40 offset0:136 offset1:140
	s_waitcnt lgkmcnt(0)
	v_mfma_f32_16x16x32_bf16 v[32:35], v[48:51], v[36:39], v[32:35]
	s_nop 7
	v_cvt_pk_bf16_f32 v32, v32, v33
	v_cvt_pk_bf16_f32 v33, v34, v35
	v_or_b32_e32 v34, 48, v106
	v_ashrrev_i32_e32 v35, 31, v34
	v_lshlrev_b64 v[34:35], 11, v[34:35]
	v_lshl_add_u64 v[34:35], v[70:71], 0, v[34:35]
	global_store_dwordx2 v[34:35], v[32:33], off
	v_mov_b32_e32 v32, s52
	ds_read_b32 v32, v32
	s_waitcnt lgkmcnt(0)
; DEVI float bflo(unsigned u) { return __uint_as_float(u << 16); }
; template <bool GDN>
; DEVI void scan_chain(int sw, const P& p, int item, char* smraw) {
;     ...
;   for (int n = 0; n < NCH; ++n) {
;     const int mc = dir == 0 ? n : (n < 4 ? 3 - n : 71 - n);
;     const int p0 = mc * 64;
;     const int itc = bhd * NCH + mc;
;     __syncthreads();
;     if (GDN) {
;       if (tid < 64) {
;         const float* gc = (const float*)(R2 + R_GC) + (size_t)bhd * TPB + p0;
;         float gcv = gc[tid], gl = gc[dir ? 0 : 63];
;         f_e[tid] = __expf(gcv);
;         f_b[tid] = ((const float*)(R2 + R_BETA))[(size_t)bhd * TPB + p0 + tid];
;         f_k[tid] = __expf(gl - gcv);
;         if (tid == 0) f_last[0] = __expf(gl);
;       }
;     } else {
;       if (tid < 128) el[tid] = ((const float*)(R2 + R1_EL))[(size_t)itc * 128 + tid];
;     }
;     __syncthreads();
;     if (GDN) {
;       const bf16_t* gq = (const bf16_t*)(R2 + R_GQ) + ((size_t)bh * TPB + p0) * 128;
;       const bf16_t* gk = (const bf16_t*)(R2 + R_GK) + ((size_t)bh * TPB + p0) * 128;
;       const bf16_t* gkt = (const bf16_t*)(R2 + R_GKT) + ((size_t)bh * 128) * TPS + p0;
;       const bf16_t* tm = (const bf16_t*)(R2 + R_TM) + (size_t)itc * 4096;
;       const bf16_t* qkm = (const bf16_t*)(R2 + R_QKM) + (size_t)itc * 4096;
; #pragma unroll
;       for (int i = 0; i < 4; ++i) {
;         int c = tid + 256 * i, row = c >> 4, kc = c & 15;
;         u32x4 uq = *(const u32x4*)(gq + row * 128 + kc * 8), uk = *(const u32x4*)(gk + row * 128 + kc * 8);
;         float fe = f_e[row], fk = f_b[row] * fe;
;         u32x4 oq, ok;
; #pragma unroll
;         for (int j = 0; j < 4; ++j) { oq[j] = pk2(bflo(uq[j]) * fe, bfhi(uq[j]) * fe); ok[j] = pk2(bflo(uk[j]) * fk, bfhi(uk[j]) * fk); }
;         *(u32x4*)(qd + row * 136 + kc * 8) = oq;
;         *(u32x4*)(kbg + row * 136 + kc * 8) = ok;
;       }
; #pragma unroll
;       for (int i = 0; i < 4; ++i) {
;         int c = tid + 256 * i, row = c >> 3, cc = c & 7;
;         u32x4 u = *(const u32x4*)(gkt + (size_t)row * TPS + cc * 8), o;
; #pragma unroll
;     ...
; #pragma unroll
;     for (int dt = 0; dt < 8; ++dt) {
;       if (GDN) S[dt] *= f_last[0];
;       else S[dt] *= *(const f32x4*)(el + dt * 16 + fq * 4);
; #pragma unroll
;       for (int kk = 0; kk < 2; ++kk) S[dt] = mfma16(ldsperm(kend, dt * 16 + fr, 72, kk, fq), vop[kk], S[dt]);
;     }
	v_pk_mul_f32 v[6:7], v[6:7], v[32:33] op_sel_hi:[1,0]
	v_pk_mul_f32 v[4:5], v[4:5], v[32:33] op_sel_hi:[1,0]
	v_add_u32_e32 v33, 0x8800, v121
	ds_read2_b64 v[34:37], v33 offset1:4
	s_waitcnt lgkmcnt(0)
	v_mfma_f32_16x16x32_bf16 v[4:7], v[34:37], v[52:55], v[4:7]
	ds_read2_b64 v[34:37], v33 offset0:8 offset1:12
	v_pk_mul_f32 v[2:3], v[2:3], v[32:33] op_sel_hi:[1,0]
	v_pk_mul_f32 v[0:1], v[0:1], v[32:33] op_sel_hi:[1,0]
	v_add_u32_e32 v33, 0x9000, v121
	s_waitcnt lgkmcnt(0)
	v_mfma_f32_16x16x32_bf16 v[4:7], v[34:37], v[48:51], v[4:7]
	ds_read2_b64 v[34:37], v33 offset0:32 offset1:36
	v_pk_mul_f32 v[10:11], v[10:11], v[32:33] op_sel_hi:[1,0]
	v_pk_mul_f32 v[8:9], v[8:9], v[32:33] op_sel_hi:[1,0]
	s_waitcnt lgkmcnt(0)
	v_mfma_f32_16x16x32_bf16 v[0:3], v[34:37], v[52:55], v[0:3]
	ds_read2_b64 v[34:37], v33 offset0:40 offset1:44
	v_add_u32_e32 v33, 0x9800, v121
	v_pk_mul_f32 v[14:15], v[14:15], v[32:33] op_sel_hi:[1,0]
	s_waitcnt lgkmcnt(0)
	v_mfma_f32_16x16x32_bf16 v[0:3], v[34:37], v[48:51], v[0:3]
	ds_read2_b64 v[34:37], v33 offset0:64 offset1:68
	v_pk_mul_f32 v[12:13], v[12:13], v[32:33] op_sel_hi:[1,0]
	s_waitcnt lgkmcnt(0)
	v_mfma_f32_16x16x32_bf16 v[8:11], v[34:37], v[52:55], v[8:11]
	ds_read2_b64 v[34:37], v33 offset0:72 offset1:76
	v_add_u32_e32 v33, v85, v120
	v_add_u32_e32 v33, 0xb800, v33
	s_waitcnt lgkmcnt(0)
	v_mfma_f32_16x16x32_bf16 v[8:11], v[34:37], v[48:51], v[8:11]
	ds_read2_b64 v[34:37], v33 offset0:96 offset1:100
	v_pk_mul_f32 v[18:19], v[18:19], v[32:33] op_sel_hi:[1,0]
	v_pk_mul_f32 v[16:17], v[16:17], v[32:33] op_sel_hi:[1,0]
	s_waitcnt lgkmcnt(0)
	v_mfma_f32_16x16x32_bf16 v[12:15], v[34:37], v[52:55], v[12:15]
	ds_read2_b64 v[34:37], v33 offset0:104 offset1:108
	v_add_u32_e32 v33, 0xa800, v121
	v_pk_mul_f32 v[22:23], v[22:23], v[32:33] op_sel_hi:[1,0]
	s_waitcnt lgkmcnt(0)
	v_mfma_f32_16x16x32_bf16 v[12:15], v[34:37], v[48:51], v[12:15]
	ds_read2_b64 v[34:37], v33 offset0:128 offset1:132
	v_pk_mul_f32 v[20:21], v[20:21], v[32:33] op_sel_hi:[1,0]
	s_waitcnt lgkmcnt(0)
	v_mfma_f32_16x16x32_bf16 v[16:19], v[34:37], v[52:55], v[16:19]
	ds_read2_b64 v[34:37], v33 offset0:136 offset1:140
	v_add_u32_e32 v33, 0xb000, v121
	v_pk_mul_f32 v[30:31], v[30:31], v[32:33] op_sel_hi:[1,0]
	s_waitcnt lgkmcnt(0)
	v_mfma_f32_16x16x32_bf16 v[16:19], v[34:37], v[48:51], v[16:19]
	ds_read2_b64 v[34:37], v33 offset0:160 offset1:164
	v_pk_mul_f32 v[28:29], v[28:29], v[32:33] op_sel_hi:[1,0]
	s_waitcnt lgkmcnt(0)
	v_mfma_f32_16x16x32_bf16 v[20:23], v[34:37], v[52:55], v[20:23]
	ds_read2_b64 v[34:37], v33 offset0:168 offset1:172
	v_add_u32_e32 v33, 0xb800, v121
	v_pk_mul_f32 v[26:27], v[26:27], v[32:33] op_sel_hi:[1,0]
	s_waitcnt lgkmcnt(0)
	v_mfma_f32_16x16x32_bf16 v[20:23], v[34:37], v[48:51], v[20:23]
	ds_read2_b64 v[34:37], v33 offset0:192 offset1:196
	v_pk_mul_f32 v[24:25], v[24:25], v[32:33] op_sel_hi:[1,0]
	s_waitcnt lgkmcnt(0)
	v_mfma_f32_16x16x32_bf16 v[28:31], v[34:37], v[52:55], v[28:31]
	ds_read2_b64 v[34:37], v33 offset0:200 offset1:204
	s_waitcnt lgkmcnt(0)
	v_mfma_f32_16x16x32_bf16 v[28:31], v[34:37], v[48:51], v[28:31]
	v_add_u32_e32 v36, 0xc000, v121
	ds_read2_b64 v[32:35], v36 offset0:224 offset1:228
	s_waitcnt lgkmcnt(0)
	v_mfma_f32_16x16x32_bf16 v[24:27], v[32:35], v[52:55], v[24:27]
	ds_read2_b64 v[32:35], v36 offset0:232 offset1:236
	s_waitcnt lgkmcnt(0)
	v_mfma_f32_16x16x32_bf16 v[24:27], v[32:35], v[48:51], v[24:27]
	s_cbranch_scc1 .LBB0_540
.LBB0_569:
	s_cmp_gt_u32 s72, 3
	s_cselect_b32 s46, 0x47, 3
	s_add_i32 s54, s46, s4
	s_and_b64 s[46:47], s[44:45], exec
	s_cselect_b32 s58, s72, s54
	s_lshl_b32 s46, s58, 6
	s_ashr_i32 s47, s46, 31
	s_add_u32 s98, s83, s46
	s_addc_u32 s99, s82, s47
	s_lshl_b64 s[98:99], s[98:99], 8
	v_lshl_add_u64 v[162:163], v[58:59], 0, s[98:99]
	v_lshl_add_u64 v[164:165], v[60:61], 0, s[98:99]
	v_lshl_add_u64 v[166:167], v[162:163], 0, v[94:95]
	global_load_dwordx4 v[170:173], v[166:167], off
	v_lshl_add_u64 v[168:169], v[164:165], 0, v[94:95]
	global_load_dwordx4 v[174:177], v[168:169], off
	v_lshl_add_u64 v[166:167], v[162:163], 0, v[96:97]
	global_load_dwordx4 v[178:181], v[166:167], off
	v_lshl_add_u64 v[168:169], v[164:165], 0, v[96:97]
	global_load_dwordx4 v[182:185], v[168:169], off
	v_lshl_add_u64 v[166:167], v[162:163], 0, v[98:99]
	global_load_dwordx4 v[186:189], v[166:167], off
	v_lshl_add_u64 v[168:169], v[164:165], 0, v[98:99]
	global_load_dwordx4 v[190:193], v[168:169], off
	v_lshl_add_u64 v[166:167], v[162:163], 0, v[100:101]
	global_load_dwordx4 v[194:197], v[166:167], off
	v_lshl_add_u64 v[168:169], v[164:165], 0, v[100:101]
	global_load_dwordx4 v[198:201], v[168:169], off
	s_lshl_b64 s[98:99], s[46:47], 1
	v_lshl_add_u64 v[162:163], v[62:63], 0, s[98:99]
	v_lshl_add_u64 v[166:167], v[162:163], 0, v[82:83]
	global_load_dwordx4 v[202:205], v[166:167], off
	v_lshl_add_u64 v[168:169], v[162:163], 0, v[86:87]
	global_load_dwordx4 v[206:209], v[168:169], off
	v_lshl_add_u64 v[166:167], v[162:163], 0, v[90:91]
	global_load_dwordx4 v[210:213], v[166:167], off
	v_lshl_add_u64 v[168:169], v[162:163], 0, v[92:93]
	global_load_dwordx4 v[214:217], v[168:169], off
	v_lshl_add_u64 v[244:245], v[68:69], 0, s[98:99]
	s_add_i32 s98, s58, s81
	s_ashr_i32 s99, s98, 31
	s_lshl_b64 s[98:99], s[98:99], 13
	v_lshl_add_u64 v[162:163], v[64:65], 0, s[98:99]
	v_lshl_add_u64 v[164:165], v[66:67], 0, s[98:99]
	v_lshl_add_u64 v[166:167], v[162:163], 0, v[102:103]
	global_load_dwordx4 v[220:223], v[166:167], off
	v_lshl_add_u64 v[168:169], v[164:165], 0, v[102:103]
	global_load_dwordx4 v[224:227], v[168:169], off
	v_lshl_add_u64 v[166:167], v[162:163], 0, v[104:105]
	global_load_dwordx4 v[228:231], v[166:167], off
	v_lshl_add_u64 v[168:169], v[164:165], 0, v[104:105]
	global_load_dwordx4 v[232:235], v[168:169], off
	global_load_dwordx2 v[236:237], v[244:245], off
	global_load_dwordx2 v[238:239], v[244:245], off offset:32
	global_load_dwordx2 v[240:241], v[244:245], off offset:64
	global_load_dwordx2 v[242:243], v[244:245], off offset:96
	s_barrier
	s_and_saveexec_b64 s[56:57], vcc
	s_cbranch_execz .LBB0_568
	s_lshl_b64 s[64:65], s[46:47], 2
	s_add_u32 s54, s6, s64
	s_addc_u32 s55, s7, s65
	v_lshl_add_u64 v[32:33], v[56:57], 2, s[54:55]
	v_mov_b32_e32 v34, s92
	global_load_dword v33, v[32:33], off
	s_nop 0
	global_load_dword v32, v34, s[54:55]
	v_lshl_add_u64 v[34:35], v[72:73], 0, s[64:65]
	global_load_dword v34, v[34:35], off
	s_waitcnt vmcnt(2)
	v_mul_f32_e32 v35, 0x3fb8aa3b, v33
	s_waitcnt vmcnt(1)
	v_sub_f32_e32 v33, v32, v33
	v_exp_f32_e32 v35, v35
	v_mul_f32_e32 v33, 0x3fb8aa3b, v33
	v_exp_f32_e32 v33, v33
	ds_write_b32 v110, v35
	s_waitcnt vmcnt(0)
	ds_write_b32 v111, v34
	ds_write_b32 v112, v33
	s_and_b64 exec, exec, s[2:3]
	s_cbranch_execz .LBB0_568
	v_mul_f32_e32 v32, 0x3fb8aa3b, v32
	v_exp_f32_e32 v32, v32
	v_mov_b32_e32 v33, s52
	ds_write_b32 v33, v32
	s_branch .LBB0_568

; template <int MODE, class Epi>
; DEVI void gemm256_phase(int sw, const bf16_t* __restrict__ W, int ldw, const bf16_t* __restrict__ X, int ldx, int K, int nN, char* shm, const Epi& epi) {
;     ...
;   auto stage = [&](int buf, int n0, int m0, int kt) {
;     const char* wk = (const char*)(W + (size_t)n0 * ldw) + kt * 128;
;     const char* xk = (const char*)(X + (size_t)m0 * ldx) + kt * 128;
; #pragma unroll
;     for (int i = 0; i < 4; ++i) {
;       unsigned ow = offW[i], ox = offX[i];
;       asm volatile("" : "+v"(ow), "+v"(ox));
;       __builtin_amdgcn_global_load_lds((const unsigned*)(wk + ow), (unsigned*)(shm + buf * STAGE_B + wid * 1024 + i * 8192), 16, 0, 0);
;       __builtin_amdgcn_global_load_lds((const unsigned*)(xk + ox), (unsigned*)(shm + buf * STAGE_B + TILE_B + wid * 1024 + i * 8192), 16, 0, 0);
;     }
;   };
;     ...
;     for (int t = 0; t < ntk; ++t) {
;       const int cur = (b0 + t) & 1;
;       const bool st_own = t + 1 < ntk, st_next = !st_own && has_next;
;       if (wid < 4) {
;         if (st_own) stage(cur ^ 1, n0, m0, kt0 + t + 1);
;         else if (st_next) stage(cur ^ 1, n1, m1, kt1);
;       }
.LBB0_704:
	s_add_i32 s0, s61, s82
	s_and_b32 s83, s0, 1
	s_add_i32 s82, s82, 1
	s_cmp_lt_i32 s82, s54
	s_cselect_b64 s[0:1], -1, 0
	s_cmp_ge_i32 s82, s54
	s_cselect_b64 s[40:41], -1, 0
	v_cmp_ne_u32_e32 vcc, 1, v197
	v_cndmask_b32_e64 v128, 0, 1, s[0:1]
	s_and_b64 s[40:41], s[38:39], s[40:41]
	v_cmp_ne_u32_e64 s[0:1], 1, v128
	s_branch .LBB0_713
	s_and_b64 vcc, exec, s[0:1]
	s_cbranch_vccnz .LBB0_707
	s_ashr_i32 s44, s81, 31
	s_add_u32 s46, s78, s81
	s_addc_u32 s47, s79, s44
	s_add_u32 s42, s46, 0x80
	s_addc_u32 s43, s47, 0
	s_add_u32 s52, s76, s81
	s_addc_u32 s53, s77, s44
	s_add_u32 s44, s52, 0x80
	s_addc_u32 s45, s53, 0
	s_lshl_b32 s88, s83, 16
	s_xor_b32 s88, s88, 0x10000
	v_mov_b32_e32 v188, v190
	v_mov_b32_e32 v128, v190
	s_add_i32 s88, s57, s88
	v_lshl_add_u64 v[130:131], s[46:47], 0, v[188:189]
	v_mov_b32_e32 v129, v189
	v_lshl_add_u64 v[130:131], v[130:131], 0, s[10:11]
	s_mov_b32 m0, s88
	v_lshl_add_u64 v[128:129], s[52:53], 0, v[128:129]
	global_load_lds_dwordx4 v[130:131], off
	v_lshl_add_u64 v[128:129], v[128:129], 0, s[10:11]
	s_add_i32 m0, s88, 0x8000
	v_mov_b32_e32 v188, v191
	global_load_lds_dwordx4 v[128:129], off
	v_mov_b32_e32 v128, v191
	v_mov_b32_e32 v129, v189
	v_lshl_add_u64 v[130:131], s[46:47], 0, v[188:189]
	v_lshl_add_u64 v[130:131], v[130:131], 0, s[10:11]
	s_add_i32 m0, s88, 0x2000
	v_lshl_add_u64 v[128:129], s[52:53], 0, v[128:129]
	global_load_lds_dwordx4 v[130:131], off
	v_lshl_add_u64 v[128:129], v[128:129], 0, s[10:11]
	s_add_i32 m0, s88, 0xa000
	v_mov_b32_e32 v188, v192
	global_load_lds_dwordx4 v[128:129], off
	v_mov_b32_e32 v128, v192
	v_mov_b32_e32 v129, v189
	v_lshl_add_u64 v[130:131], s[46:47], 0, v[188:189]
	v_lshl_add_u64 v[130:131], v[130:131], 0, s[10:11]
	s_add_i32 m0, s88, 0x4000
	v_lshl_add_u64 v[128:129], s[52:53], 0, v[128:129]
	global_load_lds_dwordx4 v[130:131], off
	v_lshl_add_u64 v[128:129], v[128:129], 0, s[10:11]
	s_add_i32 m0, s88, 0xc000
	s_nop 0
	global_load_lds_dwordx4 v[128:129], off
	v_mov_b32_e32 v128, v193
	v_mov_b32_e32 v129, v193
	s_mov_b64 s[46:47], -1
	s_cbranch_execz .LBB0_708
	s_branch .LBB0_711

; DEVI f32x4 mfma16(bf16x8 a, bf16x8 b, f32x4 c) { return __builtin_amdgcn_mfma_f32_16x16x32_bf16(a, b, c, 0, 0, 0); }
; template <int MODE, class Epi>
; DEVI void gemm256_phase(int sw, const bf16_t* __restrict__ W, int ldw, const bf16_t* __restrict__ X, int ldx, int K, int nN, char* shm, const Epi& epi) {
;     ...
;       const char* SAp = shm + cur * STAGE_B + wr * (16 * 1024) + lds_lo;
;       const char* SBp = shm + cur * STAGE_B + TILE_B + wc * (8 * 1024) + lds_lo;
; #pragma unroll
;       for (int ks = 0; ks < 2; ++ks) {
;         const int kx = (wid >> 2) ? (1 - 2 * ks) * 1024 : 0;
;         bf16x8 At[8], Bf[4];
; #pragma unroll
;         for (int m = 0; m < 8; ++m) At[m] = *(const bf16x8*)(SAp + (2 * m + ks) * 1024 + kx);
; #pragma unroll
;         for (int n = 0; n < 4; ++n) Bf[n] = *(const bf16x8*)(SBp + (2 * n + ks) * 1024 + kx);
; #pragma unroll
;         for (int m = 0; m < 8; ++m)
; #pragma unroll
;           for (int n = 0; n < 4; ++n) acc[m][n] = mfma16(At[m], Bf[n], acc[m][n]);
;         __builtin_amdgcn_sched_barrier(0);
;         if (ks == 0 && wid >= 4) {
;           if (st_own) stage(cur ^ 1, n0, m0, kt0 + t + 1);
;           else if (st_next) stage(cur ^ 1, n1, m1, kt1);
;         }
.LBB0_713:
	s_lshl_b32 s42, s83, 16
	s_add_i32 s43, s42, s58
	v_add_u32_e32 v129, s43, v194
	v_add_u32_e32 v150, s62, v129
	ds_read_b128 v[220:223], v150
	s_or_b32 s43, s42, s59
	v_add_u32_e32 v128, s43, v194
	v_add_u32_e32 v146, s62, v128
	ds_read_b128 v[134:137], v146 offset:32768
	ds_read_b128 v[138:141], v146 offset:34816
	ds_read_b128 v[142:145], v146 offset:36864
	ds_read_b128 v[146:149], v146 offset:38912
	ds_read_b128 v[224:227], v150 offset:2048
	ds_read_b128 v[228:231], v150 offset:4096
	ds_read_b128 v[232:235], v150 offset:6144
	s_add_u32 s98, s78, s81
	s_addc_u32 s99, s79, 0
	s_add_u32 s98, s98, 0x80
	s_addc_u32 s99, s99, 0
	s_add_u32 s100, s76, s81
	s_addc_u32 s101, s77, 0
	s_add_u32 s100, s100, 0x80
	s_addc_u32 s101, s101, 0
	s_xor_b32 m0, s42, 0x10000
	s_add_i32 m0, m0, s57
	s_waitcnt lgkmcnt(3)
	v_mfma_f32_16x16x32_bf16 v[124:127], v[220:223], v[134:137], v[124:127]
	v_mfma_f32_16x16x32_bf16 v[120:123], v[220:223], v[138:141], v[120:123]
	v_mfma_f32_16x16x32_bf16 v[116:119], v[220:223], v[142:145], v[116:119]
	v_mfma_f32_16x16x32_bf16 v[112:115], v[220:223], v[146:149], v[112:115]
	global_load_lds_dwordx4 v190, s[98:99]
	ds_read_b128 v[236:239], v150 offset:8192
	s_add_i32 m0, m0, 0x8000
	s_waitcnt lgkmcnt(3)
	v_mfma_f32_16x16x32_bf16 v[108:111], v[224:227], v[134:137], v[108:111]
	v_mfma_f32_16x16x32_bf16 v[104:107], v[224:227], v[138:141], v[104:107]
	v_mfma_f32_16x16x32_bf16 v[100:103], v[224:227], v[142:145], v[100:103]
	v_mfma_f32_16x16x32_bf16 v[96:99], v[224:227], v[146:149], v[96:99]
	global_load_lds_dwordx4 v190, s[100:101]
	ds_read_b128 v[240:243], v150 offset:10240
	s_add_i32 m0, m0, 0xffffa000
	s_waitcnt lgkmcnt(3)
	v_mfma_f32_16x16x32_bf16 v[92:95], v[228:231], v[134:137], v[92:95]
	v_mfma_f32_16x16x32_bf16 v[88:91], v[228:231], v[138:141], v[88:91]
	v_mfma_f32_16x16x32_bf16 v[84:87], v[228:231], v[142:145], v[84:87]
	v_mfma_f32_16x16x32_bf16 v[80:83], v[228:231], v[146:149], v[80:83]
	global_load_lds_dwordx4 v191, s[98:99]
	ds_read_b128 v[244:247], v150 offset:12288
	s_add_i32 m0, m0, 0x8000
	s_waitcnt lgkmcnt(3)
	v_mfma_f32_16x16x32_bf16 v[76:79], v[232:235], v[134:137], v[76:79]
	v_mfma_f32_16x16x32_bf16 v[72:75], v[232:235], v[138:141], v[72:75]
	v_mfma_f32_16x16x32_bf16 v[68:71], v[232:235], v[142:145], v[68:71]
	v_mfma_f32_16x16x32_bf16 v[64:67], v[232:235], v[146:149], v[64:67]
	global_load_lds_dwordx4 v191, s[100:101]
	ds_read_b128 v[248:251], v150 offset:14336
	s_add_i32 m0, m0, 0xffffa000
	s_waitcnt lgkmcnt(3)
	v_mfma_f32_16x16x32_bf16 v[60:63], v[236:239], v[134:137], v[60:63]
	v_mfma_f32_16x16x32_bf16 v[56:59], v[236:239], v[138:141], v[56:59]
	v_mfma_f32_16x16x32_bf16 v[52:55], v[236:239], v[142:145], v[52:55]
	v_mfma_f32_16x16x32_bf16 v[48:51], v[236:239], v[146:149], v[48:51]
	global_load_lds_dwordx4 v192, s[98:99]
	s_add_i32 m0, m0, 0x8000
	s_waitcnt lgkmcnt(2)
	v_mfma_f32_16x16x32_bf16 v[44:47], v[240:243], v[134:137], v[44:47]
	v_mfma_f32_16x16x32_bf16 v[40:43], v[240:243], v[138:141], v[40:43]
	v_mfma_f32_16x16x32_bf16 v[36:39], v[240:243], v[142:145], v[36:39]
	v_mfma_f32_16x16x32_bf16 v[32:35], v[240:243], v[146:149], v[32:35]
	global_load_lds_dwordx4 v192, s[100:101]
	s_add_i32 m0, m0, 0xffffa000
	s_waitcnt lgkmcnt(1)
	v_mfma_f32_16x16x32_bf16 v[28:31], v[244:247], v[134:137], v[28:31]
	v_mfma_f32_16x16x32_bf16 v[24:27], v[244:247], v[138:141], v[24:27]
	v_mfma_f32_16x16x32_bf16 v[20:23], v[244:247], v[142:145], v[20:23]
	v_mfma_f32_16x16x32_bf16 v[16:19], v[244:247], v[146:149], v[16:19]
	global_load_lds_dwordx4 v193, s[98:99]
	s_add_i32 m0, m0, 0x8000
	s_waitcnt lgkmcnt(0)
	v_mfma_f32_16x16x32_bf16 v[12:15], v[248:251], v[134:137], v[12:15]
	v_mfma_f32_16x16x32_bf16 v[8:11], v[248:251], v[138:141], v[8:11]
	v_mfma_f32_16x16x32_bf16 v[4:7], v[248:251], v[142:145], v[4:7]
	v_mfma_f32_16x16x32_bf16 v[0:3], v[248:251], v[146:149], v[0:3]
	global_load_lds_dwordx4 v193, s[100:101]
	s_andn2_b64 vcc, exec, s[8:9]
	s_branch .LBB0_703
	s_and_b64 vcc, exec, s[0:1]
	s_xor_b32 s52, s42, 0x10000
	s_cbranch_vccnz .LBB0_716
	s_ashr_i32 s42, s81, 31
	s_add_u32 s44, s78, s81
	s_addc_u32 s45, s79, s42
	s_add_u32 s0, s44, 0x80
	s_addc_u32 s1, s45, 0
	s_add_u32 s46, s76, s81
	s_addc_u32 s47, s77, s42
	s_add_u32 s42, s46, 0x80
	v_mov_b32_e32 v188, v190
	v_mov_b32_e32 v130, v190
	s_addc_u32 s43, s47, 0
	s_add_i32 s53, s57, s52
	v_lshl_add_u64 v[132:133], s[44:45], 0, v[188:189]
	v_mov_b32_e32 v131, v189
	v_lshl_add_u64 v[132:133], v[132:133], 0, s[10:11]
	s_mov_b32 m0, s53
	v_lshl_add_u64 v[130:131], s[46:47], 0, v[130:131]
	global_load_lds_dwordx4 v[132:133], off
	v_lshl_add_u64 v[130:131], v[130:131], 0, s[10:11]
	s_add_i32 m0, s53, 0x8000
	v_mov_b32_e32 v188, v191
	global_load_lds_dwordx4 v[130:131], off
	v_mov_b32_e32 v130, v191
	v_mov_b32_e32 v131, v189
	v_lshl_add_u64 v[132:133], s[44:45], 0, v[188:189]
	v_lshl_add_u64 v[132:133], v[132:133], 0, s[10:11]
	s_add_i32 m0, s53, 0x2000
	v_lshl_add_u64 v[130:131], s[46:47], 0, v[130:131]
	global_load_lds_dwordx4 v[132:133], off
	v_lshl_add_u64 v[130:131], v[130:131], 0, s[10:11]
	s_add_i32 m0, s53, 0xa000
	v_mov_b32_e32 v188, v192
	global_load_lds_dwordx4 v[130:131], off
	v_mov_b32_e32 v130, v192
	v_mov_b32_e32 v131, v189
	v_lshl_add_u64 v[132:133], s[44:45], 0, v[188:189]
	v_lshl_add_u64 v[132:133], v[132:133], 0, s[10:11]
	s_add_i32 m0, s53, 0x4000
	v_lshl_add_u64 v[130:131], s[46:47], 0, v[130:131]
	global_load_lds_dwordx4 v[132:133], off
	v_lshl_add_u64 v[130:131], v[130:131], 0, s[10:11]
	s_add_i32 m0, s53, 0xc000
	s_nop 0
	global_load_lds_dwordx4 v[130:131], off
	v_mov_b32_e32 v130, v193
	v_mov_b32_e32 v131, v193
	s_mov_b64 s[44:45], -1
	s_cbranch_execz .LBB0_717
	s_branch .LBB0_720

; template <int MODE, class Epi>
; DEVI void gemm256_phase(int sw, const bf16_t* __restrict__ W, int ldw, const bf16_t* __restrict__ X, int ldx, int K, int nN, char* shm, const Epi& epi) {
;     ...
;   auto stage = [&](int buf, int n0, int m0, int kt) {
;     const char* wk = (const char*)(W + (size_t)n0 * ldw) + kt * 128;
;     const char* xk = (const char*)(X + (size_t)m0 * ldx) + kt * 128;
; #pragma unroll
;     for (int i = 0; i < 4; ++i) {
;       unsigned ow = offW[i], ox = offX[i];
;       asm volatile("" : "+v"(ow), "+v"(ox));
;       __builtin_amdgcn_global_load_lds((const unsigned*)(wk + ow), (unsigned*)(shm + buf * STAGE_B + wid * 1024 + i * 8192), 16, 0, 0);
;       __builtin_amdgcn_global_load_lds((const unsigned*)(xk + ox), (unsigned*)(shm + buf * STAGE_B + TILE_B + wid * 1024 + i * 8192), 16, 0, 0);
;     }
;   };
;     ...
;     for (int t = 0; t < ntk; ++t) {
;       const int cur = (b0 + t) & 1;
;       const bool st_own = t + 1 < ntk, st_next = !st_own && has_next;
;       if (wid < 4) {
;         if (st_own) stage(cur ^ 1, n0, m0, kt0 + t + 1);
;         else if (st_next) stage(cur ^ 1, n1, m1, kt1);
;       }
.LBB0_985:
	s_add_i32 s10, s37, s58
	s_and_b32 s60, s10, 1
	s_mov_b64 s[10:11], -1
	s_and_b64 vcc, exec, s[4:5]
	s_branch .LBB0_987
	s_ashr_i32 s59, s57, 31
	s_add_u32 s10, s12, s57
	s_addc_u32 s11, s13, s59
	s_add_u32 s62, s55, s57
	s_addc_u32 s63, s56, s59
	s_lshl_b32 s59, s60, 16
	s_xor_b32 s61, s59, 0x10000
	v_mov_b32_e32 v128, v194
	v_mov_b32_e32 v192, v194
	s_add_i32 s61, s14, s61
	v_lshl_add_u64 v[130:131], s[10:11], 0, v[192:193]
	v_mov_b32_e32 v129, v193
	v_lshl_add_u64 v[130:131], v[130:131], 0, s[6:7]
	s_mov_b32 m0, s61
	v_lshl_add_u64 v[128:129], s[62:63], 0, v[128:129]
	global_load_lds_dwordx4 v[130:131], off
	v_lshl_add_u64 v[128:129], v[128:129], 0, s[6:7]
	s_add_i32 m0, s61, 0x8000
	v_mov_b32_e32 v192, v195
	global_load_lds_dwordx4 v[128:129], off
	v_mov_b32_e32 v128, v195
	v_mov_b32_e32 v129, v193
	v_lshl_add_u64 v[130:131], s[10:11], 0, v[192:193]
	v_lshl_add_u64 v[130:131], v[130:131], 0, s[6:7]
	s_add_i32 m0, s61, 0x2000
	v_lshl_add_u64 v[128:129], s[62:63], 0, v[128:129]
	global_load_lds_dwordx4 v[130:131], off
	v_lshl_add_u64 v[128:129], v[128:129], 0, s[6:7]
	s_add_i32 m0, s61, 0xa000
	v_mov_b32_e32 v192, v196
	global_load_lds_dwordx4 v[128:129], off
	v_mov_b32_e32 v128, v196
	v_mov_b32_e32 v129, v193
	v_lshl_add_u64 v[130:131], s[10:11], 0, v[192:193]
	v_lshl_add_u64 v[130:131], v[130:131], 0, s[6:7]
	s_add_i32 m0, s61, 0x4000
	v_lshl_add_u64 v[128:129], s[62:63], 0, v[128:129]
	global_load_lds_dwordx4 v[130:131], off
	v_lshl_add_u64 v[128:129], v[128:129], 0, s[6:7]
	s_add_i32 m0, s61, 0xc000
	v_mov_b32_e32 v192, v197
	global_load_lds_dwordx4 v[128:129], off
	v_mov_b32_e32 v128, v197
	v_mov_b32_e32 v129, v193
	v_lshl_add_u64 v[130:131], s[10:11], 0, v[192:193]
	v_lshl_add_u64 v[130:131], v[130:131], 0, s[6:7]
	s_add_i32 m0, s61, 0x6000
	v_lshl_add_u64 v[128:129], s[62:63], 0, v[128:129]
	global_load_lds_dwordx4 v[130:131], off
	v_lshl_add_u64 v[128:129], v[128:129], 0, s[6:7]
	s_add_i32 m0, s61, 0xe000
	s_mov_b64 s[10:11], 0
	global_load_lds_dwordx4 v[128:129], off

; DEVI f32x4 mfma16(bf16x8 a, bf16x8 b, f32x4 c) { return __builtin_amdgcn_mfma_f32_16x16x32_bf16(a, b, c, 0, 0, 0); }
; template <int MODE, class Epi>
; DEVI void gemm256_phase(int sw, const bf16_t* __restrict__ W, int ldw, const bf16_t* __restrict__ X, int ldx, int K, int nN, char* shm, const Epi& epi) {
;     ...
;       const char* SAp = shm + cur * STAGE_B + wr * (16 * 1024) + lds_lo;
;       const char* SBp = shm + cur * STAGE_B + TILE_B + wc * (8 * 1024) + lds_lo;
; #pragma unroll
;       for (int ks = 0; ks < 2; ++ks) {
;         const int kx = (wid >> 2) ? (1 - 2 * ks) * 1024 : 0;
;         bf16x8 At[8], Bf[4];
; #pragma unroll
;         for (int m = 0; m < 8; ++m) At[m] = *(const bf16x8*)(SAp + (2 * m + ks) * 1024 + kx);
; #pragma unroll
;         for (int n = 0; n < 4; ++n) Bf[n] = *(const bf16x8*)(SBp + (2 * n + ks) * 1024 + kx);
; #pragma unroll
;         for (int m = 0; m < 8; ++m)
; #pragma unroll
;           for (int n = 0; n < 4; ++n) acc[m][n] = mfma16(At[m], Bf[n], acc[m][n]);
;         __builtin_amdgcn_sched_barrier(0);
;         if (ks == 0 && wid >= 4) {
;           if (st_own) stage(cur ^ 1, n0, m0, kt0 + t + 1);
;           else if (st_next) stage(cur ^ 1, n1, m1, kt1);
;         }
.LBB0_989:
	s_add_i32 s10, s59, s38
	v_add_u32_e32 v129, s10, v198
	v_add_u32_e32 v154, s41, v129
	ds_read_b128 v[220:223], v154
	s_add_i32 s10, s59, s39
	v_add_u32_e32 v128, s10, v198
	v_add_u32_e32 v150, s41, v128
	ds_read_b128 v[134:137], v150 offset:32768
	ds_read_b128 v[224:227], v154 offset:2048
	ds_read_b128 v[142:145], v150 offset:34816
	ds_read_b128 v[146:149], v150 offset:36864
	ds_read_b128 v[150:153], v150 offset:38912
	ds_read_b128 v[228:231], v154 offset:4096
	ds_read_b128 v[232:235], v154 offset:6144
	s_add_u32 s98, s12, s57
	s_addc_u32 s99, s13, 0
	s_add_u32 s98, s98, 0x80
	s_addc_u32 s99, s99, 0
	s_add_u32 s100, s55, s57
	s_addc_u32 s101, s56, 0
	s_add_u32 s100, s100, 0x80
	s_addc_u32 s101, s101, 0
	s_xor_b32 m0, s59, 0x10000
	s_add_i32 m0, m0, s14
	s_waitcnt lgkmcnt(2)
	v_mfma_f32_16x16x32_bf16 v[124:127], v[220:223], v[134:137], v[124:127]
	v_mfma_f32_16x16x32_bf16 v[120:123], v[220:223], v[142:145], v[120:123]
	v_mfma_f32_16x16x32_bf16 v[116:119], v[220:223], v[146:149], v[116:119]
	v_mfma_f32_16x16x32_bf16 v[112:115], v[220:223], v[150:153], v[112:115]
	global_load_lds_dwordx4 v194, s[98:99]
	ds_read_b128 v[236:239], v154 offset:8192
	s_add_i32 m0, m0, 0x8000
	s_waitcnt lgkmcnt(3)
	v_mfma_f32_16x16x32_bf16 v[108:111], v[224:227], v[134:137], v[108:111]
	v_mfma_f32_16x16x32_bf16 v[104:107], v[224:227], v[142:145], v[104:107]
	v_mfma_f32_16x16x32_bf16 v[100:103], v[224:227], v[146:149], v[100:103]
	v_mfma_f32_16x16x32_bf16 v[96:99], v[224:227], v[150:153], v[96:99]
	global_load_lds_dwordx4 v194, s[100:101]
	ds_read_b128 v[240:243], v154 offset:10240
	s_add_i32 m0, m0, 0xffffa000
	s_waitcnt lgkmcnt(3)
	v_mfma_f32_16x16x32_bf16 v[92:95], v[228:231], v[134:137], v[92:95]
	v_mfma_f32_16x16x32_bf16 v[88:91], v[228:231], v[142:145], v[88:91]
	v_mfma_f32_16x16x32_bf16 v[84:87], v[228:231], v[146:149], v[84:87]
	v_mfma_f32_16x16x32_bf16 v[80:83], v[228:231], v[150:153], v[80:83]
	global_load_lds_dwordx4 v195, s[98:99]
	ds_read_b128 v[244:247], v154 offset:12288
	s_add_i32 m0, m0, 0x8000
	s_waitcnt lgkmcnt(3)
	v_mfma_f32_16x16x32_bf16 v[76:79], v[232:235], v[134:137], v[76:79]
	v_mfma_f32_16x16x32_bf16 v[72:75], v[232:235], v[142:145], v[72:75]
	v_mfma_f32_16x16x32_bf16 v[68:71], v[232:235], v[146:149], v[68:71]
	v_mfma_f32_16x16x32_bf16 v[64:67], v[232:235], v[150:153], v[64:67]
	global_load_lds_dwordx4 v195, s[100:101]
	ds_read_b128 v[248:251], v154 offset:14336
	s_add_i32 m0, m0, 0xffffa000
	s_waitcnt lgkmcnt(3)
	v_mfma_f32_16x16x32_bf16 v[60:63], v[236:239], v[134:137], v[60:63]
	v_mfma_f32_16x16x32_bf16 v[56:59], v[236:239], v[142:145], v[56:59]
	v_mfma_f32_16x16x32_bf16 v[52:55], v[236:239], v[146:149], v[52:55]
	v_mfma_f32_16x16x32_bf16 v[48:51], v[236:239], v[150:153], v[48:51]
	global_load_lds_dwordx4 v196, s[98:99]
	s_add_i32 m0, m0, 0x8000
	s_waitcnt lgkmcnt(2)
	v_mfma_f32_16x16x32_bf16 v[44:47], v[240:243], v[134:137], v[44:47]
	v_mfma_f32_16x16x32_bf16 v[40:43], v[240:243], v[142:145], v[40:43]
	v_mfma_f32_16x16x32_bf16 v[36:39], v[240:243], v[146:149], v[36:39]
	v_mfma_f32_16x16x32_bf16 v[32:35], v[240:243], v[150:153], v[32:35]
	global_load_lds_dwordx4 v196, s[100:101]
	s_add_i32 m0, m0, 0xffffa000
	s_waitcnt lgkmcnt(1)
	v_mfma_f32_16x16x32_bf16 v[28:31], v[244:247], v[134:137], v[28:31]
	v_mfma_f32_16x16x32_bf16 v[24:27], v[244:247], v[142:145], v[24:27]
	v_mfma_f32_16x16x32_bf16 v[20:23], v[244:247], v[146:149], v[20:23]
	v_mfma_f32_16x16x32_bf16 v[16:19], v[244:247], v[150:153], v[16:19]
	global_load_lds_dwordx4 v197, s[98:99]
	s_add_i32 m0, m0, 0x8000
	s_waitcnt lgkmcnt(0)
	v_mfma_f32_16x16x32_bf16 v[12:15], v[248:251], v[134:137], v[12:15]
	v_mfma_f32_16x16x32_bf16 v[8:11], v[248:251], v[142:145], v[8:11]
	v_mfma_f32_16x16x32_bf16 v[4:7], v[248:251], v[146:149], v[4:7]
	v_mfma_f32_16x16x32_bf16 v[0:3], v[248:251], v[150:153], v[0:3]
	global_load_lds_dwordx4 v197, s[100:101]
	s_and_b64 vcc, exec, s[0:1]
	s_branch .LBB0_984
	s_xor_b32 s10, s59, 0x10000
	s_add_i32 s59, s14, s10
	s_add_i32 s62, s59, 0xe000
	s_add_i32 s63, s59, 0x6000
	s_add_i32 s64, s59, 0xc000
	s_add_i32 s65, s59, 0x4000
	s_add_i32 s66, s59, 0xa000
	s_add_i32 s67, s59, 0x2000
	s_add_i32 s68, s59, 0x8000
	s_ashr_i32 s61, s57, 31
	s_add_u32 s10, s55, s57
	s_addc_u32 s11, s56, s61
	s_add_u32 s60, s12, s57
	s_addc_u32 s61, s13, s61
	v_mov_b32_e32 v192, v194
	v_mov_b32_e32 v130, v194
	v_mov_b32_e32 v131, v193
	v_lshl_add_u64 v[132:133], s[60:61], 0, v[192:193]
	v_lshl_add_u64 v[132:133], v[132:133], 0, s[6:7]
	s_mov_b32 m0, s59
	v_lshl_add_u64 v[130:131], s[10:11], 0, v[130:131]
	global_load_lds_dwordx4 v[132:133], off
	v_lshl_add_u64 v[130:131], v[130:131], 0, s[6:7]
	s_mov_b32 m0, s68
	v_mov_b32_e32 v192, v195
	global_load_lds_dwordx4 v[130:131], off
	v_mov_b32_e32 v130, v195
	v_mov_b32_e32 v131, v193
	v_lshl_add_u64 v[132:133], s[60:61], 0, v[192:193]
	v_lshl_add_u64 v[132:133], v[132:133], 0, s[6:7]
	s_mov_b32 m0, s67
	v_lshl_add_u64 v[130:131], s[10:11], 0, v[130:131]
	global_load_lds_dwordx4 v[132:133], off
	v_lshl_add_u64 v[130:131], v[130:131], 0, s[6:7]
	s_mov_b32 m0, s66
	v_mov_b32_e32 v192, v196
	global_load_lds_dwordx4 v[130:131], off
	v_mov_b32_e32 v130, v196
	v_mov_b32_e32 v131, v193
	v_lshl_add_u64 v[132:133], s[60:61], 0, v[192:193]
	v_lshl_add_u64 v[132:133], v[132:133], 0, s[6:7]
	s_mov_b32 m0, s65
	v_lshl_add_u64 v[130:131], s[10:11], 0, v[130:131]
	global_load_lds_dwordx4 v[132:133], off
	v_lshl_add_u64 v[130:131], v[130:131], 0, s[6:7]
	s_mov_b32 m0, s64
	v_mov_b32_e32 v192, v197
	global_load_lds_dwordx4 v[130:131], off
	v_mov_b32_e32 v130, v197
	v_mov_b32_e32 v131, v193
	v_lshl_add_u64 v[132:133], s[60:61], 0, v[192:193]
	v_lshl_add_u64 v[132:133], v[132:133], 0, s[6:7]
	s_mov_b32 m0, s63
	v_lshl_add_u64 v[130:131], s[10:11], 0, v[130:131]
	global_load_lds_dwordx4 v[132:133], off
	v_lshl_add_u64 v[130:131], v[130:131], 0, s[6:7]
	s_mov_b32 m0, s62
	s_nop 0
	global_load_lds_dwordx4 v[130:131], off
	s_branch .LBB0_984

; template <int MODE, class Epi>
; DEVI void gemm256_phase(int sw, const bf16_t* __restrict__ W, int ldw, const bf16_t* __restrict__ X, int ldx, int K, int nN, char* shm, const Epi& epi) {
;     ...
;   auto stage = [&](int buf, int n0, int m0, int kt) {
;     const char* wk = (const char*)(W + (size_t)n0 * ldw) + kt * 128;
;     const char* xk = (const char*)(X + (size_t)m0 * ldx) + kt * 128;
; #pragma unroll
;     for (int i = 0; i < 4; ++i) {
;       unsigned ow = offW[i], ox = offX[i];
;       asm volatile("" : "+v"(ow), "+v"(ox));
;       __builtin_amdgcn_global_load_lds((const unsigned*)(wk + ow), (unsigned*)(shm + buf * STAGE_B + wid * 1024 + i * 8192), 16, 0, 0);
;       __builtin_amdgcn_global_load_lds((const unsigned*)(xk + ox), (unsigned*)(shm + buf * STAGE_B + TILE_B + wid * 1024 + i * 8192), 16, 0, 0);
;     }
;   };
;     ...
;     for (int t = 0; t < ntk; ++t) {
;       const int cur = (b0 + t) & 1;
;       const bool st_own = t + 1 < ntk, st_next = !st_own && has_next;
;       if (wid < 4) {
;         if (st_own) stage(cur ^ 1, n0, m0, kt0 + t + 1);
;         else if (st_next) stage(cur ^ 1, n1, m1, kt1);
;       }
.LBB0_1034:
	s_add_i32 s0, s61, s82
	s_and_b32 s83, s0, 1
	s_add_i32 s82, s82, 1
	s_cmp_lt_i32 s82, s54
	s_cselect_b64 s[0:1], -1, 0
	s_cmp_ge_i32 s82, s54
	s_cselect_b64 s[40:41], -1, 0
	v_cmp_ne_u32_e32 vcc, 1, v197
	v_cndmask_b32_e64 v128, 0, 1, s[0:1]
	s_and_b64 s[40:41], s[38:39], s[40:41]
	v_cmp_ne_u32_e64 s[0:1], 1, v128
	s_branch .LBB0_1043
	s_and_b64 vcc, exec, s[0:1]
	s_cbranch_vccnz .LBB0_1037
	s_ashr_i32 s44, s81, 31
	s_add_u32 s46, s78, s81
	s_addc_u32 s47, s79, s44
	s_add_u32 s42, s46, 0x80
	s_addc_u32 s43, s47, 0
	s_add_u32 s52, s76, s81
	s_addc_u32 s53, s77, s44
	s_add_u32 s44, s52, 0x80
	s_addc_u32 s45, s53, 0
	s_lshl_b32 s84, s83, 16
	s_xor_b32 s84, s84, 0x10000
	v_mov_b32_e32 v188, v190
	v_mov_b32_e32 v128, v190
	s_add_i32 s84, s57, s84
	v_lshl_add_u64 v[130:131], s[46:47], 0, v[188:189]
	v_mov_b32_e32 v129, v189
	v_lshl_add_u64 v[130:131], v[130:131], 0, s[10:11]
	s_mov_b32 m0, s84
	v_lshl_add_u64 v[128:129], s[52:53], 0, v[128:129]
	global_load_lds_dwordx4 v[130:131], off
	v_lshl_add_u64 v[128:129], v[128:129], 0, s[10:11]
	s_add_i32 m0, s84, 0x8000
	v_mov_b32_e32 v188, v191
	global_load_lds_dwordx4 v[128:129], off
	v_mov_b32_e32 v128, v191
	v_mov_b32_e32 v129, v189
	v_lshl_add_u64 v[130:131], s[46:47], 0, v[188:189]
	v_lshl_add_u64 v[130:131], v[130:131], 0, s[10:11]
	s_add_i32 m0, s84, 0x2000
	v_lshl_add_u64 v[128:129], s[52:53], 0, v[128:129]
	global_load_lds_dwordx4 v[130:131], off
	v_lshl_add_u64 v[128:129], v[128:129], 0, s[10:11]
	s_add_i32 m0, s84, 0xa000
	v_mov_b32_e32 v188, v192
	global_load_lds_dwordx4 v[128:129], off
	v_mov_b32_e32 v128, v192
	v_mov_b32_e32 v129, v189
	v_lshl_add_u64 v[130:131], s[46:47], 0, v[188:189]
	v_lshl_add_u64 v[130:131], v[130:131], 0, s[10:11]
	s_add_i32 m0, s84, 0x4000
	v_lshl_add_u64 v[128:129], s[52:53], 0, v[128:129]
	global_load_lds_dwordx4 v[130:131], off
	v_lshl_add_u64 v[128:129], v[128:129], 0, s[10:11]
	s_add_i32 m0, s84, 0xc000
	s_nop 0
	global_load_lds_dwordx4 v[128:129], off
	v_mov_b32_e32 v128, v193
	v_mov_b32_e32 v129, v193
	s_mov_b64 s[46:47], -1
	s_cbranch_execz .LBB0_1038
	s_branch .LBB0_1041

; DEVI f32x4 mfma16(bf16x8 a, bf16x8 b, f32x4 c) { return __builtin_amdgcn_mfma_f32_16x16x32_bf16(a, b, c, 0, 0, 0); }
; template <int MODE, class Epi>
; DEVI void gemm256_phase(int sw, const bf16_t* __restrict__ W, int ldw, const bf16_t* __restrict__ X, int ldx, int K, int nN, char* shm, const Epi& epi) {
;     ...
;       const char* SAp = shm + cur * STAGE_B + wr * (16 * 1024) + lds_lo;
;       const char* SBp = shm + cur * STAGE_B + TILE_B + wc * (8 * 1024) + lds_lo;
; #pragma unroll
;       for (int ks = 0; ks < 2; ++ks) {
;         const int kx = (wid >> 2) ? (1 - 2 * ks) * 1024 : 0;
;         bf16x8 At[8], Bf[4];
; #pragma unroll
;         for (int m = 0; m < 8; ++m) At[m] = *(const bf16x8*)(SAp + (2 * m + ks) * 1024 + kx);
; #pragma unroll
;         for (int n = 0; n < 4; ++n) Bf[n] = *(const bf16x8*)(SBp + (2 * n + ks) * 1024 + kx);
; #pragma unroll
;         for (int m = 0; m < 8; ++m)
; #pragma unroll
;           for (int n = 0; n < 4; ++n) acc[m][n] = mfma16(At[m], Bf[n], acc[m][n]);
;         __builtin_amdgcn_sched_barrier(0);
;         if (ks == 0 && wid >= 4) {
;           if (st_own) stage(cur ^ 1, n0, m0, kt0 + t + 1);
;           else if (st_next) stage(cur ^ 1, n1, m1, kt1);
;         }
.LBB0_1043:
	s_lshl_b32 s42, s83, 16
	s_add_i32 s43, s42, s58
	v_add_u32_e32 v129, s43, v194
	v_add_u32_e32 v154, s62, v129
	ds_read_b128 v[220:223], v154
	s_or_b32 s43, s42, s59
	v_add_u32_e32 v128, s43, v194
	v_add_u32_e32 v150, s62, v128
	ds_read_b128 v[134:137], v150 offset:32768
	ds_read_b128 v[224:227], v154 offset:2048
	ds_read_b128 v[142:145], v150 offset:34816
	ds_read_b128 v[146:149], v150 offset:36864
	ds_read_b128 v[150:153], v150 offset:38912
	ds_read_b128 v[228:231], v154 offset:4096
	ds_read_b128 v[232:235], v154 offset:6144
	s_add_u32 s98, s78, s81
	s_addc_u32 s99, s79, 0
	s_add_u32 s98, s98, 0x80
	s_addc_u32 s99, s99, 0
	s_add_u32 s100, s76, s81
	s_addc_u32 s101, s77, 0
	s_add_u32 s100, s100, 0x80
	s_addc_u32 s101, s101, 0
	s_xor_b32 m0, s42, 0x10000
	s_add_i32 m0, m0, s57
	s_waitcnt lgkmcnt(2)
	v_mfma_f32_16x16x32_bf16 v[124:127], v[220:223], v[134:137], v[124:127]
	v_mfma_f32_16x16x32_bf16 v[120:123], v[220:223], v[142:145], v[120:123]
	v_mfma_f32_16x16x32_bf16 v[116:119], v[220:223], v[146:149], v[116:119]
	v_mfma_f32_16x16x32_bf16 v[112:115], v[220:223], v[150:153], v[112:115]
	global_load_lds_dwordx4 v190, s[98:99]
	ds_read_b128 v[236:239], v154 offset:8192
	s_add_i32 m0, m0, 0x8000
	s_waitcnt lgkmcnt(3)
	v_mfma_f32_16x16x32_bf16 v[108:111], v[224:227], v[134:137], v[108:111]
	v_mfma_f32_16x16x32_bf16 v[104:107], v[224:227], v[142:145], v[104:107]
	v_mfma_f32_16x16x32_bf16 v[100:103], v[224:227], v[146:149], v[100:103]
	v_mfma_f32_16x16x32_bf16 v[96:99], v[224:227], v[150:153], v[96:99]
	global_load_lds_dwordx4 v190, s[100:101]
	ds_read_b128 v[240:243], v154 offset:10240
	s_add_i32 m0, m0, 0xffffa000
	s_waitcnt lgkmcnt(3)
	v_mfma_f32_16x16x32_bf16 v[92:95], v[228:231], v[134:137], v[92:95]
	v_mfma_f32_16x16x32_bf16 v[88:91], v[228:231], v[142:145], v[88:91]
	v_mfma_f32_16x16x32_bf16 v[84:87], v[228:231], v[146:149], v[84:87]
	v_mfma_f32_16x16x32_bf16 v[80:83], v[228:231], v[150:153], v[80:83]
	global_load_lds_dwordx4 v191, s[98:99]
	ds_read_b128 v[244:247], v154 offset:12288
	s_add_i32 m0, m0, 0x8000
	s_waitcnt lgkmcnt(3)
	v_mfma_f32_16x16x32_bf16 v[76:79], v[232:235], v[134:137], v[76:79]
	v_mfma_f32_16x16x32_bf16 v[72:75], v[232:235], v[142:145], v[72:75]
	v_mfma_f32_16x16x32_bf16 v[68:71], v[232:235], v[146:149], v[68:71]
	v_mfma_f32_16x16x32_bf16 v[64:67], v[232:235], v[150:153], v[64:67]
	global_load_lds_dwordx4 v191, s[100:101]
	ds_read_b128 v[248:251], v154 offset:14336
	s_add_i32 m0, m0, 0xffffa000
	s_waitcnt lgkmcnt(3)
	v_mfma_f32_16x16x32_bf16 v[60:63], v[236:239], v[134:137], v[60:63]
	v_mfma_f32_16x16x32_bf16 v[56:59], v[236:239], v[142:145], v[56:59]
	v_mfma_f32_16x16x32_bf16 v[52:55], v[236:239], v[146:149], v[52:55]
	v_mfma_f32_16x16x32_bf16 v[48:51], v[236:239], v[150:153], v[48:51]
	global_load_lds_dwordx4 v192, s[98:99]
	s_add_i32 m0, m0, 0x8000
	s_waitcnt lgkmcnt(2)
	v_mfma_f32_16x16x32_bf16 v[44:47], v[240:243], v[134:137], v[44:47]
	v_mfma_f32_16x16x32_bf16 v[40:43], v[240:243], v[142:145], v[40:43]
	v_mfma_f32_16x16x32_bf16 v[36:39], v[240:243], v[146:149], v[36:39]
	v_mfma_f32_16x16x32_bf16 v[32:35], v[240:243], v[150:153], v[32:35]
	global_load_lds_dwordx4 v192, s[100:101]
	s_add_i32 m0, m0, 0xffffa000
	s_waitcnt lgkmcnt(1)
	v_mfma_f32_16x16x32_bf16 v[28:31], v[244:247], v[134:137], v[28:31]
	v_mfma_f32_16x16x32_bf16 v[24:27], v[244:247], v[142:145], v[24:27]
	v_mfma_f32_16x16x32_bf16 v[20:23], v[244:247], v[146:149], v[20:23]
	v_mfma_f32_16x16x32_bf16 v[16:19], v[244:247], v[150:153], v[16:19]
	global_load_lds_dwordx4 v193, s[98:99]
	s_add_i32 m0, m0, 0x8000
	s_waitcnt lgkmcnt(0)
	v_mfma_f32_16x16x32_bf16 v[12:15], v[248:251], v[134:137], v[12:15]
	v_mfma_f32_16x16x32_bf16 v[8:11], v[248:251], v[142:145], v[8:11]
	v_mfma_f32_16x16x32_bf16 v[4:7], v[248:251], v[146:149], v[4:7]
	v_mfma_f32_16x16x32_bf16 v[0:3], v[248:251], v[150:153], v[0:3]
	global_load_lds_dwordx4 v193, s[100:101]
	s_andn2_b64 vcc, exec, s[8:9]
	s_branch .LBB0_1033
	s_and_b64 vcc, exec, s[0:1]
	s_xor_b32 s52, s42, 0x10000
	s_cbranch_vccnz .LBB0_1046
	s_ashr_i32 s42, s81, 31
	s_add_u32 s44, s78, s81
	s_addc_u32 s45, s79, s42
	s_add_u32 s0, s44, 0x80
	s_addc_u32 s1, s45, 0
	s_add_u32 s46, s76, s81
	s_addc_u32 s47, s77, s42
	s_add_u32 s42, s46, 0x80
	v_mov_b32_e32 v188, v190
	v_mov_b32_e32 v130, v190
	s_addc_u32 s43, s47, 0
	s_add_i32 s53, s57, s52
	v_lshl_add_u64 v[132:133], s[44:45], 0, v[188:189]
	v_mov_b32_e32 v131, v189
	v_lshl_add_u64 v[132:133], v[132:133], 0, s[10:11]
	s_mov_b32 m0, s53
	v_lshl_add_u64 v[130:131], s[46:47], 0, v[130:131]
	global_load_lds_dwordx4 v[132:133], off
	v_lshl_add_u64 v[130:131], v[130:131], 0, s[10:11]
	s_add_i32 m0, s53, 0x8000
	v_mov_b32_e32 v188, v191
	global_load_lds_dwordx4 v[130:131], off
	v_mov_b32_e32 v130, v191
	v_mov_b32_e32 v131, v189
	v_lshl_add_u64 v[132:133], s[44:45], 0, v[188:189]
	v_lshl_add_u64 v[132:133], v[132:133], 0, s[10:11]
	s_add_i32 m0, s53, 0x2000
	v_lshl_add_u64 v[130:131], s[46:47], 0, v[130:131]
	global_load_lds_dwordx4 v[132:133], off
	v_lshl_add_u64 v[130:131], v[130:131], 0, s[10:11]
	s_add_i32 m0, s53, 0xa000
	v_mov_b32_e32 v188, v192
	global_load_lds_dwordx4 v[130:131], off
	v_mov_b32_e32 v130, v192
	v_mov_b32_e32 v131, v189
	v_lshl_add_u64 v[132:133], s[44:45], 0, v[188:189]
	v_lshl_add_u64 v[132:133], v[132:133], 0, s[10:11]
	s_add_i32 m0, s53, 0x4000
	v_lshl_add_u64 v[130:131], s[46:47], 0, v[130:131]
	global_load_lds_dwordx4 v[132:133], off
	v_lshl_add_u64 v[130:131], v[130:131], 0, s[10:11]
	s_add_i32 m0, s53, 0xc000
	s_nop 0
	global_load_lds_dwordx4 v[130:131], off
	v_mov_b32_e32 v130, v193
	v_mov_b32_e32 v131, v193
	s_mov_b64 s[44:45], -1
	s_cbranch_execz .LBB0_1047
	s_branch .LBB0_1050

; template <int MODE, class Epi>
; DEVI void gemm256_phase(int sw, const bf16_t* __restrict__ W, int ldw, const bf16_t* __restrict__ X, int ldx, int K, int nN, char* shm, const Epi& epi) {
;     ...
;   auto stage = [&](int buf, int n0, int m0, int kt) {
;     const char* wk = (const char*)(W + (size_t)n0 * ldw) + kt * 128;
;     const char* xk = (const char*)(X + (size_t)m0 * ldx) + kt * 128;
; #pragma unroll
;     for (int i = 0; i < 4; ++i) {
;       unsigned ow = offW[i], ox = offX[i];
;       asm volatile("" : "+v"(ow), "+v"(ox));
;       __builtin_amdgcn_global_load_lds((const unsigned*)(wk + ow), (unsigned*)(shm + buf * STAGE_B + wid * 1024 + i * 8192), 16, 0, 0);
;       __builtin_amdgcn_global_load_lds((const unsigned*)(xk + ox), (unsigned*)(shm + buf * STAGE_B + TILE_B + wid * 1024 + i * 8192), 16, 0, 0);
;     }
;   };
;     ...
;     for (int t = 0; t < ntk; ++t) {
;       const int cur = (b0 + t) & 1;
;       const bool st_own = t + 1 < ntk, st_next = !st_own && has_next;
;       if (wid < 4) {
;         if (st_own) stage(cur ^ 1, n0, m0, kt0 + t + 1);
;         else if (st_next) stage(cur ^ 1, n1, m1, kt1);
;       }
.LBB0_1270:
	s_add_i32 s0, s49, s73
	s_and_b32 s74, s0, 1
	s_add_i32 s73, s73, 1
	s_cmp_lt_i32 s73, s54
	s_cselect_b64 s[0:1], -1, 0
	s_cmp_ge_i32 s73, s54
	s_cselect_b64 s[8:9], -1, 0
	v_cndmask_b32_e64 v128, 0, 1, s[0:1]
	s_and_b64 s[8:9], s[2:3], s[8:9]
	s_andn2_b64 vcc, exec, s[40:41]
	v_cmp_ne_u32_e64 s[0:1], 1, v128
	s_branch .LBB0_1279
	s_and_b64 vcc, exec, s[0:1]
	s_cbranch_vccnz .LBB0_1273
	s_ashr_i32 s12, s72, 31
	s_add_u32 s14, s67, s72
	s_addc_u32 s15, s68, s12
	s_add_u32 s10, s14, 0x80
	s_addc_u32 s11, s15, 0
	s_add_u32 s46, s69, s72
	s_addc_u32 s47, s70, s12
	s_add_u32 s12, s46, 0x80
	s_addc_u32 s13, s47, 0
	s_lshl_b32 s75, s74, 16
	s_xor_b32 s75, s75, 0x10000
	v_mov_b32_e32 v188, v190
	v_mov_b32_e32 v128, v190
	s_add_i32 s75, s48, s75
	v_lshl_add_u64 v[130:131], s[14:15], 0, v[188:189]
	v_mov_b32_e32 v129, v189
	v_lshl_add_u64 v[130:131], v[130:131], 0, s[42:43]
	s_mov_b32 m0, s75
	v_lshl_add_u64 v[128:129], s[46:47], 0, v[128:129]
	global_load_lds_dwordx4 v[130:131], off
	v_lshl_add_u64 v[128:129], v[128:129], 0, s[42:43]
	s_add_i32 m0, s75, 0x8000
	v_mov_b32_e32 v188, v191
	global_load_lds_dwordx4 v[128:129], off
	v_mov_b32_e32 v128, v191
	v_mov_b32_e32 v129, v189
	v_lshl_add_u64 v[130:131], s[14:15], 0, v[188:189]
	v_lshl_add_u64 v[130:131], v[130:131], 0, s[42:43]
	s_add_i32 m0, s75, 0x2000
	v_lshl_add_u64 v[128:129], s[46:47], 0, v[128:129]
	global_load_lds_dwordx4 v[130:131], off
	v_lshl_add_u64 v[128:129], v[128:129], 0, s[42:43]
	s_add_i32 m0, s75, 0xa000
	v_mov_b32_e32 v188, v192
	global_load_lds_dwordx4 v[128:129], off
	v_mov_b32_e32 v128, v192
	v_mov_b32_e32 v129, v189
	v_lshl_add_u64 v[130:131], s[14:15], 0, v[188:189]
	v_lshl_add_u64 v[130:131], v[130:131], 0, s[42:43]
	s_add_i32 m0, s75, 0x4000
	v_lshl_add_u64 v[128:129], s[46:47], 0, v[128:129]
	global_load_lds_dwordx4 v[130:131], off
	v_lshl_add_u64 v[128:129], v[128:129], 0, s[42:43]
	s_add_i32 m0, s75, 0xc000
	s_nop 0
	global_load_lds_dwordx4 v[128:129], off
	v_mov_b32_e32 v128, v193
	v_mov_b32_e32 v129, v193
	s_mov_b64 s[14:15], -1
	s_cbranch_execz .LBB0_1274
	s_branch .LBB0_1277

; DEVI f32x4 mfma16(bf16x8 a, bf16x8 b, f32x4 c) { return __builtin_amdgcn_mfma_f32_16x16x32_bf16(a, b, c, 0, 0, 0); }
; template <int MODE, class Epi>
; DEVI void gemm256_phase(int sw, const bf16_t* __restrict__ W, int ldw, const bf16_t* __restrict__ X, int ldx, int K, int nN, char* shm, const Epi& epi) {
;     ...
;       const char* SAp = shm + cur * STAGE_B + wr * (16 * 1024) + lds_lo;
;       const char* SBp = shm + cur * STAGE_B + TILE_B + wc * (8 * 1024) + lds_lo;
; #pragma unroll
;       for (int ks = 0; ks < 2; ++ks) {
;         const int kx = (wid >> 2) ? (1 - 2 * ks) * 1024 : 0;
;         bf16x8 At[8], Bf[4];
; #pragma unroll
;         for (int m = 0; m < 8; ++m) At[m] = *(const bf16x8*)(SAp + (2 * m + ks) * 1024 + kx);
; #pragma unroll
;         for (int n = 0; n < 4; ++n) Bf[n] = *(const bf16x8*)(SBp + (2 * n + ks) * 1024 + kx);
; #pragma unroll
;         for (int m = 0; m < 8; ++m)
; #pragma unroll
;           for (int n = 0; n < 4; ++n) acc[m][n] = mfma16(At[m], Bf[n], acc[m][n]);
;         __builtin_amdgcn_sched_barrier(0);
;         if (ks == 0 && wid >= 4) {
;           if (st_own) stage(cur ^ 1, n0, m0, kt0 + t + 1);
;           else if (st_next) stage(cur ^ 1, n1, m1, kt1);
;         }
.LBB0_1279:
	s_lshl_b32 s10, s74, 16
	s_add_i32 s11, s10, s55
	v_add_u32_e32 v129, s11, v194
	v_add_u32_e32 v154, s57, v129
	ds_read_b128 v[220:223], v154
	s_or_b32 s11, s10, s56
	v_add_u32_e32 v128, s11, v194
	v_add_u32_e32 v150, s57, v128
	ds_read_b128 v[134:137], v150 offset:32768
	ds_read_b128 v[224:227], v154 offset:2048
	ds_read_b128 v[142:145], v150 offset:34816
	ds_read_b128 v[146:149], v150 offset:36864
	ds_read_b128 v[150:153], v150 offset:38912
	ds_read_b128 v[228:231], v154 offset:4096
	ds_read_b128 v[232:235], v154 offset:6144
	s_add_u32 s98, s67, s72
	s_addc_u32 s99, s68, 0
	s_add_u32 s98, s98, 0x80
	s_addc_u32 s99, s99, 0
	s_add_u32 s100, s69, s72
	s_addc_u32 s101, s70, 0
	s_add_u32 s100, s100, 0x80
	s_addc_u32 s101, s101, 0
	s_xor_b32 m0, s10, 0x10000
	s_add_i32 m0, m0, s48
	s_waitcnt lgkmcnt(2)
	v_mfma_f32_16x16x32_bf16 v[124:127], v[220:223], v[134:137], v[124:127]
	v_mfma_f32_16x16x32_bf16 v[120:123], v[220:223], v[142:145], v[120:123]
	v_mfma_f32_16x16x32_bf16 v[116:119], v[220:223], v[146:149], v[116:119]
	v_mfma_f32_16x16x32_bf16 v[112:115], v[220:223], v[150:153], v[112:115]
	global_load_lds_dwordx4 v190, s[98:99]
	ds_read_b128 v[236:239], v154 offset:8192
	s_add_i32 m0, m0, 0x8000
	s_waitcnt lgkmcnt(3)
	v_mfma_f32_16x16x32_bf16 v[108:111], v[224:227], v[134:137], v[108:111]
	v_mfma_f32_16x16x32_bf16 v[104:107], v[224:227], v[142:145], v[104:107]
	v_mfma_f32_16x16x32_bf16 v[100:103], v[224:227], v[146:149], v[100:103]
	v_mfma_f32_16x16x32_bf16 v[96:99], v[224:227], v[150:153], v[96:99]
	global_load_lds_dwordx4 v190, s[100:101]
	ds_read_b128 v[240:243], v154 offset:10240
	s_add_i32 m0, m0, 0xffffa000
	s_waitcnt lgkmcnt(3)
	v_mfma_f32_16x16x32_bf16 v[92:95], v[228:231], v[134:137], v[92:95]
	v_mfma_f32_16x16x32_bf16 v[88:91], v[228:231], v[142:145], v[88:91]
	v_mfma_f32_16x16x32_bf16 v[84:87], v[228:231], v[146:149], v[84:87]
	v_mfma_f32_16x16x32_bf16 v[80:83], v[228:231], v[150:153], v[80:83]
	global_load_lds_dwordx4 v191, s[98:99]
	ds_read_b128 v[244:247], v154 offset:12288
	s_add_i32 m0, m0, 0x8000
	s_waitcnt lgkmcnt(3)
	v_mfma_f32_16x16x32_bf16 v[76:79], v[232:235], v[134:137], v[76:79]
	v_mfma_f32_16x16x32_bf16 v[72:75], v[232:235], v[142:145], v[72:75]
	v_mfma_f32_16x16x32_bf16 v[68:71], v[232:235], v[146:149], v[68:71]
	v_mfma_f32_16x16x32_bf16 v[64:67], v[232:235], v[150:153], v[64:67]
	global_load_lds_dwordx4 v191, s[100:101]
	ds_read_b128 v[248:251], v154 offset:14336
	s_add_i32 m0, m0, 0xffffa000
	s_waitcnt lgkmcnt(3)
	v_mfma_f32_16x16x32_bf16 v[60:63], v[236:239], v[134:137], v[60:63]
	v_mfma_f32_16x16x32_bf16 v[56:59], v[236:239], v[142:145], v[56:59]
	v_mfma_f32_16x16x32_bf16 v[52:55], v[236:239], v[146:149], v[52:55]
	v_mfma_f32_16x16x32_bf16 v[48:51], v[236:239], v[150:153], v[48:51]
	global_load_lds_dwordx4 v192, s[98:99]
	s_add_i32 m0, m0, 0x8000
	s_waitcnt lgkmcnt(2)
	v_mfma_f32_16x16x32_bf16 v[44:47], v[240:243], v[134:137], v[44:47]
	v_mfma_f32_16x16x32_bf16 v[40:43], v[240:243], v[142:145], v[40:43]
	v_mfma_f32_16x16x32_bf16 v[36:39], v[240:243], v[146:149], v[36:39]
	v_mfma_f32_16x16x32_bf16 v[32:35], v[240:243], v[150:153], v[32:35]
	global_load_lds_dwordx4 v192, s[100:101]
	s_add_i32 m0, m0, 0xffffa000
	s_waitcnt lgkmcnt(1)
	v_mfma_f32_16x16x32_bf16 v[28:31], v[244:247], v[134:137], v[28:31]
	v_mfma_f32_16x16x32_bf16 v[24:27], v[244:247], v[142:145], v[24:27]
	v_mfma_f32_16x16x32_bf16 v[20:23], v[244:247], v[146:149], v[20:23]
	v_mfma_f32_16x16x32_bf16 v[16:19], v[244:247], v[150:153], v[16:19]
	global_load_lds_dwordx4 v193, s[98:99]
	s_add_i32 m0, m0, 0x8000
	s_waitcnt lgkmcnt(0)
	v_mfma_f32_16x16x32_bf16 v[12:15], v[248:251], v[134:137], v[12:15]
	v_mfma_f32_16x16x32_bf16 v[8:11], v[248:251], v[142:145], v[8:11]
	v_mfma_f32_16x16x32_bf16 v[4:7], v[248:251], v[146:149], v[4:7]
	v_mfma_f32_16x16x32_bf16 v[0:3], v[248:251], v[150:153], v[0:3]
	global_load_lds_dwordx4 v193, s[100:101]
	s_andn2_b64 vcc, exec, s[38:39]
	s_branch .LBB0_1269
	s_and_b64 vcc, exec, s[0:1]
	s_xor_b32 s46, s10, 0x10000
	s_cbranch_vccnz .LBB0_1282
	s_ashr_i32 s10, s72, 31
	s_add_u32 s12, s67, s72
	s_addc_u32 s13, s68, s10
	s_add_u32 s0, s12, 0x80
	s_addc_u32 s1, s13, 0
	s_add_u32 s14, s69, s72
	s_addc_u32 s15, s70, s10
	s_add_u32 s10, s14, 0x80
	v_mov_b32_e32 v130, v190
	v_mov_b32_e32 v188, v190
	s_addc_u32 s11, s15, 0
	s_add_i32 s47, s48, s46
	v_lshl_add_u64 v[132:133], s[12:13], 0, v[188:189]
	v_mov_b32_e32 v131, v189
	v_lshl_add_u64 v[132:133], v[132:133], 0, s[42:43]
	s_mov_b32 m0, s47
	v_lshl_add_u64 v[130:131], s[14:15], 0, v[130:131]
	global_load_lds_dwordx4 v[132:133], off
	v_lshl_add_u64 v[130:131], v[130:131], 0, s[42:43]
	s_add_i32 m0, s47, 0x8000
	v_mov_b32_e32 v188, v191
	global_load_lds_dwordx4 v[130:131], off
	v_mov_b32_e32 v130, v191
	v_mov_b32_e32 v131, v189
	v_lshl_add_u64 v[132:133], s[12:13], 0, v[188:189]
	v_lshl_add_u64 v[132:133], v[132:133], 0, s[42:43]
	s_add_i32 m0, s47, 0x2000
	v_lshl_add_u64 v[130:131], s[14:15], 0, v[130:131]
	global_load_lds_dwordx4 v[132:133], off
	v_lshl_add_u64 v[130:131], v[130:131], 0, s[42:43]
	s_add_i32 m0, s47, 0xa000
	v_mov_b32_e32 v188, v192
	global_load_lds_dwordx4 v[130:131], off
	v_mov_b32_e32 v130, v192
	v_mov_b32_e32 v131, v189
	v_lshl_add_u64 v[132:133], s[12:13], 0, v[188:189]
	v_lshl_add_u64 v[132:133], v[132:133], 0, s[42:43]
	s_add_i32 m0, s47, 0x4000
	v_lshl_add_u64 v[130:131], s[14:15], 0, v[130:131]
	global_load_lds_dwordx4 v[132:133], off
	v_lshl_add_u64 v[130:131], v[130:131], 0, s[42:43]
	s_add_i32 m0, s47, 0xc000
	s_nop 0
	global_load_lds_dwordx4 v[130:131], off
	v_mov_b32_e32 v130, v193
	v_mov_b32_e32 v131, v193
	s_mov_b64 s[12:13], -1
	s_cbranch_execz .LBB0_1283
	s_branch .LBB0_1286

; template <int MODE, class Epi>
; DEVI void gemm256_phase(int sw, const bf16_t* __restrict__ W, int ldw, const bf16_t* __restrict__ X, int ldx, int K, int nN, char* shm, const Epi& epi) {
;     ...
;   auto stage = [&](int buf, int n0, int m0, int kt) {
;     const char* wk = (const char*)(W + (size_t)n0 * ldw) + kt * 128;
;     const char* xk = (const char*)(X + (size_t)m0 * ldx) + kt * 128;
; #pragma unroll
;     for (int i = 0; i < 4; ++i) {
;       unsigned ow = offW[i], ox = offX[i];
;       asm volatile("" : "+v"(ow), "+v"(ox));
;       __builtin_amdgcn_global_load_lds((const unsigned*)(wk + ow), (unsigned*)(shm + buf * STAGE_B + wid * 1024 + i * 8192), 16, 0, 0);
;       __builtin_amdgcn_global_load_lds((const unsigned*)(xk + ox), (unsigned*)(shm + buf * STAGE_B + TILE_B + wid * 1024 + i * 8192), 16, 0, 0);
;     }
;   };
;     ...
;     for (int t = 0; t < ntk; ++t) {
;       const int cur = (b0 + t) & 1;
;       const bool st_own = t + 1 < ntk, st_next = !st_own && has_next;
;       if (wid < 4) {
;         if (st_own) stage(cur ^ 1, n0, m0, kt0 + t + 1);
;         else if (st_next) stage(cur ^ 1, n1, m1, kt1);
;       }
.LBB0_1678:
	s_add_i32 s2, s61, s79
	s_and_b32 s80, s2, 1
	s_add_i32 s79, s79, 1
	s_cmp_lt_i32 s79, s60
	s_cselect_b64 s[2:3], -1, 0
	s_cmp_ge_i32 s79, s60
	s_cselect_b64 s[40:41], -1, 0
	v_cndmask_b32_e64 v128, 0, 1, s[2:3]
	s_and_b64 s[40:41], s[34:35], s[40:41]
	s_and_b64 vcc, exec, s[0:1]
	v_cmp_ne_u32_e64 s[2:3], 1, v128
	s_branch .LBB0_1687
	s_and_b64 vcc, exec, s[2:3]
	s_cbranch_vccnz .LBB0_1681
	s_ashr_i32 s16, s78, 31
	s_add_u32 s46, s73, s78
	s_addc_u32 s47, s74, s16
	s_add_u32 s42, s46, 0x80
	s_addc_u32 s43, s47, 0
	s_add_u32 s48, s75, s78
	s_addc_u32 s49, s76, s16
	s_add_u32 s44, s48, 0x80
	s_addc_u32 s45, s49, 0
	s_lshl_b32 s16, s80, 16
	s_xor_b32 s16, s16, 0x10000
	v_mov_b32_e32 v188, v190
	v_mov_b32_e32 v128, v190
	s_add_i32 s81, s56, s16
	v_lshl_add_u64 v[130:131], s[46:47], 0, v[188:189]
	v_mov_b32_e32 v129, v189
	v_lshl_add_u64 v[130:131], v[130:131], 0, s[12:13]
	s_mov_b32 m0, s81
	v_lshl_add_u64 v[128:129], s[48:49], 0, v[128:129]
	global_load_lds_dwordx4 v[130:131], off
	v_lshl_add_u64 v[128:129], v[128:129], 0, s[12:13]
	s_add_i32 m0, s81, 0x8000
	v_mov_b32_e32 v188, v191
	global_load_lds_dwordx4 v[128:129], off
	v_mov_b32_e32 v128, v191
	v_mov_b32_e32 v129, v189
	v_lshl_add_u64 v[130:131], s[46:47], 0, v[188:189]
	v_lshl_add_u64 v[130:131], v[130:131], 0, s[12:13]
	s_add_i32 m0, s81, 0x2000
	v_lshl_add_u64 v[128:129], s[48:49], 0, v[128:129]
	global_load_lds_dwordx4 v[130:131], off
	v_lshl_add_u64 v[128:129], v[128:129], 0, s[12:13]
	s_add_i32 m0, s81, 0xa000
	v_mov_b32_e32 v188, v192
	global_load_lds_dwordx4 v[128:129], off
	v_mov_b32_e32 v128, v192
	v_mov_b32_e32 v129, v189
	v_lshl_add_u64 v[130:131], s[46:47], 0, v[188:189]
	v_lshl_add_u64 v[130:131], v[130:131], 0, s[12:13]
	s_add_i32 m0, s81, 0x4000
	v_lshl_add_u64 v[128:129], s[48:49], 0, v[128:129]
	global_load_lds_dwordx4 v[130:131], off
	v_lshl_add_u64 v[128:129], v[128:129], 0, s[12:13]
	s_add_i32 m0, s81, 0xc000
	s_nop 0
	global_load_lds_dwordx4 v[128:129], off
	v_mov_b32_e32 v128, v193
	v_mov_b32_e32 v129, v193
	s_mov_b64 s[46:47], -1
	s_cbranch_execz .LBB0_1682
	s_branch .LBB0_1685

; DEVI f32x4 mfma16(bf16x8 a, bf16x8 b, f32x4 c) { return __builtin_amdgcn_mfma_f32_16x16x32_bf16(a, b, c, 0, 0, 0); }
; template <int MODE, class Epi>
; DEVI void gemm256_phase(int sw, const bf16_t* __restrict__ W, int ldw, const bf16_t* __restrict__ X, int ldx, int K, int nN, char* shm, const Epi& epi) {
;     ...
;       const char* SAp = shm + cur * STAGE_B + wr * (16 * 1024) + lds_lo;
;       const char* SBp = shm + cur * STAGE_B + TILE_B + wc * (8 * 1024) + lds_lo;
; #pragma unroll
;       for (int ks = 0; ks < 2; ++ks) {
;         const int kx = (wid >> 2) ? (1 - 2 * ks) * 1024 : 0;
;         bf16x8 At[8], Bf[4];
; #pragma unroll
;         for (int m = 0; m < 8; ++m) At[m] = *(const bf16x8*)(SAp + (2 * m + ks) * 1024 + kx);
; #pragma unroll
;         for (int n = 0; n < 4; ++n) Bf[n] = *(const bf16x8*)(SBp + (2 * n + ks) * 1024 + kx);
; #pragma unroll
;         for (int m = 0; m < 8; ++m)
; #pragma unroll
;           for (int n = 0; n < 4; ++n) acc[m][n] = mfma16(At[m], Bf[n], acc[m][n]);
;         __builtin_amdgcn_sched_barrier(0);
;         if (ks == 0 && wid >= 4) {
;           if (st_own) stage(cur ^ 1, n0, m0, kt0 + t + 1);
;           else if (st_next) stage(cur ^ 1, n1, m1, kt1);
;         }
.LBB0_1687:
	s_lshl_b32 s42, s80, 16
	s_add_i32 s16, s42, s57
	v_add_u32_e32 v129, s16, v194
	v_add_u32_e32 v154, s62, v129
	ds_read_b128 v[220:223], v154
	s_or_b32 s16, s42, s58
	v_add_u32_e32 v128, s16, v194
	v_add_u32_e32 v150, s62, v128
	ds_read_b128 v[134:137], v150 offset:32768
	ds_read_b128 v[224:227], v154 offset:2048
	ds_read_b128 v[142:145], v150 offset:34816
	ds_read_b128 v[146:149], v150 offset:36864
	ds_read_b128 v[150:153], v150 offset:38912
	ds_read_b128 v[228:231], v154 offset:4096
	ds_read_b128 v[232:235], v154 offset:6144
	s_add_u32 s98, s73, s78
	s_addc_u32 s99, s74, 0
	s_add_u32 s98, s98, 0x80
	s_addc_u32 s99, s99, 0
	s_add_u32 s100, s75, s78
	s_addc_u32 s101, s76, 0
	s_add_u32 s100, s100, 0x80
	s_addc_u32 s101, s101, 0
	s_xor_b32 m0, s42, 0x10000
	s_add_i32 m0, m0, s56
	s_waitcnt lgkmcnt(2)
	v_mfma_f32_16x16x32_bf16 v[124:127], v[220:223], v[134:137], v[124:127]
	v_mfma_f32_16x16x32_bf16 v[120:123], v[220:223], v[142:145], v[120:123]
	v_mfma_f32_16x16x32_bf16 v[116:119], v[220:223], v[146:149], v[116:119]
	v_mfma_f32_16x16x32_bf16 v[112:115], v[220:223], v[150:153], v[112:115]
	global_load_lds_dwordx4 v190, s[98:99]
	ds_read_b128 v[236:239], v154 offset:8192
	s_add_i32 m0, m0, 0x8000
	s_waitcnt lgkmcnt(3)
	v_mfma_f32_16x16x32_bf16 v[108:111], v[224:227], v[134:137], v[108:111]
	v_mfma_f32_16x16x32_bf16 v[104:107], v[224:227], v[142:145], v[104:107]
	v_mfma_f32_16x16x32_bf16 v[100:103], v[224:227], v[146:149], v[100:103]
	v_mfma_f32_16x16x32_bf16 v[96:99], v[224:227], v[150:153], v[96:99]
	global_load_lds_dwordx4 v190, s[100:101]
	ds_read_b128 v[240:243], v154 offset:10240
	s_add_i32 m0, m0, 0xffffa000
	s_waitcnt lgkmcnt(3)
	v_mfma_f32_16x16x32_bf16 v[92:95], v[228:231], v[134:137], v[92:95]
	v_mfma_f32_16x16x32_bf16 v[88:91], v[228:231], v[142:145], v[88:91]
	v_mfma_f32_16x16x32_bf16 v[84:87], v[228:231], v[146:149], v[84:87]
	v_mfma_f32_16x16x32_bf16 v[80:83], v[228:231], v[150:153], v[80:83]
	global_load_lds_dwordx4 v191, s[98:99]
	ds_read_b128 v[244:247], v154 offset:12288
	s_add_i32 m0, m0, 0x8000
	s_waitcnt lgkmcnt(3)
	v_mfma_f32_16x16x32_bf16 v[76:79], v[232:235], v[134:137], v[76:79]
	v_mfma_f32_16x16x32_bf16 v[72:75], v[232:235], v[142:145], v[72:75]
	v_mfma_f32_16x16x32_bf16 v[68:71], v[232:235], v[146:149], v[68:71]
	v_mfma_f32_16x16x32_bf16 v[64:67], v[232:235], v[150:153], v[64:67]
	global_load_lds_dwordx4 v191, s[100:101]
	ds_read_b128 v[248:251], v154 offset:14336
	s_add_i32 m0, m0, 0xffffa000
	s_waitcnt lgkmcnt(3)
	v_mfma_f32_16x16x32_bf16 v[60:63], v[236:239], v[134:137], v[60:63]
	v_mfma_f32_16x16x32_bf16 v[56:59], v[236:239], v[142:145], v[56:59]
	v_mfma_f32_16x16x32_bf16 v[52:55], v[236:239], v[146:149], v[52:55]
	v_mfma_f32_16x16x32_bf16 v[48:51], v[236:239], v[150:153], v[48:51]
	global_load_lds_dwordx4 v192, s[98:99]
	s_add_i32 m0, m0, 0x8000
	s_waitcnt lgkmcnt(2)
	v_mfma_f32_16x16x32_bf16 v[44:47], v[240:243], v[134:137], v[44:47]
	v_mfma_f32_16x16x32_bf16 v[40:43], v[240:243], v[142:145], v[40:43]
	v_mfma_f32_16x16x32_bf16 v[36:39], v[240:243], v[146:149], v[36:39]
	v_mfma_f32_16x16x32_bf16 v[32:35], v[240:243], v[150:153], v[32:35]
	global_load_lds_dwordx4 v192, s[100:101]
	s_add_i32 m0, m0, 0xffffa000
	s_waitcnt lgkmcnt(1)
	v_mfma_f32_16x16x32_bf16 v[28:31], v[244:247], v[134:137], v[28:31]
	v_mfma_f32_16x16x32_bf16 v[24:27], v[244:247], v[142:145], v[24:27]
	v_mfma_f32_16x16x32_bf16 v[20:23], v[244:247], v[146:149], v[20:23]
	v_mfma_f32_16x16x32_bf16 v[16:19], v[244:247], v[150:153], v[16:19]
	global_load_lds_dwordx4 v193, s[98:99]
	s_add_i32 m0, m0, 0x8000
	s_waitcnt lgkmcnt(0)
	v_mfma_f32_16x16x32_bf16 v[12:15], v[248:251], v[134:137], v[12:15]
	v_mfma_f32_16x16x32_bf16 v[8:11], v[248:251], v[142:145], v[8:11]
	v_mfma_f32_16x16x32_bf16 v[4:7], v[248:251], v[146:149], v[4:7]
	v_mfma_f32_16x16x32_bf16 v[0:3], v[248:251], v[150:153], v[0:3]
	global_load_lds_dwordx4 v193, s[100:101]
	s_andn2_b64 vcc, exec, s[8:9]
	s_branch .LBB0_1677
	s_and_b64 vcc, exec, s[2:3]
	s_xor_b32 s48, s42, 0x10000
	s_cbranch_vccnz .LBB0_1690
	s_ashr_i32 s16, s78, 31
	s_add_u32 s44, s73, s78
	s_addc_u32 s45, s74, s16
	s_add_u32 s2, s44, 0x80
	s_addc_u32 s3, s45, 0
	s_add_u32 s46, s75, s78
	s_addc_u32 s47, s76, s16
	s_add_u32 s42, s46, 0x80
	v_mov_b32_e32 v130, v190
	v_mov_b32_e32 v188, v190
	s_addc_u32 s43, s47, 0
	s_add_i32 s16, s56, s48
	v_lshl_add_u64 v[132:133], s[44:45], 0, v[188:189]
	v_mov_b32_e32 v131, v189
	v_lshl_add_u64 v[132:133], v[132:133], 0, s[12:13]
	s_mov_b32 m0, s16
	v_lshl_add_u64 v[130:131], s[46:47], 0, v[130:131]
	global_load_lds_dwordx4 v[132:133], off
	v_lshl_add_u64 v[130:131], v[130:131], 0, s[12:13]
	s_add_i32 m0, s16, 0x8000
	v_mov_b32_e32 v188, v191
	global_load_lds_dwordx4 v[130:131], off
	v_mov_b32_e32 v130, v191
	v_mov_b32_e32 v131, v189
	v_lshl_add_u64 v[132:133], s[44:45], 0, v[188:189]
	v_lshl_add_u64 v[132:133], v[132:133], 0, s[12:13]
	s_add_i32 m0, s16, 0x2000
	v_lshl_add_u64 v[130:131], s[46:47], 0, v[130:131]
	global_load_lds_dwordx4 v[132:133], off
	v_lshl_add_u64 v[130:131], v[130:131], 0, s[12:13]
	s_add_i32 m0, s16, 0xa000
	v_mov_b32_e32 v188, v192
	global_load_lds_dwordx4 v[130:131], off
	v_mov_b32_e32 v130, v192
	v_mov_b32_e32 v131, v189
	v_lshl_add_u64 v[132:133], s[44:45], 0, v[188:189]
	v_lshl_add_u64 v[132:133], v[132:133], 0, s[12:13]
	s_add_i32 m0, s16, 0x4000
	v_lshl_add_u64 v[130:131], s[46:47], 0, v[130:131]
	global_load_lds_dwordx4 v[132:133], off
	v_lshl_add_u64 v[130:131], v[130:131], 0, s[12:13]
	s_add_i32 m0, s16, 0xc000
	s_nop 0
	global_load_lds_dwordx4 v[130:131], off
	v_mov_b32_e32 v130, v193
	v_mov_b32_e32 v131, v193
	s_mov_b64 s[44:45], -1
	s_cbranch_execz .LBB0_1691
	s_branch .LBB0_1694

; template <int MODE, class Epi>
; DEVI void gemm256_phase(int sw, const bf16_t* __restrict__ W, int ldw, const bf16_t* __restrict__ X, int ldx, int K, int nN, char* shm, const Epi& epi) {
;     ...
;   auto stage = [&](int buf, int n0, int m0, int kt) {
;     const char* wk = (const char*)(W + (size_t)n0 * ldw) + kt * 128;
;     const char* xk = (const char*)(X + (size_t)m0 * ldx) + kt * 128;
; #pragma unroll
;     for (int i = 0; i < 4; ++i) {
;       unsigned ow = offW[i], ox = offX[i];
;       asm volatile("" : "+v"(ow), "+v"(ox));
;       __builtin_amdgcn_global_load_lds((const unsigned*)(wk + ow), (unsigned*)(shm + buf * STAGE_B + wid * 1024 + i * 8192), 16, 0, 0);
;       __builtin_amdgcn_global_load_lds((const unsigned*)(xk + ox), (unsigned*)(shm + buf * STAGE_B + TILE_B + wid * 1024 + i * 8192), 16, 0, 0);
;     }
;   };
;     ...
;     for (int t = 0; t < ntk; ++t) {
;       const int cur = (b0 + t) & 1;
;       const bool st_own = t + 1 < ntk, st_next = !st_own && has_next;
;       if (wid < 4) {
;         if (st_own) stage(cur ^ 1, n0, m0, kt0 + t + 1);
;         else if (st_next) stage(cur ^ 1, n1, m1, kt1);
;       }
.LBB0_1760:
	s_add_i32 s10, s31, s50
	s_and_b32 s52, s10, 1
	s_mov_b64 s[10:11], -1
	s_and_b64 vcc, exec, s[4:5]
	s_branch .LBB0_1762
	s_ashr_i32 s16, s49, 31
	s_add_u32 s10, s12, s49
	s_addc_u32 s11, s13, s16
	s_add_u32 s54, s47, s49
	s_addc_u32 s55, s48, s16
	s_lshl_b32 s51, s52, 16
	s_xor_b32 s16, s51, 0x10000
	v_mov_b32_e32 v192, v194
	v_mov_b32_e32 v128, v194
	s_add_i32 s16, s14, s16
	v_lshl_add_u64 v[130:131], s[10:11], 0, v[192:193]
	v_mov_b32_e32 v129, v193
	v_lshl_add_u64 v[130:131], v[130:131], 0, s[6:7]
	s_mov_b32 m0, s16
	v_lshl_add_u64 v[128:129], s[54:55], 0, v[128:129]
	global_load_lds_dwordx4 v[130:131], off
	v_lshl_add_u64 v[128:129], v[128:129], 0, s[6:7]
	s_add_i32 m0, s16, 0x8000
	v_mov_b32_e32 v192, v195
	global_load_lds_dwordx4 v[128:129], off
	v_mov_b32_e32 v128, v195
	v_mov_b32_e32 v129, v193
	v_lshl_add_u64 v[130:131], s[10:11], 0, v[192:193]
	v_lshl_add_u64 v[130:131], v[130:131], 0, s[6:7]
	s_add_i32 m0, s16, 0x2000
	v_lshl_add_u64 v[128:129], s[54:55], 0, v[128:129]
	global_load_lds_dwordx4 v[130:131], off
	v_lshl_add_u64 v[128:129], v[128:129], 0, s[6:7]
	s_add_i32 m0, s16, 0xa000
	v_mov_b32_e32 v192, v196
	global_load_lds_dwordx4 v[128:129], off
	v_mov_b32_e32 v128, v196
	v_mov_b32_e32 v129, v193
	v_lshl_add_u64 v[130:131], s[10:11], 0, v[192:193]
	v_lshl_add_u64 v[130:131], v[130:131], 0, s[6:7]
	s_add_i32 m0, s16, 0x4000
	v_lshl_add_u64 v[128:129], s[54:55], 0, v[128:129]
	global_load_lds_dwordx4 v[130:131], off
	v_lshl_add_u64 v[128:129], v[128:129], 0, s[6:7]
	s_add_i32 m0, s16, 0xc000
	v_mov_b32_e32 v192, v197
	global_load_lds_dwordx4 v[128:129], off
	v_mov_b32_e32 v128, v197
	v_mov_b32_e32 v129, v193
	v_lshl_add_u64 v[130:131], s[10:11], 0, v[192:193]
	v_lshl_add_u64 v[130:131], v[130:131], 0, s[6:7]
	s_add_i32 m0, s16, 0x6000
	v_lshl_add_u64 v[128:129], s[54:55], 0, v[128:129]
	global_load_lds_dwordx4 v[130:131], off
	v_lshl_add_u64 v[128:129], v[128:129], 0, s[6:7]
	s_add_i32 m0, s16, 0xe000
	s_mov_b64 s[10:11], 0
	global_load_lds_dwordx4 v[128:129], off

; DEVI f32x4 mfma16(bf16x8 a, bf16x8 b, f32x4 c) { return __builtin_amdgcn_mfma_f32_16x16x32_bf16(a, b, c, 0, 0, 0); }
; template <int MODE, class Epi>
; DEVI void gemm256_phase(int sw, const bf16_t* __restrict__ W, int ldw, const bf16_t* __restrict__ X, int ldx, int K, int nN, char* shm, const Epi& epi) {
;     ...
;       const char* SAp = shm + cur * STAGE_B + wr * (16 * 1024) + lds_lo;
;       const char* SBp = shm + cur * STAGE_B + TILE_B + wc * (8 * 1024) + lds_lo;
; #pragma unroll
;       for (int ks = 0; ks < 2; ++ks) {
;         const int kx = (wid >> 2) ? (1 - 2 * ks) * 1024 : 0;
;         bf16x8 At[8], Bf[4];
; #pragma unroll
;         for (int m = 0; m < 8; ++m) At[m] = *(const bf16x8*)(SAp + (2 * m + ks) * 1024 + kx);
; #pragma unroll
;         for (int n = 0; n < 4; ++n) Bf[n] = *(const bf16x8*)(SBp + (2 * n + ks) * 1024 + kx);
; #pragma unroll
;         for (int m = 0; m < 8; ++m)
; #pragma unroll
;           for (int n = 0; n < 4; ++n) acc[m][n] = mfma16(At[m], Bf[n], acc[m][n]);
;         __builtin_amdgcn_sched_barrier(0);
;         if (ks == 0 && wid >= 4) {
;           if (st_own) stage(cur ^ 1, n0, m0, kt0 + t + 1);
;           else if (st_next) stage(cur ^ 1, n1, m1, kt1);
;         }
.LBB0_1764:
	s_add_i32 s10, s51, s34
	v_add_u32_e32 v129, s10, v198
	v_add_u32_e32 v154, s37, v129
	ds_read_b128 v[220:223], v154
	s_add_i32 s10, s51, s35
	v_add_u32_e32 v128, s10, v198
	v_add_u32_e32 v150, s37, v128
	ds_read_b128 v[134:137], v150 offset:32768
	ds_read_b128 v[224:227], v154 offset:2048
	ds_read_b128 v[142:145], v150 offset:34816
	ds_read_b128 v[146:149], v150 offset:36864
	ds_read_b128 v[150:153], v150 offset:38912
	ds_read_b128 v[228:231], v154 offset:4096
	ds_read_b128 v[232:235], v154 offset:6144
	s_add_u32 s98, s12, s49
	s_addc_u32 s99, s13, 0
	s_add_u32 s98, s98, 0x80
	s_addc_u32 s99, s99, 0
	s_add_u32 s100, s47, s49
	s_addc_u32 s101, s48, 0
	s_add_u32 s100, s100, 0x80
	s_addc_u32 s101, s101, 0
	s_xor_b32 m0, s51, 0x10000
	s_add_i32 m0, m0, s14
	s_waitcnt lgkmcnt(2)
	v_mfma_f32_16x16x32_bf16 v[124:127], v[220:223], v[134:137], v[124:127]
	v_mfma_f32_16x16x32_bf16 v[120:123], v[220:223], v[142:145], v[120:123]
	v_mfma_f32_16x16x32_bf16 v[116:119], v[220:223], v[146:149], v[116:119]
	v_mfma_f32_16x16x32_bf16 v[112:115], v[220:223], v[150:153], v[112:115]
	global_load_lds_dwordx4 v194, s[98:99]
	ds_read_b128 v[236:239], v154 offset:8192
	s_add_i32 m0, m0, 0x8000
	s_waitcnt lgkmcnt(3)
	v_mfma_f32_16x16x32_bf16 v[108:111], v[224:227], v[134:137], v[108:111]
	v_mfma_f32_16x16x32_bf16 v[104:107], v[224:227], v[142:145], v[104:107]
	v_mfma_f32_16x16x32_bf16 v[100:103], v[224:227], v[146:149], v[100:103]
	v_mfma_f32_16x16x32_bf16 v[96:99], v[224:227], v[150:153], v[96:99]
	global_load_lds_dwordx4 v194, s[100:101]
	ds_read_b128 v[240:243], v154 offset:10240
	s_add_i32 m0, m0, 0xffffa000
	s_waitcnt lgkmcnt(3)
	v_mfma_f32_16x16x32_bf16 v[92:95], v[228:231], v[134:137], v[92:95]
	v_mfma_f32_16x16x32_bf16 v[88:91], v[228:231], v[142:145], v[88:91]
	v_mfma_f32_16x16x32_bf16 v[84:87], v[228:231], v[146:149], v[84:87]
	v_mfma_f32_16x16x32_bf16 v[80:83], v[228:231], v[150:153], v[80:83]
	global_load_lds_dwordx4 v195, s[98:99]
	ds_read_b128 v[244:247], v154 offset:12288
	s_add_i32 m0, m0, 0x8000
	s_waitcnt lgkmcnt(3)
	v_mfma_f32_16x16x32_bf16 v[76:79], v[232:235], v[134:137], v[76:79]
	v_mfma_f32_16x16x32_bf16 v[72:75], v[232:235], v[142:145], v[72:75]
	v_mfma_f32_16x16x32_bf16 v[68:71], v[232:235], v[146:149], v[68:71]
	v_mfma_f32_16x16x32_bf16 v[64:67], v[232:235], v[150:153], v[64:67]
	global_load_lds_dwordx4 v195, s[100:101]
	ds_read_b128 v[248:251], v154 offset:14336
	s_add_i32 m0, m0, 0xffffa000
	s_waitcnt lgkmcnt(3)
	v_mfma_f32_16x16x32_bf16 v[60:63], v[236:239], v[134:137], v[60:63]
	v_mfma_f32_16x16x32_bf16 v[56:59], v[236:239], v[142:145], v[56:59]
	v_mfma_f32_16x16x32_bf16 v[52:55], v[236:239], v[146:149], v[52:55]
	v_mfma_f32_16x16x32_bf16 v[48:51], v[236:239], v[150:153], v[48:51]
	global_load_lds_dwordx4 v196, s[98:99]
	s_add_i32 m0, m0, 0x8000
	s_waitcnt lgkmcnt(2)
	v_mfma_f32_16x16x32_bf16 v[44:47], v[240:243], v[134:137], v[44:47]
	v_mfma_f32_16x16x32_bf16 v[40:43], v[240:243], v[142:145], v[40:43]
	v_mfma_f32_16x16x32_bf16 v[36:39], v[240:243], v[146:149], v[36:39]
	v_mfma_f32_16x16x32_bf16 v[32:35], v[240:243], v[150:153], v[32:35]
	global_load_lds_dwordx4 v196, s[100:101]
	s_add_i32 m0, m0, 0xffffa000
	s_waitcnt lgkmcnt(1)
	v_mfma_f32_16x16x32_bf16 v[28:31], v[244:247], v[134:137], v[28:31]
	v_mfma_f32_16x16x32_bf16 v[24:27], v[244:247], v[142:145], v[24:27]
	v_mfma_f32_16x16x32_bf16 v[20:23], v[244:247], v[146:149], v[20:23]
	v_mfma_f32_16x16x32_bf16 v[16:19], v[244:247], v[150:153], v[16:19]
	global_load_lds_dwordx4 v197, s[98:99]
	s_add_i32 m0, m0, 0x8000
	s_waitcnt lgkmcnt(0)
	v_mfma_f32_16x16x32_bf16 v[12:15], v[248:251], v[134:137], v[12:15]
	v_mfma_f32_16x16x32_bf16 v[8:11], v[248:251], v[142:145], v[8:11]
	v_mfma_f32_16x16x32_bf16 v[4:7], v[248:251], v[146:149], v[4:7]
	v_mfma_f32_16x16x32_bf16 v[0:3], v[248:251], v[150:153], v[0:3]
	global_load_lds_dwordx4 v197, s[100:101]
	s_and_b64 vcc, exec, s[0:1]
	s_branch .LBB0_1759
	s_xor_b32 s10, s51, 0x10000
	s_add_i32 s16, s14, s10
	s_add_i32 s17, s16, 0xe000
	s_add_i32 s18, s16, 0x6000
	s_add_i32 s19, s16, 0xc000
	s_add_i32 s28, s16, 0x4000
	s_add_i32 s29, s16, 0xa000
	s_add_i32 s33, s16, 0x2000
	s_add_i32 s51, s16, 0x8000
	s_ashr_i32 s53, s49, 31
	s_add_u32 s10, s47, s49
	s_addc_u32 s11, s48, s53
	s_add_u32 s52, s12, s49
	s_addc_u32 s53, s13, s53
	v_mov_b32_e32 v192, v194
	v_mov_b32_e32 v130, v194
	v_mov_b32_e32 v131, v193
	v_lshl_add_u64 v[132:133], s[52:53], 0, v[192:193]
	v_lshl_add_u64 v[132:133], v[132:133], 0, s[6:7]
	s_mov_b32 m0, s16
	v_lshl_add_u64 v[130:131], s[10:11], 0, v[130:131]
	global_load_lds_dwordx4 v[132:133], off
	v_lshl_add_u64 v[130:131], v[130:131], 0, s[6:7]
	s_mov_b32 m0, s51
	v_mov_b32_e32 v192, v195
	global_load_lds_dwordx4 v[130:131], off
	v_mov_b32_e32 v130, v195
	v_mov_b32_e32 v131, v193
	v_lshl_add_u64 v[132:133], s[52:53], 0, v[192:193]
	v_lshl_add_u64 v[132:133], v[132:133], 0, s[6:7]
	s_mov_b32 m0, s33
	v_lshl_add_u64 v[130:131], s[10:11], 0, v[130:131]
	global_load_lds_dwordx4 v[132:133], off
	v_lshl_add_u64 v[130:131], v[130:131], 0, s[6:7]
	s_mov_b32 m0, s29
	v_mov_b32_e32 v192, v196
	global_load_lds_dwordx4 v[130:131], off
	v_mov_b32_e32 v130, v196
	v_mov_b32_e32 v131, v193
	v_lshl_add_u64 v[132:133], s[52:53], 0, v[192:193]
	v_lshl_add_u64 v[132:133], v[132:133], 0, s[6:7]
	s_mov_b32 m0, s28
	v_lshl_add_u64 v[130:131], s[10:11], 0, v[130:131]
	global_load_lds_dwordx4 v[132:133], off
	v_lshl_add_u64 v[130:131], v[130:131], 0, s[6:7]
	s_mov_b32 m0, s19
	v_mov_b32_e32 v192, v197
	global_load_lds_dwordx4 v[130:131], off
	v_mov_b32_e32 v130, v197
	v_mov_b32_e32 v131, v193
	v_lshl_add_u64 v[132:133], s[52:53], 0, v[192:193]
	v_lshl_add_u64 v[132:133], v[132:133], 0, s[6:7]
	s_mov_b32 m0, s18
	v_lshl_add_u64 v[130:131], s[10:11], 0, v[130:131]
	global_load_lds_dwordx4 v[132:133], off
	v_lshl_add_u64 v[130:131], v[130:131], 0, s[6:7]
	s_mov_b32 m0, s17
	s_nop 0
	global_load_lds_dwordx4 v[130:131], off
	s_branch .LBB0_1759

; template <int MODE, class Epi>
; DEVI void gemm256_phase(int sw, const bf16_t* __restrict__ W, int ldw, const bf16_t* __restrict__ X, int ldx, int K, int nN, char* shm, const Epi& epi) {
;     ...
;   auto stage = [&](int buf, int n0, int m0, int kt) {
;     const char* wk = (const char*)(W + (size_t)n0 * ldw) + kt * 128;
;     const char* xk = (const char*)(X + (size_t)m0 * ldx) + kt * 128;
; #pragma unroll
;     for (int i = 0; i < 4; ++i) {
;       unsigned ow = offW[i], ox = offX[i];
;       asm volatile("" : "+v"(ow), "+v"(ox));
;       __builtin_amdgcn_global_load_lds((const unsigned*)(wk + ow), (unsigned*)(shm + buf * STAGE_B + wid * 1024 + i * 8192), 16, 0, 0);
;       __builtin_amdgcn_global_load_lds((const unsigned*)(xk + ox), (unsigned*)(shm + buf * STAGE_B + TILE_B + wid * 1024 + i * 8192), 16, 0, 0);
;     }
;   };
;     ...
;     for (int t = 0; t < ntk; ++t) {
;       const int cur = (b0 + t) & 1;
;       const bool st_own = t + 1 < ntk, st_next = !st_own && has_next;
;       if (wid < 4) {
;         if (st_own) stage(cur ^ 1, n0, m0, kt0 + t + 1);
;         else if (st_next) stage(cur ^ 1, n1, m1, kt1);
;       }
.LBB0_1801:
	s_add_i32 s2, s52, s70
	s_and_b32 s71, s2, 1
	s_add_i32 s70, s70, 1
	s_cmp_lt_i32 s70, s58
	s_cselect_b64 s[2:3], -1, 0
	s_cmp_ge_i32 s70, s58
	s_cselect_b64 s[36:37], -1, 0
	v_cndmask_b32_e64 v128, 0, 1, s[2:3]
	s_and_b64 s[36:37], s[28:29], s[36:37]
	s_and_b64 vcc, exec, s[0:1]
	v_cmp_ne_u32_e64 s[2:3], 1, v128
	s_branch .LBB0_1810
	s_and_b64 vcc, exec, s[2:3]
	s_cbranch_vccnz .LBB0_1804
	s_ashr_i32 s16, s69, 31
	s_add_u32 s42, s64, s69
	s_addc_u32 s43, s65, s16
	s_add_u32 s38, s42, 0x80
	s_addc_u32 s39, s43, 0
	s_add_u32 s44, s66, s69
	s_addc_u32 s45, s67, s16
	s_add_u32 s40, s44, 0x80
	s_addc_u32 s41, s45, 0
	s_lshl_b32 s16, s71, 16
	s_xor_b32 s16, s16, 0x10000
	v_mov_b32_e32 v188, v190
	v_mov_b32_e32 v128, v190
	s_add_i32 s72, s48, s16
	v_lshl_add_u64 v[130:131], s[42:43], 0, v[188:189]
	v_mov_b32_e32 v129, v189
	v_lshl_add_u64 v[130:131], v[130:131], 0, s[12:13]
	s_mov_b32 m0, s72
	v_lshl_add_u64 v[128:129], s[44:45], 0, v[128:129]
	global_load_lds_dwordx4 v[130:131], off
	v_lshl_add_u64 v[128:129], v[128:129], 0, s[12:13]
	s_add_i32 m0, s72, 0x8000
	v_mov_b32_e32 v188, v191
	global_load_lds_dwordx4 v[128:129], off
	v_mov_b32_e32 v128, v191
	v_mov_b32_e32 v129, v189
	v_lshl_add_u64 v[130:131], s[42:43], 0, v[188:189]
	v_lshl_add_u64 v[130:131], v[130:131], 0, s[12:13]
	s_add_i32 m0, s72, 0x2000
	v_lshl_add_u64 v[128:129], s[44:45], 0, v[128:129]
	global_load_lds_dwordx4 v[130:131], off
	v_lshl_add_u64 v[128:129], v[128:129], 0, s[12:13]
	s_add_i32 m0, s72, 0xa000
	v_mov_b32_e32 v188, v192
	global_load_lds_dwordx4 v[128:129], off
	v_mov_b32_e32 v128, v192
	v_mov_b32_e32 v129, v189
	v_lshl_add_u64 v[130:131], s[42:43], 0, v[188:189]
	v_lshl_add_u64 v[130:131], v[130:131], 0, s[12:13]
	s_add_i32 m0, s72, 0x4000
	v_lshl_add_u64 v[128:129], s[44:45], 0, v[128:129]
	global_load_lds_dwordx4 v[130:131], off
	v_lshl_add_u64 v[128:129], v[128:129], 0, s[12:13]
	s_add_i32 m0, s72, 0xc000
	s_nop 0
	global_load_lds_dwordx4 v[128:129], off
	v_mov_b32_e32 v128, v193
	v_mov_b32_e32 v129, v193
	s_mov_b64 s[42:43], -1
	s_cbranch_execz .LBB0_1805
	s_branch .LBB0_1808

; DEVI f32x4 mfma16(bf16x8 a, bf16x8 b, f32x4 c) { return __builtin_amdgcn_mfma_f32_16x16x32_bf16(a, b, c, 0, 0, 0); }
; template <int MODE, class Epi>
; DEVI void gemm256_phase(int sw, const bf16_t* __restrict__ W, int ldw, const bf16_t* __restrict__ X, int ldx, int K, int nN, char* shm, const Epi& epi) {
;     ...
;       const char* SAp = shm + cur * STAGE_B + wr * (16 * 1024) + lds_lo;
;       const char* SBp = shm + cur * STAGE_B + TILE_B + wc * (8 * 1024) + lds_lo;
; #pragma unroll
;       for (int ks = 0; ks < 2; ++ks) {
;         const int kx = (wid >> 2) ? (1 - 2 * ks) * 1024 : 0;
;         bf16x8 At[8], Bf[4];
; #pragma unroll
;         for (int m = 0; m < 8; ++m) At[m] = *(const bf16x8*)(SAp + (2 * m + ks) * 1024 + kx);
; #pragma unroll
;         for (int n = 0; n < 4; ++n) Bf[n] = *(const bf16x8*)(SBp + (2 * n + ks) * 1024 + kx);
; #pragma unroll
;         for (int m = 0; m < 8; ++m)
; #pragma unroll
;           for (int n = 0; n < 4; ++n) acc[m][n] = mfma16(At[m], Bf[n], acc[m][n]);
;         __builtin_amdgcn_sched_barrier(0);
;         if (ks == 0 && wid >= 4) {
;           if (st_own) stage(cur ^ 1, n0, m0, kt0 + t + 1);
;           else if (st_next) stage(cur ^ 1, n1, m1, kt1);
;         }
.LBB0_1810:
	s_lshl_b32 s38, s71, 16
	s_add_i32 s16, s38, s49
	v_add_u32_e32 v129, s16, v194
	v_add_u32_e32 v154, s53, v129
	ds_read_b128 v[220:223], v154
	s_or_b32 s16, s38, s50
	v_add_u32_e32 v128, s16, v194
	v_add_u32_e32 v150, s53, v128
	ds_read_b128 v[134:137], v150 offset:32768
	ds_read_b128 v[224:227], v154 offset:2048
	ds_read_b128 v[142:145], v150 offset:34816
	ds_read_b128 v[146:149], v150 offset:36864
	ds_read_b128 v[150:153], v150 offset:38912
	ds_read_b128 v[228:231], v154 offset:4096
	ds_read_b128 v[232:235], v154 offset:6144
	s_add_u32 s98, s64, s69
	s_addc_u32 s99, s65, 0
	s_add_u32 s98, s98, 0x80
	s_addc_u32 s99, s99, 0
	s_add_u32 s100, s66, s69
	s_addc_u32 s101, s67, 0
	s_add_u32 s100, s100, 0x80
	s_addc_u32 s101, s101, 0
	s_xor_b32 m0, s38, 0x10000
	s_add_i32 m0, m0, s48
	s_waitcnt lgkmcnt(2)
	v_mfma_f32_16x16x32_bf16 v[124:127], v[220:223], v[134:137], v[124:127]
	v_mfma_f32_16x16x32_bf16 v[120:123], v[220:223], v[142:145], v[120:123]
	v_mfma_f32_16x16x32_bf16 v[116:119], v[220:223], v[146:149], v[116:119]
	v_mfma_f32_16x16x32_bf16 v[112:115], v[220:223], v[150:153], v[112:115]
	global_load_lds_dwordx4 v190, s[98:99]
	ds_read_b128 v[236:239], v154 offset:8192
	s_add_i32 m0, m0, 0x8000
	s_waitcnt lgkmcnt(3)
	v_mfma_f32_16x16x32_bf16 v[108:111], v[224:227], v[134:137], v[108:111]
	v_mfma_f32_16x16x32_bf16 v[104:107], v[224:227], v[142:145], v[104:107]
	v_mfma_f32_16x16x32_bf16 v[100:103], v[224:227], v[146:149], v[100:103]
	v_mfma_f32_16x16x32_bf16 v[96:99], v[224:227], v[150:153], v[96:99]
	global_load_lds_dwordx4 v190, s[100:101]
	ds_read_b128 v[240:243], v154 offset:10240
	s_add_i32 m0, m0, 0xffffa000
	s_waitcnt lgkmcnt(3)
	v_mfma_f32_16x16x32_bf16 v[92:95], v[228:231], v[134:137], v[92:95]
	v_mfma_f32_16x16x32_bf16 v[88:91], v[228:231], v[142:145], v[88:91]
	v_mfma_f32_16x16x32_bf16 v[84:87], v[228:231], v[146:149], v[84:87]
	v_mfma_f32_16x16x32_bf16 v[80:83], v[228:231], v[150:153], v[80:83]
	global_load_lds_dwordx4 v191, s[98:99]
	ds_read_b128 v[244:247], v154 offset:12288
	s_add_i32 m0, m0, 0x8000
	s_waitcnt lgkmcnt(3)
	v_mfma_f32_16x16x32_bf16 v[76:79], v[232:235], v[134:137], v[76:79]
	v_mfma_f32_16x16x32_bf16 v[72:75], v[232:235], v[142:145], v[72:75]
	v_mfma_f32_16x16x32_bf16 v[68:71], v[232:235], v[146:149], v[68:71]
	v_mfma_f32_16x16x32_bf16 v[64:67], v[232:235], v[150:153], v[64:67]
	global_load_lds_dwordx4 v191, s[100:101]
	ds_read_b128 v[248:251], v154 offset:14336
	s_add_i32 m0, m0, 0xffffa000
	s_waitcnt lgkmcnt(3)
	v_mfma_f32_16x16x32_bf16 v[60:63], v[236:239], v[134:137], v[60:63]
	v_mfma_f32_16x16x32_bf16 v[56:59], v[236:239], v[142:145], v[56:59]
	v_mfma_f32_16x16x32_bf16 v[52:55], v[236:239], v[146:149], v[52:55]
	v_mfma_f32_16x16x32_bf16 v[48:51], v[236:239], v[150:153], v[48:51]
	global_load_lds_dwordx4 v192, s[98:99]
	s_add_i32 m0, m0, 0x8000
	s_waitcnt lgkmcnt(2)
	v_mfma_f32_16x16x32_bf16 v[44:47], v[240:243], v[134:137], v[44:47]
	v_mfma_f32_16x16x32_bf16 v[40:43], v[240:243], v[142:145], v[40:43]
	v_mfma_f32_16x16x32_bf16 v[36:39], v[240:243], v[146:149], v[36:39]
	v_mfma_f32_16x16x32_bf16 v[32:35], v[240:243], v[150:153], v[32:35]
	global_load_lds_dwordx4 v192, s[100:101]
	s_add_i32 m0, m0, 0xffffa000
	s_waitcnt lgkmcnt(1)
	v_mfma_f32_16x16x32_bf16 v[28:31], v[244:247], v[134:137], v[28:31]
	v_mfma_f32_16x16x32_bf16 v[24:27], v[244:247], v[142:145], v[24:27]
	v_mfma_f32_16x16x32_bf16 v[20:23], v[244:247], v[146:149], v[20:23]
	v_mfma_f32_16x16x32_bf16 v[16:19], v[244:247], v[150:153], v[16:19]
	global_load_lds_dwordx4 v193, s[98:99]
	s_add_i32 m0, m0, 0x8000
	s_waitcnt lgkmcnt(0)
	v_mfma_f32_16x16x32_bf16 v[12:15], v[248:251], v[134:137], v[12:15]
	v_mfma_f32_16x16x32_bf16 v[8:11], v[248:251], v[142:145], v[8:11]
	v_mfma_f32_16x16x32_bf16 v[4:7], v[248:251], v[146:149], v[4:7]
	v_mfma_f32_16x16x32_bf16 v[0:3], v[248:251], v[150:153], v[0:3]
	global_load_lds_dwordx4 v193, s[100:101]
	s_andn2_b64 vcc, exec, s[8:9]
	s_branch .LBB0_1800
	s_and_b64 vcc, exec, s[2:3]
	s_xor_b32 s44, s38, 0x10000
	s_cbranch_vccnz .LBB0_1813
	s_ashr_i32 s16, s69, 31
	s_add_u32 s40, s64, s69
	s_addc_u32 s41, s65, s16
	s_add_u32 s2, s40, 0x80
	s_addc_u32 s3, s41, 0
	s_add_u32 s42, s66, s69
	s_addc_u32 s43, s67, s16
	s_add_u32 s38, s42, 0x80
	v_mov_b32_e32 v188, v190
	v_mov_b32_e32 v130, v190
	s_addc_u32 s39, s43, 0
	s_add_i32 s16, s48, s44
	v_lshl_add_u64 v[132:133], s[40:41], 0, v[188:189]
	v_mov_b32_e32 v131, v189
	v_lshl_add_u64 v[132:133], v[132:133], 0, s[12:13]
	s_mov_b32 m0, s16
	v_lshl_add_u64 v[130:131], s[42:43], 0, v[130:131]
	global_load_lds_dwordx4 v[132:133], off
	v_lshl_add_u64 v[130:131], v[130:131], 0, s[12:13]
	s_add_i32 m0, s16, 0x8000
	v_mov_b32_e32 v188, v191
	global_load_lds_dwordx4 v[130:131], off
	v_mov_b32_e32 v130, v191
	v_mov_b32_e32 v131, v189
	v_lshl_add_u64 v[132:133], s[40:41], 0, v[188:189]
	v_lshl_add_u64 v[132:133], v[132:133], 0, s[12:13]
	s_add_i32 m0, s16, 0x2000
	v_lshl_add_u64 v[130:131], s[42:43], 0, v[130:131]
	global_load_lds_dwordx4 v[132:133], off
	v_lshl_add_u64 v[130:131], v[130:131], 0, s[12:13]
	s_add_i32 m0, s16, 0xa000
	v_mov_b32_e32 v188, v192
	global_load_lds_dwordx4 v[130:131], off
	v_mov_b32_e32 v130, v192
	v_mov_b32_e32 v131, v189
	v_lshl_add_u64 v[132:133], s[40:41], 0, v[188:189]
	v_lshl_add_u64 v[132:133], v[132:133], 0, s[12:13]
	s_add_i32 m0, s16, 0x4000
	v_lshl_add_u64 v[130:131], s[42:43], 0, v[130:131]
	global_load_lds_dwordx4 v[132:133], off
	v_lshl_add_u64 v[130:131], v[130:131], 0, s[12:13]
	s_add_i32 m0, s16, 0xc000
	s_nop 0
	global_load_lds_dwordx4 v[130:131], off
	v_mov_b32_e32 v130, v193
	v_mov_b32_e32 v131, v193
	s_mov_b64 s[40:41], -1
	s_cbranch_execz .LBB0_1814
	s_branch .LBB0_1817

; __global__ void __launch_bounds__(512, 2) mega(P p, int ph0, int ph1) {
;   __shared__ __attribute__((aligned(1024))) char smem_all[SMEM_BYTES];
	.amdhsa_kernel _Z4mega1Pii
		.amdhsa_group_segment_fixed_size 151552
		.amdhsa_private_segment_fixed_size 0
		.amdhsa_kernarg_size 536
		.amdhsa_user_sgpr_count 2
		.amdhsa_user_sgpr_dispatch_ptr 0
		.amdhsa_user_sgpr_queue_ptr 0
		.amdhsa_user_sgpr_kernarg_segment_ptr 1
		.amdhsa_user_sgpr_dispatch_id 0
		.amdhsa_user_sgpr_kernarg_preload_length 0
		.amdhsa_user_sgpr_kernarg_preload_offset 0
		.amdhsa_user_sgpr_private_segment_size 0
		.amdhsa_uses_dynamic_stack 0
		.amdhsa_enable_private_segment 0
		.amdhsa_system_sgpr_workgroup_id_x 1
		.amdhsa_system_sgpr_workgroup_id_y 0
		.amdhsa_system_sgpr_workgroup_id_z 0
		.amdhsa_system_sgpr_workgroup_info 0
		.amdhsa_system_vgpr_workitem_id 2
		.amdhsa_next_free_vgpr 256
		.amdhsa_next_free_sgpr 102
		.amdhsa_accum_offset 256
		.amdhsa_reserve_vcc 1
		.amdhsa_float_round_mode_32 0
		.amdhsa_float_round_mode_16_64 0
		.amdhsa_float_denorm_mode_32 3
		.amdhsa_float_denorm_mode_16_64 3
		.amdhsa_dx10_clamp 1
		.amdhsa_ieee_mode 1
		.amdhsa_fp16_overflow 0
		.amdhsa_tg_split 0
		.amdhsa_exception_fp_ieee_invalid_op 0
		.amdhsa_exception_fp_denorm_src 0
		.amdhsa_exception_fp_ieee_div_zero 0
		.amdhsa_exception_fp_ieee_overflow 0
		.amdhsa_exception_fp_ieee_underflow 0
		.amdhsa_exception_fp_ieee_inexact 0
		.amdhsa_exception_int_div_zero 0
	.end_amdhsa_kernel

; __global__ void __launch_bounds__(512, 2) mega(P p, int ph0, int ph1) {
;   __shared__ __attribute__((aligned(1024))) char smem_all[SMEM_BYTES];
.Lfunc_end0:
	.size	_Z4mega1Pii, .Lfunc_end0-_Z4mega1Pii
	.set _Z4mega1Pii.num_vgpr, 256
	.set _Z4mega1Pii.num_agpr, 0
	.set _Z4mega1Pii.numbered_sgpr, 102
	.set _Z4mega1Pii.num_named_barrier, 0
	.set _Z4mega1Pii.private_seg_size, 0
	.set _Z4mega1Pii.uses_vcc, 1
	.set _Z4mega1Pii.uses_flat_scratch, 0
	.set _Z4mega1Pii.has_dyn_sized_stack, 0
	.set _Z4mega1Pii.has_recursion, 0
	.set _Z4mega1Pii.has_indirect_call, 0

; __global__ void __launch_bounds__(512, 2) mega(P p, int ph0, int ph1) {
;   __shared__ __attribute__((aligned(1024))) char smem_all[SMEM_BYTES];
amdhsa.kernels:
  - .agpr_count:     0
    .args:
      - .offset:         0
        .size:           272
        .value_kind:     by_value
      - .offset:         272
        .size:           4
        .value_kind:     by_value
      - .offset:         276
        .size:           4
        .value_kind:     by_value
      - .offset:         280
        .size:           4
        .value_kind:     hidden_block_count_x
      - .offset:         284
        .size:           4
        .value_kind:     hidden_block_count_y
      - .offset:         288
        .size:           4
        .value_kind:     hidden_block_count_z
      - .offset:         292
        .size:           2
        .value_kind:     hidden_group_size_x
      - .offset:         294
        .size:           2
        .value_kind:     hidden_group_size_y
      - .offset:         296
        .size:           2
        .value_kind:     hidden_group_size_z
      - .offset:         298
        .size:           2
        .value_kind:     hidden_remainder_x
      - .offset:         300
        .size:           2
        .value_kind:     hidden_remainder_y
      - .offset:         302
        .size:           2
        .value_kind:     hidden_remainder_z
      - .offset:         320
        .size:           8
        .value_kind:     hidden_global_offset_x
      - .offset:         328
        .size:           8
        .value_kind:     hidden_global_offset_y
      - .offset:         336
        .size:           8
        .value_kind:     hidden_global_offset_z
      - .offset:         344
        .size:           2
        .value_kind:     hidden_grid_dims
      - .offset:         368
        .size:           8
        .value_kind:     hidden_multigrid_sync_arg
    .group_segment_fixed_size: 151552
    .kernarg_segment_align: 8
    .kernarg_segment_size: 536
    .language:       OpenCL C
    .language_version:
      - 2
      - 0
    .max_flat_workgroup_size: 512
    .name:           _Z4mega1Pii
    .private_segment_fixed_size: 0
    .sgpr_count:     108
    .sgpr_spill_count: 115
    .symbol:         _Z4mega1Pii.kd
    .uniform_work_group_size: 1
    .uses_dynamic_stack: false
    .vgpr_count:     256
    .vgpr_spill_count: 0
    .wavefront_size: 64
